# v11: v10 + m0-write/address-VALU swap removes 80 s_nop 0 before LDS-DMA loads in the 8 GEMM K-loops
# baseline (speedup 1.0000x reference)
.LBB0_237:
	ds_read_b128 v[128:131], v169
	ds_read_b128 v[152:155], v169 offset:1024
	ds_read_b128 v[156:159], v169 offset:2048
	ds_read_b128 v[160:163], v169 offset:3072
	s_add_u32 s20, s8, 0xfff80080
	s_addc_u32 s21, s9, -1
	s_cmp_eq_u32 s35, 28
	s_cselect_b32 s21, s1, s21
	s_cselect_b32 s20, s7, s20
	s_cselect_b32 s79, s22, s34
	s_cselect_b32 s78, s23, s33
	v_lshl_add_u64 v[164:165], s[8:9], 0, v[142:143]
	s_add_i32 m0, s12, 0xc000
	ds_read_b128 v[172:175], v170
	ds_read_b128 v[176:179], v170 offset:1024
	ds_read_b128 v[180:183], v170 offset:2048
	ds_read_b128 v[184:187], v170 offset:3072
	ds_read_b128 v[188:191], v170 offset:4096
	ds_read_b128 v[194:197], v170 offset:5120
	ds_read_b128 v[198:201], v170 offset:6144
	ds_read_b128 v[202:205], v170 offset:7168
	global_load_lds_dwordx4 v[164:165], off
	s_add_i32 m0, s12, 0xe000
	v_lshl_add_u64 v[164:165], s[8:9], 0, v[146:147]
	global_load_lds_dwordx4 v[164:165], off
	s_waitcnt lgkmcnt(8)
	s_barrier
	s_waitcnt lgkmcnt(0)
	s_setprio 1
	v_mfma_f32_16x16x32_bf16 v[124:127], v[128:131], v[172:175], v[124:127]
	v_mfma_f32_16x16x32_bf16 v[120:123], v[156:159], v[172:175], v[120:123]
	v_mfma_f32_16x16x32_bf16 v[108:111], v[128:131], v[180:183], v[108:111]
	v_mfma_f32_16x16x32_bf16 v[104:107], v[156:159], v[180:183], v[104:107]
	v_mfma_f32_16x16x32_bf16 v[92:95], v[128:131], v[188:191], v[92:95]
	v_mfma_f32_16x16x32_bf16 v[88:91], v[156:159], v[188:191], v[88:91]
	v_mfma_f32_16x16x32_bf16 v[76:79], v[128:131], v[198:201], v[76:79]
	v_mfma_f32_16x16x32_bf16 v[72:75], v[156:159], v[198:201], v[72:75]
	v_mfma_f32_16x16x32_bf16 v[124:127], v[152:155], v[176:179], v[124:127]
	v_mfma_f32_16x16x32_bf16 v[120:123], v[160:163], v[176:179], v[120:123]
	v_mfma_f32_16x16x32_bf16 v[108:111], v[152:155], v[184:187], v[108:111]
	v_mfma_f32_16x16x32_bf16 v[104:107], v[160:163], v[184:187], v[104:107]
	v_mfma_f32_16x16x32_bf16 v[92:95], v[152:155], v[194:197], v[92:95]
	v_mfma_f32_16x16x32_bf16 v[88:91], v[160:163], v[194:197], v[88:91]
	v_mfma_f32_16x16x32_bf16 v[76:79], v[152:155], v[202:205], v[76:79]
	v_mfma_f32_16x16x32_bf16 v[72:75], v[160:163], v[202:205], v[72:75]
	s_setprio 0
	s_barrier
	s_add_i32 s50, s82, s11
	v_lshl_add_u64 v[164:165], s[78:79], 0, v[134:135]
	s_mov_b32 m0, s50
	ds_read_b128 v[206:209], v171
	ds_read_b128 v[210:213], v171 offset:1024
	ds_read_b128 v[214:217], v171 offset:2048
	ds_read_b128 v[218:221], v171 offset:3072
	global_load_lds_dwordx4 v[164:165], off
	s_add_i32 m0, s50, 0x2000
	v_lshl_add_u64 v[222:223], s[78:79], 0, v[138:139]
	global_load_lds_dwordx4 v[222:223], off
	s_barrier
	s_waitcnt lgkmcnt(0)
	s_setprio 1
	v_mfma_f32_16x16x32_bf16 v[116:119], v[206:209], v[172:175], v[116:119]
	v_mfma_f32_16x16x32_bf16 v[112:115], v[214:217], v[172:175], v[112:115]
	v_mfma_f32_16x16x32_bf16 v[100:103], v[206:209], v[180:183], v[100:103]
	v_mfma_f32_16x16x32_bf16 v[96:99], v[214:217], v[180:183], v[96:99]
	v_mfma_f32_16x16x32_bf16 v[84:87], v[206:209], v[188:191], v[84:87]
	v_mfma_f32_16x16x32_bf16 v[80:83], v[214:217], v[188:191], v[80:83]
	v_mfma_f32_16x16x32_bf16 v[68:71], v[206:209], v[198:201], v[68:71]
	v_mfma_f32_16x16x32_bf16 v[64:67], v[214:217], v[198:201], v[64:67]
	v_mfma_f32_16x16x32_bf16 v[116:119], v[210:213], v[176:179], v[116:119]
	v_mfma_f32_16x16x32_bf16 v[112:115], v[218:221], v[176:179], v[112:115]
	v_mfma_f32_16x16x32_bf16 v[100:103], v[210:213], v[184:187], v[100:103]
	v_mfma_f32_16x16x32_bf16 v[96:99], v[218:221], v[184:187], v[96:99]
	v_mfma_f32_16x16x32_bf16 v[84:87], v[210:213], v[194:197], v[84:87]
	v_mfma_f32_16x16x32_bf16 v[80:83], v[218:221], v[194:197], v[80:83]
	v_mfma_f32_16x16x32_bf16 v[68:71], v[210:213], v[202:205], v[68:71]
	v_mfma_f32_16x16x32_bf16 v[64:67], v[218:221], v[202:205], v[64:67]
	s_setprio 0
	s_mov_b32 m0, s12
	v_lshl_add_u64 v[224:225], s[20:21], 0, v[132:133]
	s_barrier
	ds_read_b128 v[172:175], v170 offset:16384
	ds_read_b128 v[176:179], v170 offset:17408
	ds_read_b128 v[180:183], v170 offset:18432
	ds_read_b128 v[184:187], v170 offset:19456
	ds_read_b128 v[188:191], v170 offset:20480
	ds_read_b128 v[194:197], v170 offset:21504
	ds_read_b128 v[198:201], v170 offset:22528
	ds_read_b128 v[202:205], v170 offset:23552
	global_load_lds_dwordx4 v[224:225], off
	s_mov_b32 m0, s36
	v_lshl_add_u64 v[226:227], s[20:21], 0, v[136:137]
	global_load_lds_dwordx4 v[226:227], off
	s_barrier
	s_waitcnt lgkmcnt(0)
	s_setprio 1
	v_mfma_f32_16x16x32_bf16 v[60:63], v[128:131], v[172:175], v[60:63]
	v_mfma_f32_16x16x32_bf16 v[56:59], v[156:159], v[172:175], v[56:59]
	v_mfma_f32_16x16x32_bf16 v[44:47], v[128:131], v[180:183], v[44:47]
	v_mfma_f32_16x16x32_bf16 v[40:43], v[156:159], v[180:183], v[40:43]
	v_mfma_f32_16x16x32_bf16 v[28:31], v[128:131], v[188:191], v[28:31]
	v_mfma_f32_16x16x32_bf16 v[24:27], v[156:159], v[188:191], v[24:27]
	v_mfma_f32_16x16x32_bf16 v[12:15], v[128:131], v[198:201], v[12:15]
	v_mfma_f32_16x16x32_bf16 v[8:11], v[156:159], v[198:201], v[8:11]
	v_mfma_f32_16x16x32_bf16 v[60:63], v[152:155], v[176:179], v[60:63]
	v_mfma_f32_16x16x32_bf16 v[56:59], v[160:163], v[176:179], v[56:59]
	v_mfma_f32_16x16x32_bf16 v[44:47], v[152:155], v[184:187], v[44:47]
	v_mfma_f32_16x16x32_bf16 v[40:43], v[160:163], v[184:187], v[40:43]
	v_mfma_f32_16x16x32_bf16 v[28:31], v[152:155], v[194:197], v[28:31]
	v_mfma_f32_16x16x32_bf16 v[24:27], v[160:163], v[194:197], v[24:27]
	v_mfma_f32_16x16x32_bf16 v[12:15], v[152:155], v[202:205], v[12:15]
	v_mfma_f32_16x16x32_bf16 v[8:11], v[160:163], v[202:205], v[8:11]
	s_setprio 0
	s_barrier
	s_add_u32 s50, s78, 0x80000
	s_addc_u32 s51, s79, 0
	s_add_i32 s58, s84, s11
	s_mov_b32 m0, s58
	v_lshl_add_u64 v[128:129], s[50:51], 0, v[134:135]
	global_load_lds_dwordx4 v[128:129], off
	s_add_i32 m0, s58, 0x2000
	v_lshl_add_u64 v[128:129], s[50:51], 0, v[138:139]
	global_load_lds_dwordx4 v[128:129], off
	s_waitcnt vmcnt(6)
	s_barrier
	s_setprio 1
	v_mfma_f32_16x16x32_bf16 v[52:55], v[206:209], v[172:175], v[52:55]
	v_mfma_f32_16x16x32_bf16 v[48:51], v[214:217], v[172:175], v[48:51]
	v_mfma_f32_16x16x32_bf16 v[36:39], v[206:209], v[180:183], v[36:39]
	v_mfma_f32_16x16x32_bf16 v[32:35], v[214:217], v[180:183], v[32:35]
	v_mfma_f32_16x16x32_bf16 v[20:23], v[206:209], v[188:191], v[20:23]
	v_mfma_f32_16x16x32_bf16 v[16:19], v[214:217], v[188:191], v[16:19]
	v_mfma_f32_16x16x32_bf16 v[4:7], v[206:209], v[198:201], v[4:7]
	v_mfma_f32_16x16x32_bf16 v[0:3], v[214:217], v[198:201], v[0:3]
	v_mfma_f32_16x16x32_bf16 v[52:55], v[210:213], v[176:179], v[52:55]
	v_mfma_f32_16x16x32_bf16 v[48:51], v[218:221], v[176:179], v[48:51]
	v_mfma_f32_16x16x32_bf16 v[36:39], v[210:213], v[184:187], v[36:39]
	v_mfma_f32_16x16x32_bf16 v[32:35], v[218:221], v[184:187], v[32:35]
	v_mfma_f32_16x16x32_bf16 v[20:23], v[210:213], v[194:197], v[20:23]
	v_mfma_f32_16x16x32_bf16 v[16:19], v[218:221], v[194:197], v[16:19]
	v_mfma_f32_16x16x32_bf16 v[4:7], v[210:213], v[202:205], v[4:7]
	v_mfma_f32_16x16x32_bf16 v[0:3], v[218:221], v[202:205], v[0:3]
	s_setprio 0
	s_add_i32 s50, 0, 0x18000
	v_add_u32_e32 v140, s50, v167
	s_barrier
	ds_read_b128 v[128:131], v140
	ds_read_b128 v[152:155], v140 offset:1024
	ds_read_b128 v[156:159], v140 offset:2048
	ds_read_b128 v[160:163], v140 offset:3072
	s_add_u32 s20, s20, 0x80000
	s_addc_u32 s21, s21, 0
	s_mov_b32 m0, s37
	v_lshl_add_u64 v[206:207], s[20:21], 0, v[132:133]
	ds_read_b128 v[172:175], v170 offset:32768
	ds_read_b128 v[176:179], v170 offset:33792
	ds_read_b128 v[180:183], v170 offset:34816
	ds_read_b128 v[184:187], v170 offset:35840
	ds_read_b128 v[188:191], v170 offset:36864
	ds_read_b128 v[194:197], v170 offset:37888
	ds_read_b128 v[198:201], v170 offset:38912
	ds_read_b128 v[202:205], v170 offset:39936
	global_load_lds_dwordx4 v[206:207], off
	s_mov_b32 m0, s38
	v_lshl_add_u64 v[206:207], s[20:21], 0, v[136:137]
	global_load_lds_dwordx4 v[206:207], off
	s_waitcnt lgkmcnt(8)
	s_barrier
	s_waitcnt lgkmcnt(0)
	s_setprio 1
	v_mfma_f32_16x16x32_bf16 v[124:127], v[128:131], v[172:175], v[124:127]
	v_mfma_f32_16x16x32_bf16 v[120:123], v[156:159], v[172:175], v[120:123]
	v_mfma_f32_16x16x32_bf16 v[108:111], v[128:131], v[180:183], v[108:111]
	v_mfma_f32_16x16x32_bf16 v[104:107], v[156:159], v[180:183], v[104:107]
	v_mfma_f32_16x16x32_bf16 v[92:95], v[128:131], v[188:191], v[92:95]
	v_mfma_f32_16x16x32_bf16 v[88:91], v[156:159], v[188:191], v[88:91]
	v_mfma_f32_16x16x32_bf16 v[76:79], v[128:131], v[198:201], v[76:79]
	v_mfma_f32_16x16x32_bf16 v[72:75], v[156:159], v[198:201], v[72:75]
	v_mfma_f32_16x16x32_bf16 v[124:127], v[152:155], v[176:179], v[124:127]
	v_mfma_f32_16x16x32_bf16 v[120:123], v[160:163], v[176:179], v[120:123]
	v_mfma_f32_16x16x32_bf16 v[108:111], v[152:155], v[184:187], v[108:111]
	v_mfma_f32_16x16x32_bf16 v[104:107], v[160:163], v[184:187], v[104:107]
	v_mfma_f32_16x16x32_bf16 v[92:95], v[152:155], v[194:197], v[92:95]
	v_mfma_f32_16x16x32_bf16 v[88:91], v[160:163], v[194:197], v[88:91]
	v_mfma_f32_16x16x32_bf16 v[76:79], v[152:155], v[202:205], v[76:79]
	v_mfma_f32_16x16x32_bf16 v[72:75], v[160:163], v[202:205], v[72:75]
	s_setprio 0
	s_barrier
	s_add_i32 s51, 0, 0x1c000
	s_add_i32 s20, s50, s11
	v_add_u32_e32 v140, s51, v167
	v_lshl_add_u64 v[164:165], v[164:165], 0, s[18:19]
	s_mov_b32 m0, s20
	ds_read_b128 v[206:209], v140
	ds_read_b128 v[210:213], v140 offset:1024
	ds_read_b128 v[214:217], v140 offset:2048
	ds_read_b128 v[218:221], v140 offset:3072
	global_load_lds_dwordx4 v[164:165], off
	s_add_i32 m0, s20, 0x2000
	v_lshl_add_u64 v[164:165], v[222:223], 0, s[18:19]
	global_load_lds_dwordx4 v[164:165], off
	s_barrier
	s_waitcnt lgkmcnt(0)
	s_setprio 1
	v_mfma_f32_16x16x32_bf16 v[116:119], v[206:209], v[172:175], v[116:119]
	v_mfma_f32_16x16x32_bf16 v[112:115], v[214:217], v[172:175], v[112:115]
	v_mfma_f32_16x16x32_bf16 v[100:103], v[206:209], v[180:183], v[100:103]
	v_mfma_f32_16x16x32_bf16 v[96:99], v[214:217], v[180:183], v[96:99]
	v_mfma_f32_16x16x32_bf16 v[84:87], v[206:209], v[188:191], v[84:87]
	v_mfma_f32_16x16x32_bf16 v[80:83], v[214:217], v[188:191], v[80:83]
	v_mfma_f32_16x16x32_bf16 v[68:71], v[206:209], v[198:201], v[68:71]
	v_mfma_f32_16x16x32_bf16 v[64:67], v[214:217], v[198:201], v[64:67]
	v_mfma_f32_16x16x32_bf16 v[116:119], v[210:213], v[176:179], v[116:119]
	v_mfma_f32_16x16x32_bf16 v[112:115], v[218:221], v[176:179], v[112:115]
	v_mfma_f32_16x16x32_bf16 v[100:103], v[210:213], v[184:187], v[100:103]
	v_mfma_f32_16x16x32_bf16 v[96:99], v[218:221], v[184:187], v[96:99]
	v_mfma_f32_16x16x32_bf16 v[84:87], v[210:213], v[194:197], v[84:87]
	v_mfma_f32_16x16x32_bf16 v[80:83], v[218:221], v[194:197], v[80:83]
	v_mfma_f32_16x16x32_bf16 v[68:71], v[210:213], v[202:205], v[68:71]
	v_mfma_f32_16x16x32_bf16 v[64:67], v[218:221], v[202:205], v[64:67]
	s_setprio 0
	s_mov_b32 m0, s57
	v_lshl_add_u64 v[164:165], v[224:225], 0, s[18:19]
	s_barrier
	ds_read_b128 v[172:175], v170 offset:49152
	ds_read_b128 v[176:179], v170 offset:50176
	ds_read_b128 v[180:183], v170 offset:51200
	ds_read_b128 v[184:187], v170 offset:52224
	ds_read_b128 v[188:191], v170 offset:53248
	ds_read_b128 v[194:197], v170 offset:54272
	ds_read_b128 v[198:201], v170 offset:55296
	ds_read_b128 v[202:205], v170 offset:56320
	global_load_lds_dwordx4 v[164:165], off
	s_mov_b32 m0, s80
	v_lshl_add_u64 v[164:165], v[226:227], 0, s[18:19]
	global_load_lds_dwordx4 v[164:165], off
	s_barrier
	s_waitcnt lgkmcnt(0)
	s_setprio 1
	v_mfma_f32_16x16x32_bf16 v[60:63], v[128:131], v[172:175], v[60:63]
	v_mfma_f32_16x16x32_bf16 v[56:59], v[156:159], v[172:175], v[56:59]
	v_mfma_f32_16x16x32_bf16 v[44:47], v[128:131], v[180:183], v[44:47]
	v_mfma_f32_16x16x32_bf16 v[40:43], v[156:159], v[180:183], v[40:43]
	v_mfma_f32_16x16x32_bf16 v[28:31], v[128:131], v[188:191], v[28:31]
	v_mfma_f32_16x16x32_bf16 v[24:27], v[156:159], v[188:191], v[24:27]
	v_mfma_f32_16x16x32_bf16 v[12:15], v[128:131], v[198:201], v[12:15]
	v_mfma_f32_16x16x32_bf16 v[8:11], v[156:159], v[198:201], v[8:11]
	v_mfma_f32_16x16x32_bf16 v[60:63], v[152:155], v[176:179], v[60:63]
	v_mfma_f32_16x16x32_bf16 v[56:59], v[160:163], v[176:179], v[56:59]
	v_mfma_f32_16x16x32_bf16 v[44:47], v[152:155], v[184:187], v[44:47]
	v_mfma_f32_16x16x32_bf16 v[40:43], v[160:163], v[184:187], v[40:43]
	v_mfma_f32_16x16x32_bf16 v[28:31], v[152:155], v[194:197], v[28:31]
	v_mfma_f32_16x16x32_bf16 v[24:27], v[160:163], v[194:197], v[24:27]
	v_mfma_f32_16x16x32_bf16 v[12:15], v[152:155], v[202:205], v[12:15]
	v_mfma_f32_16x16x32_bf16 v[8:11], v[160:163], v[202:205], v[8:11]
	s_setprio 0
	s_barrier
	s_add_u32 s20, s78, 0x80080
	s_addc_u32 s21, s79, 0
	s_add_i32 s50, s51, s11
	s_mov_b32 m0, s50
	v_lshl_add_u64 v[128:129], s[20:21], 0, v[134:135]
	global_load_lds_dwordx4 v[128:129], off
	s_add_i32 m0, s50, 0x2000
	v_lshl_add_u64 v[128:129], s[20:21], 0, v[138:139]
	global_load_lds_dwordx4 v[128:129], off
	s_waitcnt vmcnt(6)
	s_barrier
	s_setprio 1
	v_mfma_f32_16x16x32_bf16 v[52:55], v[206:209], v[172:175], v[52:55]
	v_mfma_f32_16x16x32_bf16 v[48:51], v[214:217], v[172:175], v[48:51]
	v_mfma_f32_16x16x32_bf16 v[36:39], v[206:209], v[180:183], v[36:39]
	v_mfma_f32_16x16x32_bf16 v[32:35], v[214:217], v[180:183], v[32:35]
	v_mfma_f32_16x16x32_bf16 v[20:23], v[206:209], v[188:191], v[20:23]
	v_mfma_f32_16x16x32_bf16 v[16:19], v[214:217], v[188:191], v[16:19]
	v_mfma_f32_16x16x32_bf16 v[4:7], v[206:209], v[198:201], v[4:7]
	v_mfma_f32_16x16x32_bf16 v[0:3], v[214:217], v[198:201], v[0:3]
	v_mfma_f32_16x16x32_bf16 v[52:55], v[210:213], v[176:179], v[52:55]
	v_mfma_f32_16x16x32_bf16 v[48:51], v[218:221], v[176:179], v[48:51]
	v_mfma_f32_16x16x32_bf16 v[36:39], v[210:213], v[184:187], v[36:39]
	v_mfma_f32_16x16x32_bf16 v[32:35], v[218:221], v[184:187], v[32:35]
	v_mfma_f32_16x16x32_bf16 v[20:23], v[210:213], v[194:197], v[20:23]
	v_mfma_f32_16x16x32_bf16 v[16:19], v[218:221], v[194:197], v[16:19]
	v_mfma_f32_16x16x32_bf16 v[4:7], v[210:213], v[202:205], v[4:7]
	v_mfma_f32_16x16x32_bf16 v[0:3], v[218:221], v[202:205], v[0:3]
	s_setprio 0
	s_add_i32 s35, s35, 2
	s_add_u32 s8, s8, 0x100
	s_addc_u32 s9, s9, 0
	s_add_u32 s33, s33, 0x100
	s_addc_u32 s34, s34, 0
	s_cmp_gt_u32 s35, 29
	s_barrier
	s_cbranch_scc0 .LBB0_237
	s_lshl_b32 s65, s6, 8
	v_lshl_add_u32 v154, s0, 8, v166
	v_or_b32_e32 v152, s65, v168
	v_ashrrev_i32_e32 v155, 31, v154
	v_lshlrev_b64 v[162:163], 7, v[154:155]
	v_lshlrev_b64 v[160:161], 11, v[154:155]
	v_mad_i64_i32 v[158:159], s[0:1], v154, s85, 0
	v_cmp_gt_i32_e64 s[8:9], s39, v154
	v_lshlrev_b64 v[156:157], 12, v[154:155]
	v_cvt_pk_bf16_f32 v128, v124, v125
	v_cvt_pk_bf16_f32 v129, v126, v127
	v_cvt_pk_bf16_f32 v130, v120, v121
	v_cvt_pk_bf16_f32 v131, v122, v123
	v_cmp_lt_i32_e64 s[6:7], s86, v152
	s_and_saveexec_b64 s[0:1], s[6:7]
	s_xor_b64 s[0:1], exec, s[0:1]
	s_cbranch_execz .LBB0_255
	s_cmpk_gt_u32 s65, 0xbff
	s_mov_b64 s[20:21], -1
	s_cbranch_scc0 .LBB0_251
	s_cmpk_gt_u32 s65, 0x17ff
	s_cbranch_scc0 .LBB0_248
	s_cmpk_gt_u32 s65, 0x1bff
	s_cbranch_scc0 .LBB0_245
	v_cmp_gt_u32_e32 vcc, s87, v152
	s_and_saveexec_b64 s[20:21], vcc
	s_cbranch_execz .LBB0_244
	v_readlane_b32 s22, v254, 24
	v_readlane_b32 s23, v254, 25
	v_mov_b32_e32 v153, v141
	s_nop 0
	v_lshl_add_u64 v[164:165], s[22:23], 0, v[162:163]
	v_lshl_add_u64 v[164:165], v[152:153], 2, v[164:165]
	v_add_co_u32_e32 v172, vcc, 0xffff9000, v164
	s_nop 1
	v_addc_co_u32_e32 v173, vcc, -1, v165, vcc
	v_add_co_u32_e32 v164, vcc, 0xffffa000, v164
	global_store_dwordx4 v[172:173], v[124:127], off
	s_nop 0
	v_addc_co_u32_e32 v165, vcc, -1, v165, vcc
	global_store_dwordx4 v[164:165], v[120:123], off offset:-4080

.LBB0_912:
	ds_read_b128 v[150:153], v161
	ds_read_b128 v[154:157], v161 offset:1024
	ds_read_b128 v[164:167], v161 offset:2048
	ds_read_b128 v[168:171], v161 offset:3072
	s_add_u32 s20, s48, 0xfff80080
	s_addc_u32 s21, s49, -1
	s_cmp_eq_u32 s47, 28
	s_cselect_b32 s21, s17, s21
	s_cselect_b32 s20, s33, s20
	s_cselect_b32 s51, s15, s45
	s_cselect_b32 s50, s34, s35
	v_lshl_add_u64 v[208:209], s[48:49], 0, v[138:139]
	s_add_i32 m0, s36, 0xc000
	ds_read_b128 v[172:175], v162
	ds_read_b128 v[176:179], v162 offset:1024
	ds_read_b128 v[180:183], v162 offset:2048
	ds_read_b128 v[184:187], v162 offset:3072
	ds_read_b128 v[188:191], v162 offset:4096
	ds_read_b128 v[196:199], v162 offset:5120
	ds_read_b128 v[200:203], v162 offset:6144
	ds_read_b128 v[204:207], v162 offset:7168
	global_load_lds_dwordx4 v[208:209], off
	s_add_i32 m0, s36, 0xe000
	v_lshl_add_u64 v[208:209], s[48:49], 0, v[140:141]
	global_load_lds_dwordx4 v[208:209], off
	s_waitcnt lgkmcnt(8)
	s_barrier
	s_waitcnt lgkmcnt(0)
	s_setprio 1
	v_mfma_f32_16x16x32_bf16 v[124:127], v[150:153], v[172:175], v[124:127]
	v_mfma_f32_16x16x32_bf16 v[120:123], v[164:167], v[172:175], v[120:123]
	v_mfma_f32_16x16x32_bf16 v[108:111], v[150:153], v[180:183], v[108:111]
	v_mfma_f32_16x16x32_bf16 v[104:107], v[164:167], v[180:183], v[104:107]
	v_mfma_f32_16x16x32_bf16 v[92:95], v[150:153], v[188:191], v[92:95]
	v_mfma_f32_16x16x32_bf16 v[88:91], v[164:167], v[188:191], v[88:91]
	v_mfma_f32_16x16x32_bf16 v[76:79], v[150:153], v[200:203], v[76:79]
	v_mfma_f32_16x16x32_bf16 v[72:75], v[164:167], v[200:203], v[72:75]
	v_mfma_f32_16x16x32_bf16 v[124:127], v[154:157], v[176:179], v[124:127]
	v_mfma_f32_16x16x32_bf16 v[120:123], v[168:171], v[176:179], v[120:123]
	v_mfma_f32_16x16x32_bf16 v[108:111], v[154:157], v[184:187], v[108:111]
	v_mfma_f32_16x16x32_bf16 v[104:107], v[168:171], v[184:187], v[104:107]
	v_mfma_f32_16x16x32_bf16 v[92:95], v[154:157], v[196:199], v[92:95]
	v_mfma_f32_16x16x32_bf16 v[88:91], v[168:171], v[196:199], v[88:91]
	v_mfma_f32_16x16x32_bf16 v[76:79], v[154:157], v[204:207], v[76:79]
	v_mfma_f32_16x16x32_bf16 v[72:75], v[168:171], v[204:207], v[72:75]
	s_setprio 0
	s_barrier
	s_add_i32 s65, s62, s23
	v_lshl_add_u64 v[224:225], s[50:51], 0, v[130:131]
	s_mov_b32 m0, s65
	ds_read_b128 v[208:211], v163
	ds_read_b128 v[212:215], v163 offset:1024
	ds_read_b128 v[216:219], v163 offset:2048
	ds_read_b128 v[220:223], v163 offset:3072
	global_load_lds_dwordx4 v[224:225], off
	s_add_i32 m0, s65, 0x2000
	v_lshl_add_u64 v[226:227], s[50:51], 0, v[134:135]
	global_load_lds_dwordx4 v[226:227], off
	s_barrier
	s_waitcnt lgkmcnt(0)
	s_setprio 1
	v_mfma_f32_16x16x32_bf16 v[116:119], v[208:211], v[172:175], v[116:119]
	v_mfma_f32_16x16x32_bf16 v[112:115], v[216:219], v[172:175], v[112:115]
	v_mfma_f32_16x16x32_bf16 v[100:103], v[208:211], v[180:183], v[100:103]
	v_mfma_f32_16x16x32_bf16 v[96:99], v[216:219], v[180:183], v[96:99]
	v_mfma_f32_16x16x32_bf16 v[84:87], v[208:211], v[188:191], v[84:87]
	v_mfma_f32_16x16x32_bf16 v[80:83], v[216:219], v[188:191], v[80:83]
	v_mfma_f32_16x16x32_bf16 v[68:71], v[208:211], v[200:203], v[68:71]
	v_mfma_f32_16x16x32_bf16 v[64:67], v[216:219], v[200:203], v[64:67]
	v_mfma_f32_16x16x32_bf16 v[116:119], v[212:215], v[176:179], v[116:119]
	v_mfma_f32_16x16x32_bf16 v[112:115], v[220:223], v[176:179], v[112:115]
	v_mfma_f32_16x16x32_bf16 v[100:103], v[212:215], v[184:187], v[100:103]
	v_mfma_f32_16x16x32_bf16 v[96:99], v[220:223], v[184:187], v[96:99]
	v_mfma_f32_16x16x32_bf16 v[84:87], v[212:215], v[196:199], v[84:87]
	v_mfma_f32_16x16x32_bf16 v[80:83], v[220:223], v[196:199], v[80:83]
	v_mfma_f32_16x16x32_bf16 v[68:71], v[212:215], v[204:207], v[68:71]
	v_mfma_f32_16x16x32_bf16 v[64:67], v[220:223], v[204:207], v[64:67]
	s_setprio 0
	s_mov_b32 m0, s36
	v_lshl_add_u64 v[228:229], s[20:21], 0, v[128:129]
	s_barrier
	ds_read_b128 v[172:175], v162 offset:16384
	ds_read_b128 v[176:179], v162 offset:17408
	ds_read_b128 v[180:183], v162 offset:18432
	ds_read_b128 v[184:187], v162 offset:19456
	ds_read_b128 v[188:191], v162 offset:20480
	ds_read_b128 v[196:199], v162 offset:21504
	ds_read_b128 v[200:203], v162 offset:22528
	ds_read_b128 v[204:207], v162 offset:23552
	global_load_lds_dwordx4 v[228:229], off
	s_mov_b32 m0, s37
	v_lshl_add_u64 v[230:231], s[20:21], 0, v[132:133]
	global_load_lds_dwordx4 v[230:231], off
	s_barrier
	s_waitcnt lgkmcnt(0)
	s_setprio 1
	v_mfma_f32_16x16x32_bf16 v[60:63], v[150:153], v[172:175], v[60:63]
	v_mfma_f32_16x16x32_bf16 v[56:59], v[164:167], v[172:175], v[56:59]
	v_mfma_f32_16x16x32_bf16 v[44:47], v[150:153], v[180:183], v[44:47]
	v_mfma_f32_16x16x32_bf16 v[40:43], v[164:167], v[180:183], v[40:43]
	v_mfma_f32_16x16x32_bf16 v[28:31], v[150:153], v[188:191], v[28:31]
	v_mfma_f32_16x16x32_bf16 v[24:27], v[164:167], v[188:191], v[24:27]
	v_mfma_f32_16x16x32_bf16 v[12:15], v[150:153], v[200:203], v[12:15]
	v_mfma_f32_16x16x32_bf16 v[8:11], v[164:167], v[200:203], v[8:11]
	v_mfma_f32_16x16x32_bf16 v[60:63], v[154:157], v[176:179], v[60:63]
	v_mfma_f32_16x16x32_bf16 v[56:59], v[168:171], v[176:179], v[56:59]
	v_mfma_f32_16x16x32_bf16 v[44:47], v[154:157], v[184:187], v[44:47]
	v_mfma_f32_16x16x32_bf16 v[40:43], v[168:171], v[184:187], v[40:43]
	v_mfma_f32_16x16x32_bf16 v[28:31], v[154:157], v[196:199], v[28:31]
	v_mfma_f32_16x16x32_bf16 v[24:27], v[168:171], v[196:199], v[24:27]
	v_mfma_f32_16x16x32_bf16 v[12:15], v[154:157], v[204:207], v[12:15]
	v_mfma_f32_16x16x32_bf16 v[8:11], v[168:171], v[204:207], v[8:11]
	s_setprio 0
	s_barrier
	s_add_u32 s66, s50, 0x80000
	s_addc_u32 s67, s51, 0
	s_add_i32 s65, s63, s23
	s_mov_b32 m0, s65
	v_lshl_add_u64 v[150:151], s[66:67], 0, v[130:131]
	global_load_lds_dwordx4 v[150:151], off
	s_add_i32 m0, s65, 0x2000
	v_lshl_add_u64 v[150:151], s[66:67], 0, v[134:135]
	global_load_lds_dwordx4 v[150:151], off
	s_waitcnt vmcnt(6)
	s_barrier
	s_setprio 1
	v_mfma_f32_16x16x32_bf16 v[52:55], v[208:211], v[172:175], v[52:55]
	v_mfma_f32_16x16x32_bf16 v[48:51], v[216:219], v[172:175], v[48:51]
	v_mfma_f32_16x16x32_bf16 v[36:39], v[208:211], v[180:183], v[36:39]
	v_mfma_f32_16x16x32_bf16 v[32:35], v[216:219], v[180:183], v[32:35]
	v_mfma_f32_16x16x32_bf16 v[20:23], v[208:211], v[188:191], v[20:23]
	v_mfma_f32_16x16x32_bf16 v[16:19], v[216:219], v[188:191], v[16:19]
	v_mfma_f32_16x16x32_bf16 v[4:7], v[208:211], v[200:203], v[4:7]
	v_mfma_f32_16x16x32_bf16 v[0:3], v[216:219], v[200:203], v[0:3]
	v_mfma_f32_16x16x32_bf16 v[52:55], v[212:215], v[176:179], v[52:55]
	v_mfma_f32_16x16x32_bf16 v[48:51], v[220:223], v[176:179], v[48:51]
	v_mfma_f32_16x16x32_bf16 v[36:39], v[212:215], v[184:187], v[36:39]
	v_mfma_f32_16x16x32_bf16 v[32:35], v[220:223], v[184:187], v[32:35]
	v_mfma_f32_16x16x32_bf16 v[20:23], v[212:215], v[196:199], v[20:23]
	v_mfma_f32_16x16x32_bf16 v[16:19], v[220:223], v[196:199], v[16:19]
	v_mfma_f32_16x16x32_bf16 v[4:7], v[212:215], v[204:207], v[4:7]
	v_mfma_f32_16x16x32_bf16 v[0:3], v[220:223], v[204:207], v[0:3]
	s_setprio 0
	s_add_i32 s65, 0, 0x18000
	v_add_u32_e32 v136, s65, v158
	s_barrier
	ds_read_b128 v[150:153], v136
	ds_read_b128 v[154:157], v136 offset:1024
	ds_read_b128 v[164:167], v136 offset:2048
	ds_read_b128 v[168:171], v136 offset:3072
	s_add_u32 s20, s20, 0x80000
	s_addc_u32 s21, s21, 0
	s_mov_b32 m0, s38
	v_lshl_add_u64 v[208:209], s[20:21], 0, v[128:129]
	ds_read_b128 v[172:175], v162 offset:32768
	ds_read_b128 v[176:179], v162 offset:33792
	ds_read_b128 v[180:183], v162 offset:34816
	ds_read_b128 v[184:187], v162 offset:35840
	ds_read_b128 v[188:191], v162 offset:36864
	ds_read_b128 v[196:199], v162 offset:37888
	ds_read_b128 v[200:203], v162 offset:38912
	ds_read_b128 v[204:207], v162 offset:39936
	global_load_lds_dwordx4 v[208:209], off
	s_mov_b32 m0, s39
	v_lshl_add_u64 v[208:209], s[20:21], 0, v[132:133]
	global_load_lds_dwordx4 v[208:209], off
	s_waitcnt lgkmcnt(8)
	s_barrier
	s_waitcnt lgkmcnt(0)
	s_setprio 1
	v_mfma_f32_16x16x32_bf16 v[124:127], v[150:153], v[172:175], v[124:127]
	v_mfma_f32_16x16x32_bf16 v[120:123], v[164:167], v[172:175], v[120:123]
	v_mfma_f32_16x16x32_bf16 v[108:111], v[150:153], v[180:183], v[108:111]
	v_mfma_f32_16x16x32_bf16 v[104:107], v[164:167], v[180:183], v[104:107]
	v_mfma_f32_16x16x32_bf16 v[92:95], v[150:153], v[188:191], v[92:95]
	v_mfma_f32_16x16x32_bf16 v[88:91], v[164:167], v[188:191], v[88:91]
	v_mfma_f32_16x16x32_bf16 v[76:79], v[150:153], v[200:203], v[76:79]
	v_mfma_f32_16x16x32_bf16 v[72:75], v[164:167], v[200:203], v[72:75]
	v_mfma_f32_16x16x32_bf16 v[124:127], v[154:157], v[176:179], v[124:127]
	v_mfma_f32_16x16x32_bf16 v[120:123], v[168:171], v[176:179], v[120:123]
	v_mfma_f32_16x16x32_bf16 v[108:111], v[154:157], v[184:187], v[108:111]
	v_mfma_f32_16x16x32_bf16 v[104:107], v[168:171], v[184:187], v[104:107]
	v_mfma_f32_16x16x32_bf16 v[92:95], v[154:157], v[196:199], v[92:95]
	v_mfma_f32_16x16x32_bf16 v[88:91], v[168:171], v[196:199], v[88:91]
	v_mfma_f32_16x16x32_bf16 v[76:79], v[154:157], v[204:207], v[76:79]
	v_mfma_f32_16x16x32_bf16 v[72:75], v[168:171], v[204:207], v[72:75]
	s_setprio 0
	s_barrier
	s_add_i32 s66, 0, 0x1c000
	s_add_i32 s20, s65, s23
	v_add_u32_e32 v136, s66, v158
	v_lshl_add_u64 v[224:225], v[224:225], 0, s[10:11]
	s_mov_b32 m0, s20
	ds_read_b128 v[208:211], v136
	ds_read_b128 v[212:215], v136 offset:1024
	ds_read_b128 v[216:219], v136 offset:2048
	ds_read_b128 v[220:223], v136 offset:3072
	global_load_lds_dwordx4 v[224:225], off
	s_add_i32 m0, s20, 0x2000
	v_lshl_add_u64 v[224:225], v[226:227], 0, s[10:11]
	global_load_lds_dwordx4 v[224:225], off
	s_barrier
	s_waitcnt lgkmcnt(0)
	s_setprio 1
	v_mfma_f32_16x16x32_bf16 v[116:119], v[208:211], v[172:175], v[116:119]
	v_mfma_f32_16x16x32_bf16 v[112:115], v[216:219], v[172:175], v[112:115]
	v_mfma_f32_16x16x32_bf16 v[100:103], v[208:211], v[180:183], v[100:103]
	v_mfma_f32_16x16x32_bf16 v[96:99], v[216:219], v[180:183], v[96:99]
	v_mfma_f32_16x16x32_bf16 v[84:87], v[208:211], v[188:191], v[84:87]
	v_mfma_f32_16x16x32_bf16 v[80:83], v[216:219], v[188:191], v[80:83]
	v_mfma_f32_16x16x32_bf16 v[68:71], v[208:211], v[200:203], v[68:71]
	v_mfma_f32_16x16x32_bf16 v[64:67], v[216:219], v[200:203], v[64:67]
	v_mfma_f32_16x16x32_bf16 v[116:119], v[212:215], v[176:179], v[116:119]
	v_mfma_f32_16x16x32_bf16 v[112:115], v[220:223], v[176:179], v[112:115]
	v_mfma_f32_16x16x32_bf16 v[100:103], v[212:215], v[184:187], v[100:103]
	v_mfma_f32_16x16x32_bf16 v[96:99], v[220:223], v[184:187], v[96:99]
	v_mfma_f32_16x16x32_bf16 v[84:87], v[212:215], v[196:199], v[84:87]
	v_mfma_f32_16x16x32_bf16 v[80:83], v[220:223], v[196:199], v[80:83]
	v_mfma_f32_16x16x32_bf16 v[68:71], v[212:215], v[204:207], v[68:71]
	v_mfma_f32_16x16x32_bf16 v[64:67], v[220:223], v[204:207], v[64:67]
	s_setprio 0
	s_mov_b32 m0, s58
	v_lshl_add_u64 v[224:225], v[228:229], 0, s[10:11]
	s_barrier
	ds_read_b128 v[172:175], v162 offset:49152
	ds_read_b128 v[176:179], v162 offset:50176
	ds_read_b128 v[180:183], v162 offset:51200
	ds_read_b128 v[184:187], v162 offset:52224
	ds_read_b128 v[188:191], v162 offset:53248
	ds_read_b128 v[196:199], v162 offset:54272
	ds_read_b128 v[200:203], v162 offset:55296
	ds_read_b128 v[204:207], v162 offset:56320
	global_load_lds_dwordx4 v[224:225], off
	s_mov_b32 m0, s59
	v_lshl_add_u64 v[224:225], v[230:231], 0, s[10:11]
	global_load_lds_dwordx4 v[224:225], off
	s_barrier
	s_waitcnt lgkmcnt(0)
	s_setprio 1
	v_mfma_f32_16x16x32_bf16 v[60:63], v[150:153], v[172:175], v[60:63]
	v_mfma_f32_16x16x32_bf16 v[56:59], v[164:167], v[172:175], v[56:59]
	v_mfma_f32_16x16x32_bf16 v[44:47], v[150:153], v[180:183], v[44:47]
	v_mfma_f32_16x16x32_bf16 v[40:43], v[164:167], v[180:183], v[40:43]
	v_mfma_f32_16x16x32_bf16 v[28:31], v[150:153], v[188:191], v[28:31]
	v_mfma_f32_16x16x32_bf16 v[24:27], v[164:167], v[188:191], v[24:27]
	v_mfma_f32_16x16x32_bf16 v[12:15], v[150:153], v[200:203], v[12:15]
	v_mfma_f32_16x16x32_bf16 v[8:11], v[164:167], v[200:203], v[8:11]
	v_mfma_f32_16x16x32_bf16 v[60:63], v[154:157], v[176:179], v[60:63]
	v_mfma_f32_16x16x32_bf16 v[56:59], v[168:171], v[176:179], v[56:59]
	v_mfma_f32_16x16x32_bf16 v[44:47], v[154:157], v[184:187], v[44:47]
	v_mfma_f32_16x16x32_bf16 v[40:43], v[168:171], v[184:187], v[40:43]
	v_mfma_f32_16x16x32_bf16 v[28:31], v[154:157], v[196:199], v[28:31]
	v_mfma_f32_16x16x32_bf16 v[24:27], v[168:171], v[196:199], v[24:27]
	v_mfma_f32_16x16x32_bf16 v[12:15], v[154:157], v[204:207], v[12:15]
	v_mfma_f32_16x16x32_bf16 v[8:11], v[168:171], v[204:207], v[8:11]
	s_setprio 0
	s_barrier
	s_add_u32 s20, s50, 0x80080
	s_addc_u32 s21, s51, 0
	s_add_i32 s50, s66, s23
	s_mov_b32 m0, s50
	v_lshl_add_u64 v[150:151], s[20:21], 0, v[130:131]
	global_load_lds_dwordx4 v[150:151], off
	s_add_i32 m0, s50, 0x2000
	v_lshl_add_u64 v[150:151], s[20:21], 0, v[134:135]
	global_load_lds_dwordx4 v[150:151], off
	s_waitcnt vmcnt(6)
	s_barrier
	s_setprio 1
	v_mfma_f32_16x16x32_bf16 v[52:55], v[208:211], v[172:175], v[52:55]
	v_mfma_f32_16x16x32_bf16 v[48:51], v[216:219], v[172:175], v[48:51]
	v_mfma_f32_16x16x32_bf16 v[36:39], v[208:211], v[180:183], v[36:39]
	v_mfma_f32_16x16x32_bf16 v[32:35], v[216:219], v[180:183], v[32:35]
	v_mfma_f32_16x16x32_bf16 v[20:23], v[208:211], v[188:191], v[20:23]
	v_mfma_f32_16x16x32_bf16 v[16:19], v[216:219], v[188:191], v[16:19]
	v_mfma_f32_16x16x32_bf16 v[4:7], v[208:211], v[200:203], v[4:7]
	v_mfma_f32_16x16x32_bf16 v[0:3], v[216:219], v[200:203], v[0:3]
	v_mfma_f32_16x16x32_bf16 v[52:55], v[212:215], v[176:179], v[52:55]
	v_mfma_f32_16x16x32_bf16 v[48:51], v[220:223], v[176:179], v[48:51]
	v_mfma_f32_16x16x32_bf16 v[36:39], v[212:215], v[184:187], v[36:39]
	v_mfma_f32_16x16x32_bf16 v[32:35], v[220:223], v[184:187], v[32:35]
	v_mfma_f32_16x16x32_bf16 v[20:23], v[212:215], v[196:199], v[20:23]
	v_mfma_f32_16x16x32_bf16 v[16:19], v[220:223], v[196:199], v[16:19]
	v_mfma_f32_16x16x32_bf16 v[4:7], v[212:215], v[204:207], v[4:7]
	v_mfma_f32_16x16x32_bf16 v[0:3], v[220:223], v[204:207], v[0:3]
	s_setprio 0
	s_add_i32 s47, s47, 2
	s_add_u32 s48, s48, 0x100
	s_addc_u32 s49, s49, 0
	s_add_u32 s35, s35, 0x100
	s_addc_u32 s45, s45, 0
	s_cmp_gt_u32 s47, 29
	s_cbranch_scc0 .Lepi_nl_about
	s_cmp_lg_u32 s57, 64
	s_cbranch_scc1 .Lepi_nl_about
	s_lshl_b32 s15, s46, 8
	s_add_i32 s15, s15, s57
	v_or_b32_e32 v154, s15, v147
	s_add_i32 s17, s15, 0xffffe000
	v_lshl_or_b32 v150, s44, 8, v160
	s_lshr_b32 s17, s17, 12
	v_lshlrev_b32_e32 v151, 13, v154
	s_add_i32 s17, s17, 1
	s_sub_u32 s34, s54, 0x4000000
	s_subb_u32 s35, s55, 0
	v_lshlrev_b32_e32 v152, 12, v154
	s_cmp_gt_i32 s15, s64
	s_cselect_b32 s34, s34, s52
	s_cselect_b32 s35, s35, s53
	s_cselect_b32 s17, s17, 0
	s_mul_i32 s17, s17, 0xc000
	v_lshl_add_u32 v151, v150, 2, v151
	s_add_u32 s20, s8, s17
	s_addc_u32 s21, s9, 0
	v_lshl_add_u32 v152, v150, 1, v152
	v_lshlrev_b32_e32 v153, 2, v150
	s_nop 0
	global_load_dwordx4 v[196:199], v153, s[20:21]
	global_load_dwordx4 v[200:203], v153, s[20:21] offset:16
	global_load_dwordx4 v[204:207], v153, s[20:21] offset:512
	global_load_dwordx4 v[208:211], v153, s[20:21] offset:528
	global_load_dwordx4 v[164:167], v151, s[34:35]
	global_load_dwordx4 v[168:171], v151, s[34:35] offset:16
	global_load_dwordx4 v[172:175], v151, s[34:35] offset:512
	global_load_dwordx4 v[176:179], v151, s[34:35] offset:528
	v_add_u32_e32 v155, 0x20000, v151
	global_load_dwordx4 v[180:183], v155, s[34:35]
	global_load_dwordx4 v[184:187], v155, s[34:35] offset:16
	global_load_dwordx4 v[188:191], v155, s[34:35] offset:512
	global_load_dwordx4 v[212:215], v155, s[34:35] offset:528
	v_add_u32_e32 v155, 0x40000, v151
	global_load_dwordx4 v[216:219], v155, s[34:35]
	global_load_dwordx4 v[220:223], v155, s[34:35] offset:16
	global_load_dwordx4 v[224:227], v155, s[34:35] offset:512
	global_load_dwordx4 v[228:231], v155, s[34:35] offset:528
	v_add_u32_e32 v155, 0x60000, v151
	global_load_dwordx4 v[236:239], v155, s[34:35]
	global_load_dwordx4 v[240:243], v155, s[34:35] offset:16
	global_load_dwordx4 v[244:247], v155, s[34:35] offset:512
	global_load_dwordx4 v[248:251], v155, s[34:35] offset:528
	s_waitcnt vmcnt(0)
	v_pk_fma_f32 v[124:125], v[124:125], v[196:197], v[164:165]
	v_pk_fma_f32 v[126:127], v[126:127], v[198:199], v[166:167]
	v_pk_fma_f32 v[120:121], v[120:121], v[200:201], v[168:169]
	v_pk_fma_f32 v[122:123], v[122:123], v[202:203], v[170:171]
	v_cvt_pk_bf16_f32 v123, v122, v123
	v_cvt_pk_bf16_f32 v122, v120, v121
	v_cvt_pk_bf16_f32 v121, v126, v127
	v_cvt_pk_bf16_f32 v120, v124, v125
	global_store_dwordx4 v152, v[120:123], s[74:75]
	v_pk_fma_f32 v[116:117], v[116:117], v[204:205], v[172:173]
	v_pk_fma_f32 v[118:119], v[118:119], v[206:207], v[174:175]
	v_pk_fma_f32 v[112:113], v[112:113], v[208:209], v[176:177]
	v_pk_fma_f32 v[114:115], v[114:115], v[210:211], v[178:179]
	v_cvt_pk_bf16_f32 v115, v114, v115
	v_cvt_pk_bf16_f32 v114, v112, v113
	v_cvt_pk_bf16_f32 v113, v118, v119
	v_cvt_pk_bf16_f32 v112, v116, v117
	global_store_dwordx4 v152, v[112:115], s[74:75] offset:256
	v_pk_fma_f32 v[108:109], v[108:109], v[196:197], v[180:181]
	v_pk_fma_f32 v[110:111], v[110:111], v[198:199], v[182:183]
	v_pk_fma_f32 v[104:105], v[104:105], v[200:201], v[184:185]
	v_pk_fma_f32 v[106:107], v[106:107], v[202:203], v[186:187]
	v_cvt_pk_bf16_f32 v107, v106, v107
	v_cvt_pk_bf16_f32 v106, v104, v105
	v_cvt_pk_bf16_f32 v105, v110, v111
	v_cvt_pk_bf16_f32 v104, v108, v109
	v_add_u32_e32 v156, 0x10000, v152
	global_store_dwordx4 v156, v[104:107], s[74:75]
	v_pk_fma_f32 v[100:101], v[100:101], v[204:205], v[188:189]
	v_pk_fma_f32 v[102:103], v[102:103], v[206:207], v[190:191]
	v_pk_fma_f32 v[96:97], v[96:97], v[208:209], v[212:213]
	v_pk_fma_f32 v[98:99], v[98:99], v[210:211], v[214:215]
	v_cvt_pk_bf16_f32 v99, v98, v99
	v_cvt_pk_bf16_f32 v98, v96, v97
	v_cvt_pk_bf16_f32 v97, v102, v103
	v_cvt_pk_bf16_f32 v96, v100, v101
	v_add_u32_e32 v156, 0x10000, v152
	global_store_dwordx4 v156, v[96:99], s[74:75] offset:256
	v_add_u32_e32 v155, 0x100000, v151
	global_load_dwordx4 v[164:167], v155, s[34:35]
	global_load_dwordx4 v[168:171], v155, s[34:35] offset:16
	global_load_dwordx4 v[172:175], v155, s[34:35] offset:512
	global_load_dwordx4 v[176:179], v155, s[34:35] offset:528
	v_add_u32_e32 v155, 0x120000, v151
	global_load_dwordx4 v[180:183], v155, s[34:35]
	global_load_dwordx4 v[184:187], v155, s[34:35] offset:16
	global_load_dwordx4 v[188:191], v155, s[34:35] offset:512
	global_load_dwordx4 v[212:215], v155, s[34:35] offset:528
	v_pk_fma_f32 v[92:93], v[92:93], v[196:197], v[216:217]
	v_pk_fma_f32 v[94:95], v[94:95], v[198:199], v[218:219]
	v_pk_fma_f32 v[88:89], v[88:89], v[200:201], v[220:221]
	v_pk_fma_f32 v[90:91], v[90:91], v[202:203], v[222:223]
	v_cvt_pk_bf16_f32 v91, v90, v91
	v_cvt_pk_bf16_f32 v90, v88, v89
	v_cvt_pk_bf16_f32 v89, v94, v95
	v_cvt_pk_bf16_f32 v88, v92, v93
	v_add_u32_e32 v156, 0x20000, v152
	global_store_dwordx4 v156, v[88:91], s[74:75]
	v_pk_fma_f32 v[84:85], v[84:85], v[204:205], v[224:225]
	v_pk_fma_f32 v[86:87], v[86:87], v[206:207], v[226:227]
	v_pk_fma_f32 v[80:81], v[80:81], v[208:209], v[228:229]
	v_pk_fma_f32 v[82:83], v[82:83], v[210:211], v[230:231]
	v_cvt_pk_bf16_f32 v83, v82, v83
	v_cvt_pk_bf16_f32 v82, v80, v81
	v_cvt_pk_bf16_f32 v81, v86, v87
	v_cvt_pk_bf16_f32 v80, v84, v85
	v_add_u32_e32 v156, 0x20000, v152
	global_store_dwordx4 v156, v[80:83], s[74:75] offset:256
	v_pk_fma_f32 v[76:77], v[76:77], v[196:197], v[236:237]
	v_pk_fma_f32 v[78:79], v[78:79], v[198:199], v[238:239]
	v_pk_fma_f32 v[72:73], v[72:73], v[200:201], v[240:241]
	v_pk_fma_f32 v[74:75], v[74:75], v[202:203], v[242:243]
	v_cvt_pk_bf16_f32 v75, v74, v75
	v_cvt_pk_bf16_f32 v74, v72, v73
	v_cvt_pk_bf16_f32 v73, v78, v79
	v_cvt_pk_bf16_f32 v72, v76, v77
	v_add_u32_e32 v156, 0x30000, v152
	global_store_dwordx4 v156, v[72:75], s[74:75]
	v_pk_fma_f32 v[68:69], v[68:69], v[204:205], v[244:245]
	v_pk_fma_f32 v[70:71], v[70:71], v[206:207], v[246:247]
	v_pk_fma_f32 v[64:65], v[64:65], v[208:209], v[248:249]
	v_pk_fma_f32 v[66:67], v[66:67], v[210:211], v[250:251]
	v_cvt_pk_bf16_f32 v67, v66, v67
	v_cvt_pk_bf16_f32 v66, v64, v65
	v_cvt_pk_bf16_f32 v65, v70, v71
	v_cvt_pk_bf16_f32 v64, v68, v69
	v_add_u32_e32 v156, 0x30000, v152
	global_store_dwordx4 v156, v[64:67], s[74:75] offset:256
	v_add_u32_e32 v155, 0x140000, v151
	global_load_dwordx4 v[216:219], v155, s[34:35]
	global_load_dwordx4 v[220:223], v155, s[34:35] offset:16
	global_load_dwordx4 v[224:227], v155, s[34:35] offset:512
	global_load_dwordx4 v[228:231], v155, s[34:35] offset:528
	v_add_u32_e32 v155, 0x160000, v151
	global_load_dwordx4 v[236:239], v155, s[34:35]
	global_load_dwordx4 v[240:243], v155, s[34:35] offset:16
	global_load_dwordx4 v[244:247], v155, s[34:35] offset:512
	global_load_dwordx4 v[248:251], v155, s[34:35] offset:528
	s_waitcnt vmcnt(0)
	v_pk_fma_f32 v[60:61], v[60:61], v[196:197], v[164:165]
	v_pk_fma_f32 v[62:63], v[62:63], v[198:199], v[166:167]
	v_pk_fma_f32 v[56:57], v[56:57], v[200:201], v[168:169]
	v_pk_fma_f32 v[58:59], v[58:59], v[202:203], v[170:171]
	v_cvt_pk_bf16_f32 v59, v58, v59
	v_cvt_pk_bf16_f32 v58, v56, v57
	v_cvt_pk_bf16_f32 v57, v62, v63
	v_cvt_pk_bf16_f32 v56, v60, v61
	v_add_u32_e32 v156, 0x80000, v152
	global_store_dwordx4 v156, v[56:59], s[74:75]
	v_pk_fma_f32 v[52:53], v[52:53], v[204:205], v[172:173]
	v_pk_fma_f32 v[54:55], v[54:55], v[206:207], v[174:175]
	v_pk_fma_f32 v[48:49], v[48:49], v[208:209], v[176:177]
	v_pk_fma_f32 v[50:51], v[50:51], v[210:211], v[178:179]
	v_cvt_pk_bf16_f32 v51, v50, v51
	v_cvt_pk_bf16_f32 v50, v48, v49
	v_cvt_pk_bf16_f32 v49, v54, v55
	v_cvt_pk_bf16_f32 v48, v52, v53
	v_add_u32_e32 v156, 0x80000, v152
	global_store_dwordx4 v156, v[48:51], s[74:75] offset:256
	v_pk_fma_f32 v[44:45], v[44:45], v[196:197], v[180:181]
	v_pk_fma_f32 v[46:47], v[46:47], v[198:199], v[182:183]
	v_pk_fma_f32 v[40:41], v[40:41], v[200:201], v[184:185]
	v_pk_fma_f32 v[42:43], v[42:43], v[202:203], v[186:187]
	v_cvt_pk_bf16_f32 v43, v42, v43
	v_cvt_pk_bf16_f32 v42, v40, v41
	v_cvt_pk_bf16_f32 v41, v46, v47
	v_cvt_pk_bf16_f32 v40, v44, v45
	v_add_u32_e32 v156, 0x90000, v152
	global_store_dwordx4 v156, v[40:43], s[74:75]
	v_pk_fma_f32 v[36:37], v[36:37], v[204:205], v[188:189]
	v_pk_fma_f32 v[38:39], v[38:39], v[206:207], v[190:191]
	v_pk_fma_f32 v[32:33], v[32:33], v[208:209], v[212:213]
	v_pk_fma_f32 v[34:35], v[34:35], v[210:211], v[214:215]
	v_cvt_pk_bf16_f32 v35, v34, v35
	v_cvt_pk_bf16_f32 v34, v32, v33
	v_cvt_pk_bf16_f32 v33, v38, v39
	v_cvt_pk_bf16_f32 v32, v36, v37
	v_add_u32_e32 v156, 0x90000, v152
	global_store_dwordx4 v156, v[32:35], s[74:75] offset:256
	v_pk_fma_f32 v[28:29], v[28:29], v[196:197], v[216:217]
	v_pk_fma_f32 v[30:31], v[30:31], v[198:199], v[218:219]
	v_pk_fma_f32 v[24:25], v[24:25], v[200:201], v[220:221]
	v_pk_fma_f32 v[26:27], v[26:27], v[202:203], v[222:223]
	v_cvt_pk_bf16_f32 v27, v26, v27
	v_cvt_pk_bf16_f32 v26, v24, v25
	v_cvt_pk_bf16_f32 v25, v30, v31
	v_cvt_pk_bf16_f32 v24, v28, v29
	v_add_u32_e32 v156, 0xa0000, v152
	global_store_dwordx4 v156, v[24:27], s[74:75]
	v_pk_fma_f32 v[20:21], v[20:21], v[204:205], v[224:225]
	v_pk_fma_f32 v[22:23], v[22:23], v[206:207], v[226:227]
	v_pk_fma_f32 v[16:17], v[16:17], v[208:209], v[228:229]
	v_pk_fma_f32 v[18:19], v[18:19], v[210:211], v[230:231]
	v_cvt_pk_bf16_f32 v19, v18, v19
	v_cvt_pk_bf16_f32 v18, v16, v17
	v_cvt_pk_bf16_f32 v17, v22, v23
	v_cvt_pk_bf16_f32 v16, v20, v21
	v_add_u32_e32 v156, 0xa0000, v152
	global_store_dwordx4 v156, v[16:19], s[74:75] offset:256
	v_pk_fma_f32 v[12:13], v[12:13], v[196:197], v[236:237]
	v_pk_fma_f32 v[14:15], v[14:15], v[198:199], v[238:239]
	v_pk_fma_f32 v[8:9], v[8:9], v[200:201], v[240:241]
	v_pk_fma_f32 v[10:11], v[10:11], v[202:203], v[242:243]
	v_cvt_pk_bf16_f32 v11, v10, v11
	v_cvt_pk_bf16_f32 v10, v8, v9
	v_cvt_pk_bf16_f32 v9, v14, v15
	v_cvt_pk_bf16_f32 v8, v12, v13
	v_add_u32_e32 v156, 0xb0000, v152
	global_store_dwordx4 v156, v[8:11], s[74:75]
	v_pk_fma_f32 v[4:5], v[4:5], v[204:205], v[244:245]
	v_pk_fma_f32 v[6:7], v[6:7], v[206:207], v[246:247]
	v_pk_fma_f32 v[0:1], v[0:1], v[208:209], v[248:249]
	v_pk_fma_f32 v[2:3], v[2:3], v[210:211], v[250:251]
	v_cvt_pk_bf16_f32 v3, v2, v3
	v_cvt_pk_bf16_f32 v2, v0, v1
	v_cvt_pk_bf16_f32 v1, v6, v7
	v_cvt_pk_bf16_f32 v0, v4, v5
	v_add_u32_e32 v156, 0xb0000, v152
	global_store_dwordx4 v156, v[0:3], s[74:75] offset:256

.LBB0_999:
	ds_read_b128 v[156:159], v152
	ds_read_b128 v[160:163], v152 offset:1024
	ds_read_b128 v[164:167], v152 offset:2048
	ds_read_b128 v[168:171], v152 offset:3072
	s_add_u32 s20, s46, 0xfff80080
	s_addc_u32 s21, s47, -1
	s_cmp_eq_u32 s58, 28
	s_cselect_b32 s21, s15, s21
	s_cselect_b32 s20, s54, s20
	s_cselect_b32 s49, s11, s57
	s_cselect_b32 s48, s55, s56
	v_lshl_add_u64 v[148:149], s[46:47], 0, v[136:137]
	s_add_i32 m0, s35, 0xc000
	ds_read_b128 v[172:175], v153
	ds_read_b128 v[176:179], v153 offset:1024
	ds_read_b128 v[180:183], v153 offset:2048
	ds_read_b128 v[184:187], v153 offset:3072
	ds_read_b128 v[188:191], v153 offset:4096
	ds_read_b128 v[196:199], v153 offset:5120
	ds_read_b128 v[200:203], v153 offset:6144
	ds_read_b128 v[204:207], v153 offset:7168
	global_load_lds_dwordx4 v[148:149], off
	s_add_i32 m0, s35, 0xe000
	v_lshl_add_u64 v[148:149], s[46:47], 0, v[138:139]
	global_load_lds_dwordx4 v[148:149], off
	s_waitcnt lgkmcnt(8)
	s_barrier
	s_waitcnt lgkmcnt(0)
	s_setprio 1
	v_mfma_f32_16x16x32_bf16 v[124:127], v[156:159], v[172:175], v[124:127]
	v_mfma_f32_16x16x32_bf16 v[120:123], v[164:167], v[172:175], v[120:123]
	v_mfma_f32_16x16x32_bf16 v[108:111], v[156:159], v[180:183], v[108:111]
	v_mfma_f32_16x16x32_bf16 v[104:107], v[164:167], v[180:183], v[104:107]
	v_mfma_f32_16x16x32_bf16 v[92:95], v[156:159], v[188:191], v[92:95]
	v_mfma_f32_16x16x32_bf16 v[88:91], v[164:167], v[188:191], v[88:91]
	v_mfma_f32_16x16x32_bf16 v[76:79], v[156:159], v[200:203], v[76:79]
	v_mfma_f32_16x16x32_bf16 v[72:75], v[164:167], v[200:203], v[72:75]
	v_mfma_f32_16x16x32_bf16 v[124:127], v[160:163], v[176:179], v[124:127]
	v_mfma_f32_16x16x32_bf16 v[120:123], v[168:171], v[176:179], v[120:123]
	v_mfma_f32_16x16x32_bf16 v[108:111], v[160:163], v[184:187], v[108:111]
	v_mfma_f32_16x16x32_bf16 v[104:107], v[168:171], v[184:187], v[104:107]
	v_mfma_f32_16x16x32_bf16 v[92:95], v[160:163], v[196:199], v[92:95]
	v_mfma_f32_16x16x32_bf16 v[88:91], v[168:171], v[196:199], v[88:91]
	v_mfma_f32_16x16x32_bf16 v[76:79], v[160:163], v[204:207], v[76:79]
	v_mfma_f32_16x16x32_bf16 v[72:75], v[168:171], v[204:207], v[72:75]
	s_setprio 0
	s_barrier
	s_add_i32 s59, s52, s23
	v_lshl_add_u64 v[148:149], s[48:49], 0, v[132:133]
	s_mov_b32 m0, s59
	ds_read_b128 v[208:211], v154
	ds_read_b128 v[212:215], v154 offset:1024
	ds_read_b128 v[216:219], v154 offset:2048
	ds_read_b128 v[220:223], v154 offset:3072
	global_load_lds_dwordx4 v[148:149], off
	s_add_i32 m0, s59, 0x2000
	v_lshl_add_u64 v[224:225], s[48:49], 0, v[128:129]
	global_load_lds_dwordx4 v[224:225], off
	s_barrier
	s_waitcnt lgkmcnt(0)
	s_setprio 1
	v_mfma_f32_16x16x32_bf16 v[116:119], v[208:211], v[172:175], v[116:119]
	v_mfma_f32_16x16x32_bf16 v[112:115], v[216:219], v[172:175], v[112:115]
	v_mfma_f32_16x16x32_bf16 v[100:103], v[208:211], v[180:183], v[100:103]
	v_mfma_f32_16x16x32_bf16 v[96:99], v[216:219], v[180:183], v[96:99]
	v_mfma_f32_16x16x32_bf16 v[84:87], v[208:211], v[188:191], v[84:87]
	v_mfma_f32_16x16x32_bf16 v[80:83], v[216:219], v[188:191], v[80:83]
	v_mfma_f32_16x16x32_bf16 v[68:71], v[208:211], v[200:203], v[68:71]
	v_mfma_f32_16x16x32_bf16 v[64:67], v[216:219], v[200:203], v[64:67]
	v_mfma_f32_16x16x32_bf16 v[116:119], v[212:215], v[176:179], v[116:119]
	v_mfma_f32_16x16x32_bf16 v[112:115], v[220:223], v[176:179], v[112:115]
	v_mfma_f32_16x16x32_bf16 v[100:103], v[212:215], v[184:187], v[100:103]
	v_mfma_f32_16x16x32_bf16 v[96:99], v[220:223], v[184:187], v[96:99]
	v_mfma_f32_16x16x32_bf16 v[84:87], v[212:215], v[196:199], v[84:87]
	v_mfma_f32_16x16x32_bf16 v[80:83], v[220:223], v[196:199], v[80:83]
	v_mfma_f32_16x16x32_bf16 v[68:71], v[212:215], v[204:207], v[68:71]
	v_mfma_f32_16x16x32_bf16 v[64:67], v[220:223], v[204:207], v[64:67]
	s_setprio 0
	s_mov_b32 m0, s35
	v_lshl_add_u64 v[226:227], s[20:21], 0, v[134:135]
	s_barrier
	ds_read_b128 v[172:175], v153 offset:16384
	ds_read_b128 v[176:179], v153 offset:17408
	ds_read_b128 v[180:183], v153 offset:18432
	ds_read_b128 v[184:187], v153 offset:19456
	ds_read_b128 v[188:191], v153 offset:20480
	ds_read_b128 v[196:199], v153 offset:21504
	ds_read_b128 v[200:203], v153 offset:22528
	ds_read_b128 v[204:207], v153 offset:23552
	global_load_lds_dwordx4 v[226:227], off
	s_mov_b32 m0, s36
	v_lshl_add_u64 v[228:229], s[20:21], 0, v[130:131]
	global_load_lds_dwordx4 v[228:229], off
	s_barrier
	s_waitcnt lgkmcnt(0)
	s_setprio 1
	v_mfma_f32_16x16x32_bf16 v[60:63], v[156:159], v[172:175], v[60:63]
	v_mfma_f32_16x16x32_bf16 v[56:59], v[164:167], v[172:175], v[56:59]
	v_mfma_f32_16x16x32_bf16 v[44:47], v[156:159], v[180:183], v[44:47]
	v_mfma_f32_16x16x32_bf16 v[40:43], v[164:167], v[180:183], v[40:43]
	v_mfma_f32_16x16x32_bf16 v[28:31], v[156:159], v[188:191], v[28:31]
	v_mfma_f32_16x16x32_bf16 v[24:27], v[164:167], v[188:191], v[24:27]
	v_mfma_f32_16x16x32_bf16 v[12:15], v[156:159], v[200:203], v[12:15]
	v_mfma_f32_16x16x32_bf16 v[8:11], v[164:167], v[200:203], v[8:11]
	v_mfma_f32_16x16x32_bf16 v[60:63], v[160:163], v[176:179], v[60:63]
	v_mfma_f32_16x16x32_bf16 v[56:59], v[168:171], v[176:179], v[56:59]
	v_mfma_f32_16x16x32_bf16 v[44:47], v[160:163], v[184:187], v[44:47]
	v_mfma_f32_16x16x32_bf16 v[40:43], v[168:171], v[184:187], v[40:43]
	v_mfma_f32_16x16x32_bf16 v[28:31], v[160:163], v[196:199], v[28:31]
	v_mfma_f32_16x16x32_bf16 v[24:27], v[168:171], v[196:199], v[24:27]
	v_mfma_f32_16x16x32_bf16 v[12:15], v[160:163], v[204:207], v[12:15]
	v_mfma_f32_16x16x32_bf16 v[8:11], v[168:171], v[204:207], v[8:11]
	s_setprio 0
	s_barrier
	s_add_u32 s60, s48, 0x80000
	s_addc_u32 s61, s49, 0
	s_add_i32 s59, s53, s23
	s_mov_b32 m0, s59
	v_lshl_add_u64 v[156:157], s[60:61], 0, v[132:133]
	global_load_lds_dwordx4 v[156:157], off
	s_add_i32 m0, s59, 0x2000
	v_lshl_add_u64 v[156:157], s[60:61], 0, v[128:129]
	global_load_lds_dwordx4 v[156:157], off
	s_waitcnt vmcnt(6)
	s_barrier
	s_setprio 1
	v_mfma_f32_16x16x32_bf16 v[52:55], v[208:211], v[172:175], v[52:55]
	v_mfma_f32_16x16x32_bf16 v[48:51], v[216:219], v[172:175], v[48:51]
	v_mfma_f32_16x16x32_bf16 v[36:39], v[208:211], v[180:183], v[36:39]
	v_mfma_f32_16x16x32_bf16 v[32:35], v[216:219], v[180:183], v[32:35]
	v_mfma_f32_16x16x32_bf16 v[20:23], v[208:211], v[188:191], v[20:23]
	v_mfma_f32_16x16x32_bf16 v[16:19], v[216:219], v[188:191], v[16:19]
	v_mfma_f32_16x16x32_bf16 v[4:7], v[208:211], v[200:203], v[4:7]
	v_mfma_f32_16x16x32_bf16 v[0:3], v[216:219], v[200:203], v[0:3]
	v_mfma_f32_16x16x32_bf16 v[52:55], v[212:215], v[176:179], v[52:55]
	v_mfma_f32_16x16x32_bf16 v[48:51], v[220:223], v[176:179], v[48:51]
	v_mfma_f32_16x16x32_bf16 v[36:39], v[212:215], v[184:187], v[36:39]
	v_mfma_f32_16x16x32_bf16 v[32:35], v[220:223], v[184:187], v[32:35]
	v_mfma_f32_16x16x32_bf16 v[20:23], v[212:215], v[196:199], v[20:23]
	v_mfma_f32_16x16x32_bf16 v[16:19], v[220:223], v[196:199], v[16:19]
	v_mfma_f32_16x16x32_bf16 v[4:7], v[212:215], v[204:207], v[4:7]
	v_mfma_f32_16x16x32_bf16 v[0:3], v[220:223], v[204:207], v[0:3]
	s_setprio 0
	s_add_i32 s59, 0, 0x18000
	v_add_u32_e32 v155, s59, v150
	s_barrier
	ds_read_b128 v[156:159], v155
	ds_read_b128 v[160:163], v155 offset:1024
	ds_read_b128 v[164:167], v155 offset:2048
	ds_read_b128 v[168:171], v155 offset:3072
	s_add_u32 s20, s20, 0x80000
	s_addc_u32 s21, s21, 0
	s_mov_b32 m0, s37
	v_lshl_add_u64 v[208:209], s[20:21], 0, v[134:135]
	ds_read_b128 v[172:175], v153 offset:32768
	ds_read_b128 v[176:179], v153 offset:33792
	ds_read_b128 v[180:183], v153 offset:34816
	ds_read_b128 v[184:187], v153 offset:35840
	ds_read_b128 v[188:191], v153 offset:36864
	ds_read_b128 v[196:199], v153 offset:37888
	ds_read_b128 v[200:203], v153 offset:38912
	ds_read_b128 v[204:207], v153 offset:39936
	global_load_lds_dwordx4 v[208:209], off
	s_mov_b32 m0, s38
	v_lshl_add_u64 v[208:209], s[20:21], 0, v[130:131]
	global_load_lds_dwordx4 v[208:209], off
	s_waitcnt lgkmcnt(8)
	s_barrier
	s_waitcnt lgkmcnt(0)
	s_setprio 1
	v_mfma_f32_16x16x32_bf16 v[124:127], v[156:159], v[172:175], v[124:127]
	v_mfma_f32_16x16x32_bf16 v[120:123], v[164:167], v[172:175], v[120:123]
	v_mfma_f32_16x16x32_bf16 v[108:111], v[156:159], v[180:183], v[108:111]
	v_mfma_f32_16x16x32_bf16 v[104:107], v[164:167], v[180:183], v[104:107]
	v_mfma_f32_16x16x32_bf16 v[92:95], v[156:159], v[188:191], v[92:95]
	v_mfma_f32_16x16x32_bf16 v[88:91], v[164:167], v[188:191], v[88:91]
	v_mfma_f32_16x16x32_bf16 v[76:79], v[156:159], v[200:203], v[76:79]
	v_mfma_f32_16x16x32_bf16 v[72:75], v[164:167], v[200:203], v[72:75]
	v_mfma_f32_16x16x32_bf16 v[124:127], v[160:163], v[176:179], v[124:127]
	v_mfma_f32_16x16x32_bf16 v[120:123], v[168:171], v[176:179], v[120:123]
	v_mfma_f32_16x16x32_bf16 v[108:111], v[160:163], v[184:187], v[108:111]
	v_mfma_f32_16x16x32_bf16 v[104:107], v[168:171], v[184:187], v[104:107]
	v_mfma_f32_16x16x32_bf16 v[92:95], v[160:163], v[196:199], v[92:95]
	v_mfma_f32_16x16x32_bf16 v[88:91], v[168:171], v[196:199], v[88:91]
	v_mfma_f32_16x16x32_bf16 v[76:79], v[160:163], v[204:207], v[76:79]
	v_mfma_f32_16x16x32_bf16 v[72:75], v[168:171], v[204:207], v[72:75]
	s_setprio 0
	s_barrier
	s_add_i32 s60, 0, 0x1c000
	s_add_i32 s20, s59, s23
	v_add_u32_e32 v155, s60, v150
	v_lshl_add_u64 v[148:149], v[148:149], 0, s[8:9]
	s_mov_b32 m0, s20
	ds_read_b128 v[208:211], v155
	ds_read_b128 v[212:215], v155 offset:1024
	ds_read_b128 v[216:219], v155 offset:2048
	ds_read_b128 v[220:223], v155 offset:3072
	global_load_lds_dwordx4 v[148:149], off
	s_add_i32 m0, s20, 0x2000
	v_lshl_add_u64 v[148:149], v[224:225], 0, s[8:9]
	global_load_lds_dwordx4 v[148:149], off
	s_barrier
	s_waitcnt lgkmcnt(0)
	s_setprio 1
	v_mfma_f32_16x16x32_bf16 v[116:119], v[208:211], v[172:175], v[116:119]
	v_mfma_f32_16x16x32_bf16 v[112:115], v[216:219], v[172:175], v[112:115]
	v_mfma_f32_16x16x32_bf16 v[100:103], v[208:211], v[180:183], v[100:103]
	v_mfma_f32_16x16x32_bf16 v[96:99], v[216:219], v[180:183], v[96:99]
	v_mfma_f32_16x16x32_bf16 v[84:87], v[208:211], v[188:191], v[84:87]
	v_mfma_f32_16x16x32_bf16 v[80:83], v[216:219], v[188:191], v[80:83]
	v_mfma_f32_16x16x32_bf16 v[68:71], v[208:211], v[200:203], v[68:71]
	v_mfma_f32_16x16x32_bf16 v[64:67], v[216:219], v[200:203], v[64:67]
	v_mfma_f32_16x16x32_bf16 v[116:119], v[212:215], v[176:179], v[116:119]
	v_mfma_f32_16x16x32_bf16 v[112:115], v[220:223], v[176:179], v[112:115]
	v_mfma_f32_16x16x32_bf16 v[100:103], v[212:215], v[184:187], v[100:103]
	v_mfma_f32_16x16x32_bf16 v[96:99], v[220:223], v[184:187], v[96:99]
	v_mfma_f32_16x16x32_bf16 v[84:87], v[212:215], v[196:199], v[84:87]
	v_mfma_f32_16x16x32_bf16 v[80:83], v[220:223], v[196:199], v[80:83]
	v_mfma_f32_16x16x32_bf16 v[68:71], v[212:215], v[204:207], v[68:71]
	v_mfma_f32_16x16x32_bf16 v[64:67], v[220:223], v[204:207], v[64:67]
	s_setprio 0
	s_mov_b32 m0, s45
	v_lshl_add_u64 v[148:149], v[226:227], 0, s[8:9]
	s_barrier
	ds_read_b128 v[172:175], v153 offset:49152
	ds_read_b128 v[176:179], v153 offset:50176
	ds_read_b128 v[180:183], v153 offset:51200
	ds_read_b128 v[184:187], v153 offset:52224
	ds_read_b128 v[188:191], v153 offset:53248
	ds_read_b128 v[196:199], v153 offset:54272
	ds_read_b128 v[200:203], v153 offset:55296
	ds_read_b128 v[204:207], v153 offset:56320
	global_load_lds_dwordx4 v[148:149], off
	s_mov_b32 m0, s50
	v_lshl_add_u64 v[148:149], v[228:229], 0, s[8:9]
	global_load_lds_dwordx4 v[148:149], off
	s_barrier
	s_waitcnt lgkmcnt(0)
	s_setprio 1
	v_mfma_f32_16x16x32_bf16 v[60:63], v[156:159], v[172:175], v[60:63]
	v_mfma_f32_16x16x32_bf16 v[56:59], v[164:167], v[172:175], v[56:59]
	v_mfma_f32_16x16x32_bf16 v[44:47], v[156:159], v[180:183], v[44:47]
	v_mfma_f32_16x16x32_bf16 v[40:43], v[164:167], v[180:183], v[40:43]
	v_mfma_f32_16x16x32_bf16 v[28:31], v[156:159], v[188:191], v[28:31]
	v_mfma_f32_16x16x32_bf16 v[24:27], v[164:167], v[188:191], v[24:27]
	v_mfma_f32_16x16x32_bf16 v[12:15], v[156:159], v[200:203], v[12:15]
	v_mfma_f32_16x16x32_bf16 v[8:11], v[164:167], v[200:203], v[8:11]
	v_mfma_f32_16x16x32_bf16 v[60:63], v[160:163], v[176:179], v[60:63]
	v_mfma_f32_16x16x32_bf16 v[56:59], v[168:171], v[176:179], v[56:59]
	v_mfma_f32_16x16x32_bf16 v[44:47], v[160:163], v[184:187], v[44:47]
	v_mfma_f32_16x16x32_bf16 v[40:43], v[168:171], v[184:187], v[40:43]
	v_mfma_f32_16x16x32_bf16 v[28:31], v[160:163], v[196:199], v[28:31]
	v_mfma_f32_16x16x32_bf16 v[24:27], v[168:171], v[196:199], v[24:27]
	v_mfma_f32_16x16x32_bf16 v[12:15], v[160:163], v[204:207], v[12:15]
	v_mfma_f32_16x16x32_bf16 v[8:11], v[168:171], v[204:207], v[8:11]
	s_setprio 0
	s_barrier
	s_add_u32 s20, s48, 0x80080
	s_addc_u32 s21, s49, 0
	s_add_i32 s48, s60, s23
	s_mov_b32 m0, s48
	v_lshl_add_u64 v[148:149], s[20:21], 0, v[132:133]
	global_load_lds_dwordx4 v[148:149], off
	s_add_i32 m0, s48, 0x2000
	v_lshl_add_u64 v[148:149], s[20:21], 0, v[128:129]
	global_load_lds_dwordx4 v[148:149], off
	s_waitcnt vmcnt(6)
	s_barrier
	s_setprio 1
	v_mfma_f32_16x16x32_bf16 v[52:55], v[208:211], v[172:175], v[52:55]
	v_mfma_f32_16x16x32_bf16 v[48:51], v[216:219], v[172:175], v[48:51]
	v_mfma_f32_16x16x32_bf16 v[36:39], v[208:211], v[180:183], v[36:39]
	v_mfma_f32_16x16x32_bf16 v[32:35], v[216:219], v[180:183], v[32:35]
	v_mfma_f32_16x16x32_bf16 v[20:23], v[208:211], v[188:191], v[20:23]
	v_mfma_f32_16x16x32_bf16 v[16:19], v[216:219], v[188:191], v[16:19]
	v_mfma_f32_16x16x32_bf16 v[4:7], v[208:211], v[200:203], v[4:7]
	v_mfma_f32_16x16x32_bf16 v[0:3], v[216:219], v[200:203], v[0:3]
	v_mfma_f32_16x16x32_bf16 v[52:55], v[212:215], v[176:179], v[52:55]
	v_mfma_f32_16x16x32_bf16 v[48:51], v[220:223], v[176:179], v[48:51]
	v_mfma_f32_16x16x32_bf16 v[36:39], v[212:215], v[184:187], v[36:39]
	v_mfma_f32_16x16x32_bf16 v[32:35], v[220:223], v[184:187], v[32:35]
	v_mfma_f32_16x16x32_bf16 v[20:23], v[212:215], v[196:199], v[20:23]
	v_mfma_f32_16x16x32_bf16 v[16:19], v[220:223], v[196:199], v[16:19]
	v_mfma_f32_16x16x32_bf16 v[4:7], v[212:215], v[204:207], v[4:7]
	v_mfma_f32_16x16x32_bf16 v[0:3], v[220:223], v[204:207], v[0:3]
	s_setprio 0
	s_add_i32 s58, s58, 2
	s_add_u32 s46, s46, 0x100
	s_addc_u32 s47, s47, 0
	s_add_u32 s56, s56, 0x100
	s_addc_u32 s57, s57, 0
	s_cmp_gt_u32 s58, 29
	s_cbranch_scc0 .Ldup_nl_mlpin0
	s_cmpk_gt_u32 s12, 0xff
	s_cbranch_scc0 .Ldup_nl_mlpin0
	v_lshl_add_u32 v148, s44, 8, v147
	v_max_f32_e32 v124, v124, v124
	v_max_f32_e32 v120, v120, v120
	v_ashrrev_i32_e32 v149, 31, v148
	v_max_f32_e32 v124, 0, v124
	v_max_f32_e32 v120, 0, v120
	v_lshlrev_b64 v[158:159], 14, v[148:149]
	v_mul_f32_e32 v149, v124, v124
	v_mul_f32_e32 v124, v120, v120
	v_max_f32_e32 v120, v125, v125
	v_max_f32_e32 v121, v121, v121
	v_max_f32_e32 v120, 0, v120
	v_max_f32_e32 v121, 0, v121
	v_mul_f32_e32 v155, v120, v120
	v_mul_f32_e32 v160, v121, v121
	v_max_f32_e32 v120, v126, v126
	v_max_f32_e32 v121, v122, v122
	v_max_f32_e32 v120, 0, v120
	v_max_f32_e32 v121, 0, v121
	v_lshl_or_b32 v156, s33, 8, v151
	v_mul_f32_e32 v161, v120, v120
	v_mul_f32_e32 v125, v121, v121
	v_max_f32_e32 v120, v127, v127
	v_max_f32_e32 v121, v123, v123
	v_max_f32_e32 v116, v116, v116
	v_max_f32_e32 v112, v112, v112
	v_max_f32_e32 v117, v117, v117
	v_max_f32_e32 v113, v113, v113
	v_max_f32_e32 v118, v118, v118
	v_max_f32_e32 v114, v114, v114
	v_max_f32_e32 v119, v119, v119
	v_max_f32_e32 v115, v115, v115
	v_ashrrev_i32_e32 v157, 31, v156
	v_max_f32_e32 v120, 0, v120
	v_max_f32_e32 v121, 0, v121
	v_max_f32_e32 v116, 0, v116
	v_max_f32_e32 v112, 0, v112
	v_max_f32_e32 v117, 0, v117
	v_max_f32_e32 v113, 0, v113
	v_max_f32_e32 v118, 0, v118
	v_max_f32_e32 v114, 0, v114
	v_max_f32_e32 v119, 0, v119
	v_max_f32_e32 v115, 0, v115
	v_mul_f32_e32 v162, v120, v120
	v_mul_f32_e32 v163, v121, v121
	v_lshl_add_u64 v[122:123], s[28:29], 0, v[158:159]
	v_lshlrev_b64 v[120:121], 1, v[156:157]
	v_mul_f32_e32 v116, v116, v116
	v_mul_f32_e32 v112, v112, v112
	v_mul_f32_e32 v117, v117, v117
	v_mul_f32_e32 v113, v113, v113
	v_mul_f32_e32 v118, v118, v118
	v_mul_f32_e32 v114, v114, v114
	v_mul_f32_e32 v119, v119, v119
	v_mul_f32_e32 v115, v115, v115
	v_max_f32_e32 v104, v104, v104
	v_lshl_add_u64 v[126:127], v[122:123], 0, v[120:121]
	v_cvt_pk_bf16_f32 v115, v114, v115
	v_cvt_pk_bf16_f32 v114, v112, v113
	v_cvt_pk_bf16_f32 v113, v118, v119
	v_cvt_pk_bf16_f32 v112, v116, v117
	v_max_f32_e32 v104, 0, v104
	global_store_dwordx4 v[126:127], v[112:115], off offset:256
	v_max_f32_e32 v105, v105, v105
	v_max_f32_e32 v105, 0, v105
	v_mul_f32_e32 v115, v104, v104
	v_max_f32_e32 v104, v109, v109
	v_max_f32_e32 v104, 0, v104
	v_mul_f32_e32 v116, v104, v104
	v_mul_f32_e32 v117, v105, v105
	v_max_f32_e32 v104, v110, v110
	v_max_f32_e32 v105, v106, v106
	v_or_b32_e32 v112, 16, v148
	v_max_f32_e32 v104, 0, v104
	v_max_f32_e32 v105, 0, v105
	v_ashrrev_i32_e32 v113, 31, v112
	v_mul_f32_e32 v110, v104, v104
	v_mul_f32_e32 v106, v105, v105
	v_max_f32_e32 v104, v111, v111
	v_max_f32_e32 v105, v107, v107
	v_max_f32_e32 v100, v100, v100
	v_max_f32_e32 v96, v96, v96
	v_max_f32_e32 v101, v101, v101
	v_max_f32_e32 v97, v97, v97
	v_max_f32_e32 v102, v102, v102
	v_max_f32_e32 v98, v98, v98
	v_max_f32_e32 v103, v103, v103
	v_max_f32_e32 v99, v99, v99
	v_lshlrev_b64 v[112:113], 14, v[112:113]
	v_max_f32_e32 v108, v108, v108
	v_max_f32_e32 v104, 0, v104
	v_max_f32_e32 v105, 0, v105
	v_max_f32_e32 v100, 0, v100
	v_max_f32_e32 v96, 0, v96
	v_max_f32_e32 v101, 0, v101
	v_max_f32_e32 v97, 0, v97
	v_max_f32_e32 v102, 0, v102
	v_max_f32_e32 v98, 0, v98
	v_max_f32_e32 v103, 0, v103
	v_max_f32_e32 v99, 0, v99
	v_max_f32_e32 v108, 0, v108
	v_mul_f32_e32 v111, v104, v104
	v_mul_f32_e32 v107, v105, v105
	v_lshl_add_u64 v[104:105], s[28:29], 0, v[112:113]
	v_mul_f32_e32 v100, v100, v100
	v_mul_f32_e32 v96, v96, v96
	v_mul_f32_e32 v101, v101, v101
	v_mul_f32_e32 v97, v97, v97
	v_mul_f32_e32 v102, v102, v102
	v_mul_f32_e32 v98, v98, v98
	v_mul_f32_e32 v103, v103, v103
	v_mul_f32_e32 v99, v99, v99
	v_max_f32_e32 v88, v88, v88
	v_mul_f32_e32 v114, v108, v108
	v_lshl_add_u64 v[108:109], v[104:105], 0, v[120:121]
	v_cvt_pk_bf16_f32 v99, v98, v99
	v_cvt_pk_bf16_f32 v98, v96, v97
	v_cvt_pk_bf16_f32 v97, v102, v103
	v_cvt_pk_bf16_f32 v96, v100, v101
	v_max_f32_e32 v88, 0, v88
	global_store_dwordx4 v[108:109], v[96:99], off offset:256
	v_max_f32_e32 v89, v89, v89
	v_max_f32_e32 v89, 0, v89
	v_mul_f32_e32 v99, v88, v88
	v_max_f32_e32 v88, v93, v93
	v_max_f32_e32 v88, 0, v88
	v_mul_f32_e32 v100, v88, v88
	v_mul_f32_e32 v101, v89, v89
	v_max_f32_e32 v88, v94, v94
	v_max_f32_e32 v89, v90, v90
	v_or_b32_e32 v96, 32, v148
	v_max_f32_e32 v88, 0, v88
	v_max_f32_e32 v89, 0, v89
	v_ashrrev_i32_e32 v97, 31, v96
	v_mul_f32_e32 v94, v88, v88
	v_mul_f32_e32 v90, v89, v89
	v_max_f32_e32 v88, v95, v95
	v_max_f32_e32 v89, v91, v91
	v_max_f32_e32 v84, v84, v84
	v_max_f32_e32 v80, v80, v80
	v_max_f32_e32 v85, v85, v85
	v_max_f32_e32 v81, v81, v81
	v_max_f32_e32 v86, v86, v86
	v_max_f32_e32 v82, v82, v82
	v_max_f32_e32 v87, v87, v87
	v_max_f32_e32 v83, v83, v83
	v_lshlrev_b64 v[96:97], 14, v[96:97]
	v_max_f32_e32 v92, v92, v92
	v_max_f32_e32 v88, 0, v88
	v_max_f32_e32 v89, 0, v89
	v_max_f32_e32 v84, 0, v84
	v_max_f32_e32 v80, 0, v80
	v_max_f32_e32 v85, 0, v85
	v_max_f32_e32 v81, 0, v81
	v_max_f32_e32 v86, 0, v86
	v_max_f32_e32 v82, 0, v82
	v_max_f32_e32 v87, 0, v87
	v_max_f32_e32 v83, 0, v83
	v_max_f32_e32 v92, 0, v92
	v_mul_f32_e32 v95, v88, v88
	v_mul_f32_e32 v91, v89, v89
	v_lshl_add_u64 v[88:89], s[28:29], 0, v[96:97]
	v_mul_f32_e32 v84, v84, v84
	v_mul_f32_e32 v80, v80, v80
	v_mul_f32_e32 v85, v85, v85
	v_mul_f32_e32 v81, v81, v81
	v_mul_f32_e32 v86, v86, v86
	v_mul_f32_e32 v82, v82, v82
	v_mul_f32_e32 v87, v87, v87
	v_mul_f32_e32 v83, v83, v83
	v_max_f32_e32 v72, v72, v72
	v_mul_f32_e32 v98, v92, v92
	v_lshl_add_u64 v[92:93], v[88:89], 0, v[120:121]
	v_cvt_pk_bf16_f32 v83, v82, v83
	v_cvt_pk_bf16_f32 v82, v80, v81
	v_cvt_pk_bf16_f32 v81, v86, v87
	v_cvt_pk_bf16_f32 v80, v84, v85
	v_max_f32_e32 v72, 0, v72
	global_store_dwordx4 v[92:93], v[80:83], off offset:256
	v_max_f32_e32 v73, v73, v73
	v_max_f32_e32 v73, 0, v73
	v_mul_f32_e32 v83, v72, v72
	v_max_f32_e32 v72, v77, v77
	v_max_f32_e32 v72, 0, v72
	v_mul_f32_e32 v84, v72, v72
	v_mul_f32_e32 v85, v73, v73
	v_max_f32_e32 v72, v78, v78
	v_max_f32_e32 v73, v74, v74
	v_or_b32_e32 v80, 48, v148
	v_max_f32_e32 v72, 0, v72
	v_max_f32_e32 v73, 0, v73
	v_ashrrev_i32_e32 v81, 31, v80
	v_mul_f32_e32 v78, v72, v72
	v_mul_f32_e32 v74, v73, v73
	v_max_f32_e32 v72, v79, v79
	v_max_f32_e32 v73, v75, v75
	v_max_f32_e32 v68, v68, v68
	v_max_f32_e32 v64, v64, v64
	v_max_f32_e32 v69, v69, v69
	v_max_f32_e32 v65, v65, v65
	v_max_f32_e32 v70, v70, v70
	v_max_f32_e32 v66, v66, v66
	v_max_f32_e32 v71, v71, v71
	v_max_f32_e32 v67, v67, v67
	v_lshlrev_b64 v[80:81], 14, v[80:81]
	v_max_f32_e32 v76, v76, v76
	v_max_f32_e32 v72, 0, v72
	v_max_f32_e32 v73, 0, v73
	v_max_f32_e32 v68, 0, v68
	v_max_f32_e32 v64, 0, v64
	v_max_f32_e32 v69, 0, v69
	v_max_f32_e32 v65, 0, v65
	v_max_f32_e32 v70, 0, v70
	v_max_f32_e32 v66, 0, v66
	v_max_f32_e32 v71, 0, v71
	v_max_f32_e32 v67, 0, v67
	v_max_f32_e32 v76, 0, v76
	v_mul_f32_e32 v79, v72, v72
	v_mul_f32_e32 v75, v73, v73
	v_lshl_add_u64 v[72:73], s[28:29], 0, v[80:81]
	v_mul_f32_e32 v68, v68, v68
	v_mul_f32_e32 v64, v64, v64
	v_mul_f32_e32 v69, v69, v69
	v_mul_f32_e32 v65, v65, v65
	v_mul_f32_e32 v70, v70, v70
	v_mul_f32_e32 v66, v66, v66
	v_mul_f32_e32 v71, v71, v71
	v_mul_f32_e32 v67, v67, v67
	v_max_f32_e32 v56, v56, v56
	v_mul_f32_e32 v82, v76, v76
	v_lshl_add_u64 v[76:77], v[72:73], 0, v[120:121]
	v_cvt_pk_bf16_f32 v67, v66, v67
	v_cvt_pk_bf16_f32 v66, v64, v65
	v_cvt_pk_bf16_f32 v65, v70, v71
	v_cvt_pk_bf16_f32 v64, v68, v69
	v_max_f32_e32 v56, 0, v56
	global_store_dwordx4 v[76:77], v[64:67], off offset:256
	v_max_f32_e32 v57, v57, v57
	v_max_f32_e32 v57, 0, v57
	v_mul_f32_e32 v67, v56, v56
	v_max_f32_e32 v56, v61, v61
	v_max_f32_e32 v56, 0, v56
	v_mul_f32_e32 v68, v56, v56
	v_mul_f32_e32 v69, v57, v57
	v_max_f32_e32 v56, v62, v62
	v_max_f32_e32 v57, v58, v58
	v_add_u32_e32 v64, 0x80, v148
	v_max_f32_e32 v56, 0, v56
	v_max_f32_e32 v57, 0, v57
	v_ashrrev_i32_e32 v65, 31, v64
	v_mul_f32_e32 v62, v56, v56
	v_mul_f32_e32 v58, v57, v57
	v_max_f32_e32 v56, v63, v63
	v_max_f32_e32 v57, v59, v59
	v_max_f32_e32 v52, v52, v52
	v_max_f32_e32 v48, v48, v48
	v_max_f32_e32 v53, v53, v53
	v_max_f32_e32 v49, v49, v49
	v_max_f32_e32 v54, v54, v54
	v_max_f32_e32 v50, v50, v50
	v_max_f32_e32 v55, v55, v55
	v_max_f32_e32 v51, v51, v51
	v_lshlrev_b64 v[64:65], 14, v[64:65]
	v_max_f32_e32 v60, v60, v60
	v_max_f32_e32 v56, 0, v56
	v_max_f32_e32 v57, 0, v57
	v_max_f32_e32 v52, 0, v52
	v_max_f32_e32 v48, 0, v48
	v_max_f32_e32 v53, 0, v53
	v_max_f32_e32 v49, 0, v49
	v_max_f32_e32 v54, 0, v54
	v_max_f32_e32 v50, 0, v50
	v_max_f32_e32 v55, 0, v55
	v_max_f32_e32 v51, 0, v51
	v_max_f32_e32 v60, 0, v60
	v_mul_f32_e32 v63, v56, v56
	v_mul_f32_e32 v59, v57, v57
	v_lshl_add_u64 v[56:57], s[28:29], 0, v[64:65]
	v_mul_f32_e32 v52, v52, v52
	v_mul_f32_e32 v48, v48, v48
	v_mul_f32_e32 v53, v53, v53
	v_mul_f32_e32 v49, v49, v49
	v_mul_f32_e32 v54, v54, v54
	v_mul_f32_e32 v50, v50, v50
	v_mul_f32_e32 v55, v55, v55
	v_mul_f32_e32 v51, v51, v51
	v_max_f32_e32 v40, v40, v40
	v_mul_f32_e32 v66, v60, v60
	v_lshl_add_u64 v[60:61], v[56:57], 0, v[120:121]
	v_cvt_pk_bf16_f32 v51, v50, v51
	v_cvt_pk_bf16_f32 v50, v48, v49
	v_cvt_pk_bf16_f32 v49, v54, v55
	v_cvt_pk_bf16_f32 v48, v52, v53
	v_max_f32_e32 v40, 0, v40
	global_store_dwordx4 v[60:61], v[48:51], off offset:256
	v_max_f32_e32 v41, v41, v41
	v_max_f32_e32 v41, 0, v41
	v_mul_f32_e32 v51, v40, v40
	v_max_f32_e32 v40, v45, v45
	v_max_f32_e32 v40, 0, v40
	v_mul_f32_e32 v52, v40, v40
	v_mul_f32_e32 v53, v41, v41
	v_max_f32_e32 v40, v46, v46
	v_max_f32_e32 v41, v42, v42
	v_add_u32_e32 v48, 0x90, v148
	v_max_f32_e32 v40, 0, v40
	v_max_f32_e32 v41, 0, v41
	v_ashrrev_i32_e32 v49, 31, v48
	v_mul_f32_e32 v46, v40, v40
	v_mul_f32_e32 v42, v41, v41
	v_max_f32_e32 v40, v47, v47
	v_max_f32_e32 v41, v43, v43
	v_max_f32_e32 v36, v36, v36
	v_max_f32_e32 v32, v32, v32
	v_max_f32_e32 v37, v37, v37
	v_max_f32_e32 v33, v33, v33
	v_max_f32_e32 v38, v38, v38
	v_max_f32_e32 v34, v34, v34
	v_max_f32_e32 v39, v39, v39
	v_max_f32_e32 v35, v35, v35
	v_lshlrev_b64 v[48:49], 14, v[48:49]
	v_max_f32_e32 v44, v44, v44
	v_max_f32_e32 v40, 0, v40
	v_max_f32_e32 v41, 0, v41
	v_max_f32_e32 v36, 0, v36
	v_max_f32_e32 v32, 0, v32
	v_max_f32_e32 v37, 0, v37
	v_max_f32_e32 v33, 0, v33
	v_max_f32_e32 v38, 0, v38
	v_max_f32_e32 v34, 0, v34
	v_max_f32_e32 v39, 0, v39
	v_max_f32_e32 v35, 0, v35
	v_max_f32_e32 v44, 0, v44
	v_mul_f32_e32 v47, v40, v40
	v_mul_f32_e32 v43, v41, v41
	v_lshl_add_u64 v[40:41], s[28:29], 0, v[48:49]
	v_mul_f32_e32 v36, v36, v36
	v_mul_f32_e32 v32, v32, v32
	v_mul_f32_e32 v37, v37, v37
	v_mul_f32_e32 v33, v33, v33
	v_mul_f32_e32 v38, v38, v38
	v_mul_f32_e32 v34, v34, v34
	v_mul_f32_e32 v39, v39, v39
	v_mul_f32_e32 v35, v35, v35
	v_max_f32_e32 v24, v24, v24
	v_mul_f32_e32 v50, v44, v44
	v_lshl_add_u64 v[44:45], v[40:41], 0, v[120:121]
	v_cvt_pk_bf16_f32 v35, v34, v35
	v_cvt_pk_bf16_f32 v34, v32, v33
	v_cvt_pk_bf16_f32 v33, v38, v39
	v_cvt_pk_bf16_f32 v32, v36, v37
	v_max_f32_e32 v24, 0, v24
	global_store_dwordx4 v[44:45], v[32:35], off offset:256
	v_max_f32_e32 v25, v25, v25
	v_max_f32_e32 v25, 0, v25
	v_mul_f32_e32 v35, v24, v24
	v_max_f32_e32 v24, v29, v29
	v_max_f32_e32 v24, 0, v24
	v_mul_f32_e32 v36, v24, v24
	v_mul_f32_e32 v37, v25, v25
	v_max_f32_e32 v24, v30, v30
	v_max_f32_e32 v25, v26, v26
	v_add_u32_e32 v32, 0xa0, v148
	v_max_f32_e32 v24, 0, v24
	v_max_f32_e32 v25, 0, v25
	v_ashrrev_i32_e32 v33, 31, v32
	v_mul_f32_e32 v30, v24, v24
	v_mul_f32_e32 v26, v25, v25
	v_max_f32_e32 v24, v31, v31
	v_max_f32_e32 v25, v27, v27
	v_max_f32_e32 v20, v20, v20
	v_max_f32_e32 v16, v16, v16
	v_max_f32_e32 v21, v21, v21
	v_max_f32_e32 v17, v17, v17
	v_max_f32_e32 v22, v22, v22
	v_max_f32_e32 v18, v18, v18
	v_max_f32_e32 v23, v23, v23
	v_max_f32_e32 v19, v19, v19
	v_lshlrev_b64 v[32:33], 14, v[32:33]
	v_max_f32_e32 v28, v28, v28
	v_max_f32_e32 v24, 0, v24
	v_max_f32_e32 v25, 0, v25
	v_max_f32_e32 v20, 0, v20
	v_max_f32_e32 v16, 0, v16
	v_max_f32_e32 v21, 0, v21
	v_max_f32_e32 v17, 0, v17
	v_max_f32_e32 v22, 0, v22
	v_max_f32_e32 v18, 0, v18
	v_max_f32_e32 v23, 0, v23
	v_max_f32_e32 v19, 0, v19
	v_max_f32_e32 v28, 0, v28
	v_mul_f32_e32 v31, v24, v24
	v_mul_f32_e32 v27, v25, v25
	v_lshl_add_u64 v[24:25], s[28:29], 0, v[32:33]
	v_mul_f32_e32 v20, v20, v20
	v_mul_f32_e32 v16, v16, v16
	v_mul_f32_e32 v21, v21, v21
	v_mul_f32_e32 v17, v17, v17
	v_mul_f32_e32 v22, v22, v22
	v_mul_f32_e32 v18, v18, v18
	v_mul_f32_e32 v23, v23, v23
	v_mul_f32_e32 v19, v19, v19
	v_max_f32_e32 v8, v8, v8
	v_mul_f32_e32 v34, v28, v28
	v_lshl_add_u64 v[28:29], v[24:25], 0, v[120:121]
	v_cvt_pk_bf16_f32 v19, v18, v19
	v_cvt_pk_bf16_f32 v18, v16, v17
	v_cvt_pk_bf16_f32 v17, v22, v23
	v_cvt_pk_bf16_f32 v16, v20, v21
	v_max_f32_e32 v8, 0, v8
	global_store_dwordx4 v[28:29], v[16:19], off offset:256
	v_max_f32_e32 v9, v9, v9
	v_max_f32_e32 v9, 0, v9
	v_mul_f32_e32 v19, v8, v8
	v_max_f32_e32 v8, v13, v13
	v_max_f32_e32 v8, 0, v8
	v_mul_f32_e32 v20, v8, v8
	v_mul_f32_e32 v21, v9, v9
	v_max_f32_e32 v8, v14, v14
	v_max_f32_e32 v9, v10, v10
	v_add_u32_e32 v16, 0xb0, v148
	v_max_f32_e32 v8, 0, v8
	v_max_f32_e32 v9, 0, v9
	v_ashrrev_i32_e32 v17, 31, v16
	v_max_f32_e32 v12, v12, v12
	v_mul_f32_e32 v14, v8, v8
	v_mul_f32_e32 v10, v9, v9
	v_max_f32_e32 v8, v15, v15
	v_max_f32_e32 v9, v11, v11
	v_max_f32_e32 v4, v4, v4
	v_max_f32_e32 v0, v0, v0
	v_max_f32_e32 v5, v5, v5
	v_max_f32_e32 v1, v1, v1
	v_max_f32_e32 v6, v6, v6
	v_max_f32_e32 v2, v2, v2
	v_max_f32_e32 v7, v7, v7
	v_max_f32_e32 v3, v3, v3
	v_lshlrev_b64 v[16:17], 14, v[16:17]
	v_max_f32_e32 v12, 0, v12
	v_max_f32_e32 v8, 0, v8
	v_max_f32_e32 v9, 0, v9
	v_max_f32_e32 v4, 0, v4
	v_max_f32_e32 v0, 0, v0
	v_max_f32_e32 v5, 0, v5
	v_max_f32_e32 v1, 0, v1
	v_max_f32_e32 v6, 0, v6
	v_max_f32_e32 v2, 0, v2
	v_max_f32_e32 v7, 0, v7
	v_max_f32_e32 v3, 0, v3
	v_mul_f32_e32 v18, v12, v12
	v_mul_f32_e32 v15, v8, v8
	v_mul_f32_e32 v11, v9, v9
	v_lshl_add_u64 v[8:9], s[28:29], 0, v[16:17]
	v_mul_f32_e32 v4, v4, v4
	v_mul_f32_e32 v0, v0, v0
	v_mul_f32_e32 v5, v5, v5
	v_mul_f32_e32 v1, v1, v1
	v_mul_f32_e32 v6, v6, v6
	v_mul_f32_e32 v2, v2, v2
	v_mul_f32_e32 v7, v7, v7
	v_mul_f32_e32 v3, v3, v3
	v_cvt_pk_bf16_f32 v125, v125, v163
	v_cvt_pk_bf16_f32 v124, v124, v160
	v_cvt_pk_bf16_f32 v123, v161, v162
	v_cvt_pk_bf16_f32 v122, v149, v155
	v_cvt_pk_bf16_f32 v107, v106, v107
	v_cvt_pk_bf16_f32 v106, v115, v117
	v_cvt_pk_bf16_f32 v105, v110, v111
	v_cvt_pk_bf16_f32 v104, v114, v116
	v_cvt_pk_bf16_f32 v91, v90, v91
	v_cvt_pk_bf16_f32 v90, v99, v101
	v_cvt_pk_bf16_f32 v89, v94, v95
	v_cvt_pk_bf16_f32 v88, v98, v100
	v_cvt_pk_bf16_f32 v75, v74, v75
	v_cvt_pk_bf16_f32 v74, v83, v85
	v_cvt_pk_bf16_f32 v73, v78, v79
	v_cvt_pk_bf16_f32 v72, v82, v84
	v_cvt_pk_bf16_f32 v59, v58, v59
	v_cvt_pk_bf16_f32 v58, v67, v69
	v_cvt_pk_bf16_f32 v57, v62, v63
	v_cvt_pk_bf16_f32 v56, v66, v68
	v_cvt_pk_bf16_f32 v43, v42, v43
	v_cvt_pk_bf16_f32 v42, v51, v53
	v_cvt_pk_bf16_f32 v41, v46, v47
	v_cvt_pk_bf16_f32 v40, v50, v52
	v_cvt_pk_bf16_f32 v27, v26, v27
	v_cvt_pk_bf16_f32 v26, v35, v37
	v_cvt_pk_bf16_f32 v25, v30, v31
	v_cvt_pk_bf16_f32 v24, v34, v36
	v_lshl_add_u64 v[12:13], v[8:9], 0, v[120:121]
	v_cvt_pk_bf16_f32 v11, v10, v11
	v_cvt_pk_bf16_f32 v10, v19, v21
	v_cvt_pk_bf16_f32 v9, v14, v15
	v_cvt_pk_bf16_f32 v8, v18, v20
	v_cvt_pk_bf16_f32 v3, v2, v3
	v_cvt_pk_bf16_f32 v2, v0, v1
	v_cvt_pk_bf16_f32 v1, v6, v7
	v_cvt_pk_bf16_f32 v0, v4, v5
	global_store_dwordx4 v[126:127], v[122:125], off
	global_store_dwordx4 v[108:109], v[104:107], off
	global_store_dwordx4 v[92:93], v[88:91], off
	global_store_dwordx4 v[76:77], v[72:75], off
	global_store_dwordx4 v[60:61], v[56:59], off
	global_store_dwordx4 v[44:45], v[40:43], off
	global_store_dwordx4 v[28:29], v[24:27], off
	global_store_dwordx4 v[12:13], v[8:11], off
	global_store_dwordx4 v[12:13], v[0:3], off offset:256

.LBB0_1030:
	ds_read_b128 v[148:151], v159
	ds_read_b128 v[152:155], v159 offset:1024
	ds_read_b128 v[162:165], v159 offset:2048
	ds_read_b128 v[166:169], v159 offset:3072
	s_add_u32 s20, s48, 0xffe00080
	s_addc_u32 s21, s49, -1
	s_cmpk_eq_i32 s63, 0x7c
	s_cselect_b32 s21, s17, s21
	s_cselect_b32 s20, s59, s20
	s_cselect_b32 s51, s15, s62
	s_cselect_b32 s50, s60, s61
	v_lshl_add_u64 v[190:191], s[48:49], 0, v[136:137]
	s_add_i32 m0, s37, 0xc000
	ds_read_b128 v[170:173], v160
	ds_read_b128 v[174:177], v160 offset:1024
	ds_read_b128 v[178:181], v160 offset:2048
	ds_read_b128 v[182:185], v160 offset:3072
	ds_read_b128 v[186:189], v160 offset:4096
	ds_read_b128 v[196:199], v160 offset:5120
	ds_read_b128 v[200:203], v160 offset:6144
	ds_read_b128 v[204:207], v160 offset:7168
	global_load_lds_dwordx4 v[190:191], off
	s_add_i32 m0, s37, 0xe000
	v_lshl_add_u64 v[190:191], s[48:49], 0, v[138:139]
	global_load_lds_dwordx4 v[190:191], off
	s_waitcnt lgkmcnt(8)
	s_barrier
	s_waitcnt lgkmcnt(0)
	s_setprio 1
	v_mfma_f32_16x16x32_bf16 v[124:127], v[148:151], v[170:173], v[124:127]
	v_mfma_f32_16x16x32_bf16 v[120:123], v[162:165], v[170:173], v[120:123]
	v_mfma_f32_16x16x32_bf16 v[108:111], v[148:151], v[178:181], v[108:111]
	v_mfma_f32_16x16x32_bf16 v[104:107], v[162:165], v[178:181], v[104:107]
	v_mfma_f32_16x16x32_bf16 v[92:95], v[148:151], v[186:189], v[92:95]
	v_mfma_f32_16x16x32_bf16 v[88:91], v[162:165], v[186:189], v[88:91]
	v_mfma_f32_16x16x32_bf16 v[76:79], v[148:151], v[200:203], v[76:79]
	v_mfma_f32_16x16x32_bf16 v[72:75], v[162:165], v[200:203], v[72:75]
	v_mfma_f32_16x16x32_bf16 v[124:127], v[152:155], v[174:177], v[124:127]
	v_mfma_f32_16x16x32_bf16 v[120:123], v[166:169], v[174:177], v[120:123]
	v_mfma_f32_16x16x32_bf16 v[108:111], v[152:155], v[182:185], v[108:111]
	v_mfma_f32_16x16x32_bf16 v[104:107], v[166:169], v[182:185], v[104:107]
	v_mfma_f32_16x16x32_bf16 v[92:95], v[152:155], v[196:199], v[92:95]
	v_mfma_f32_16x16x32_bf16 v[88:91], v[166:169], v[196:199], v[88:91]
	v_mfma_f32_16x16x32_bf16 v[76:79], v[152:155], v[204:207], v[76:79]
	v_mfma_f32_16x16x32_bf16 v[72:75], v[166:169], v[204:207], v[72:75]
	s_setprio 0
	s_barrier
	s_add_i32 s64, s55, s23
	v_lshl_add_u64 v[190:191], s[50:51], 0, v[132:133]
	s_mov_b32 m0, s64
	ds_read_b128 v[208:211], v161
	ds_read_b128 v[212:215], v161 offset:1024
	ds_read_b128 v[216:219], v161 offset:2048
	ds_read_b128 v[220:223], v161 offset:3072
	global_load_lds_dwordx4 v[190:191], off
	s_add_i32 m0, s64, 0x2000
	v_lshl_add_u64 v[224:225], s[50:51], 0, v[128:129]
	global_load_lds_dwordx4 v[224:225], off
	s_barrier
	s_waitcnt lgkmcnt(0)
	s_setprio 1
	v_mfma_f32_16x16x32_bf16 v[116:119], v[208:211], v[170:173], v[116:119]
	v_mfma_f32_16x16x32_bf16 v[112:115], v[216:219], v[170:173], v[112:115]
	v_mfma_f32_16x16x32_bf16 v[100:103], v[208:211], v[178:181], v[100:103]
	v_mfma_f32_16x16x32_bf16 v[96:99], v[216:219], v[178:181], v[96:99]
	v_mfma_f32_16x16x32_bf16 v[84:87], v[208:211], v[186:189], v[84:87]
	v_mfma_f32_16x16x32_bf16 v[80:83], v[216:219], v[186:189], v[80:83]
	v_mfma_f32_16x16x32_bf16 v[68:71], v[208:211], v[200:203], v[68:71]
	v_mfma_f32_16x16x32_bf16 v[64:67], v[216:219], v[200:203], v[64:67]
	v_mfma_f32_16x16x32_bf16 v[116:119], v[212:215], v[174:177], v[116:119]
	v_mfma_f32_16x16x32_bf16 v[112:115], v[220:223], v[174:177], v[112:115]
	v_mfma_f32_16x16x32_bf16 v[100:103], v[212:215], v[182:185], v[100:103]
	v_mfma_f32_16x16x32_bf16 v[96:99], v[220:223], v[182:185], v[96:99]
	v_mfma_f32_16x16x32_bf16 v[84:87], v[212:215], v[196:199], v[84:87]
	v_mfma_f32_16x16x32_bf16 v[80:83], v[220:223], v[196:199], v[80:83]
	v_mfma_f32_16x16x32_bf16 v[68:71], v[212:215], v[204:207], v[68:71]
	v_mfma_f32_16x16x32_bf16 v[64:67], v[220:223], v[204:207], v[64:67]
	s_setprio 0
	s_mov_b32 m0, s37
	v_lshl_add_u64 v[226:227], s[20:21], 0, v[134:135]
	s_barrier
	ds_read_b128 v[170:173], v160 offset:16384
	ds_read_b128 v[174:177], v160 offset:17408
	ds_read_b128 v[178:181], v160 offset:18432
	ds_read_b128 v[182:185], v160 offset:19456
	ds_read_b128 v[186:189], v160 offset:20480
	ds_read_b128 v[196:199], v160 offset:21504
	ds_read_b128 v[200:203], v160 offset:22528
	ds_read_b128 v[204:207], v160 offset:23552
	global_load_lds_dwordx4 v[226:227], off
	s_mov_b32 m0, s38
	v_lshl_add_u64 v[228:229], s[20:21], 0, v[130:131]
	global_load_lds_dwordx4 v[228:229], off
	s_barrier
	s_waitcnt lgkmcnt(0)
	s_setprio 1
	v_mfma_f32_16x16x32_bf16 v[60:63], v[148:151], v[170:173], v[60:63]
	v_mfma_f32_16x16x32_bf16 v[56:59], v[162:165], v[170:173], v[56:59]
	v_mfma_f32_16x16x32_bf16 v[44:47], v[148:151], v[178:181], v[44:47]
	v_mfma_f32_16x16x32_bf16 v[40:43], v[162:165], v[178:181], v[40:43]
	v_mfma_f32_16x16x32_bf16 v[28:31], v[148:151], v[186:189], v[28:31]
	v_mfma_f32_16x16x32_bf16 v[24:27], v[162:165], v[186:189], v[24:27]
	v_mfma_f32_16x16x32_bf16 v[12:15], v[148:151], v[200:203], v[12:15]
	v_mfma_f32_16x16x32_bf16 v[8:11], v[162:165], v[200:203], v[8:11]
	v_mfma_f32_16x16x32_bf16 v[60:63], v[152:155], v[174:177], v[60:63]
	v_mfma_f32_16x16x32_bf16 v[56:59], v[166:169], v[174:177], v[56:59]
	v_mfma_f32_16x16x32_bf16 v[44:47], v[152:155], v[182:185], v[44:47]
	v_mfma_f32_16x16x32_bf16 v[40:43], v[166:169], v[182:185], v[40:43]
	v_mfma_f32_16x16x32_bf16 v[28:31], v[152:155], v[196:199], v[28:31]
	v_mfma_f32_16x16x32_bf16 v[24:27], v[166:169], v[196:199], v[24:27]
	v_mfma_f32_16x16x32_bf16 v[12:15], v[152:155], v[204:207], v[12:15]
	v_mfma_f32_16x16x32_bf16 v[8:11], v[166:169], v[204:207], v[8:11]
	s_setprio 0
	s_barrier
	s_add_u32 s64, s50, 0x200000
	s_addc_u32 s65, s51, 0
	s_add_i32 s66, s57, s23
	s_mov_b32 m0, s66
	v_lshl_add_u64 v[148:149], s[64:65], 0, v[132:133]
	global_load_lds_dwordx4 v[148:149], off
	s_add_i32 m0, s66, 0x2000
	v_lshl_add_u64 v[148:149], s[64:65], 0, v[128:129]
	global_load_lds_dwordx4 v[148:149], off
	s_waitcnt vmcnt(6)
	s_barrier
	s_setprio 1
	v_mfma_f32_16x16x32_bf16 v[52:55], v[208:211], v[170:173], v[52:55]
	v_mfma_f32_16x16x32_bf16 v[48:51], v[216:219], v[170:173], v[48:51]
	v_mfma_f32_16x16x32_bf16 v[36:39], v[208:211], v[178:181], v[36:39]
	v_mfma_f32_16x16x32_bf16 v[32:35], v[216:219], v[178:181], v[32:35]
	v_mfma_f32_16x16x32_bf16 v[20:23], v[208:211], v[186:189], v[20:23]
	v_mfma_f32_16x16x32_bf16 v[16:19], v[216:219], v[186:189], v[16:19]
	v_mfma_f32_16x16x32_bf16 v[4:7], v[208:211], v[200:203], v[4:7]
	v_mfma_f32_16x16x32_bf16 v[0:3], v[216:219], v[200:203], v[0:3]
	v_mfma_f32_16x16x32_bf16 v[52:55], v[212:215], v[174:177], v[52:55]
	v_mfma_f32_16x16x32_bf16 v[48:51], v[220:223], v[174:177], v[48:51]
	v_mfma_f32_16x16x32_bf16 v[36:39], v[212:215], v[182:185], v[36:39]
	v_mfma_f32_16x16x32_bf16 v[32:35], v[220:223], v[182:185], v[32:35]
	v_mfma_f32_16x16x32_bf16 v[20:23], v[212:215], v[196:199], v[20:23]
	v_mfma_f32_16x16x32_bf16 v[16:19], v[220:223], v[196:199], v[16:19]
	v_mfma_f32_16x16x32_bf16 v[4:7], v[212:215], v[204:207], v[4:7]
	v_mfma_f32_16x16x32_bf16 v[0:3], v[220:223], v[204:207], v[0:3]
	s_setprio 0
	s_add_i32 s64, 0, 0x18000
	v_add_u32_e32 v166, s64, v156
	s_barrier
	ds_read_b128 v[148:151], v166
	ds_read_b128 v[152:155], v166 offset:1024
	ds_read_b128 v[162:165], v166 offset:2048
	ds_read_b128 v[166:169], v166 offset:3072
	s_add_u32 s20, s20, 0x200000
	s_addc_u32 s21, s21, 0
	s_mov_b32 m0, s39
	v_lshl_add_u64 v[208:209], s[20:21], 0, v[134:135]
	ds_read_b128 v[170:173], v160 offset:32768
	ds_read_b128 v[174:177], v160 offset:33792
	ds_read_b128 v[178:181], v160 offset:34816
	ds_read_b128 v[182:185], v160 offset:35840
	ds_read_b128 v[186:189], v160 offset:36864
	ds_read_b128 v[196:199], v160 offset:37888
	ds_read_b128 v[200:203], v160 offset:38912
	ds_read_b128 v[204:207], v160 offset:39936
	global_load_lds_dwordx4 v[208:209], off
	s_mov_b32 m0, s47
	v_lshl_add_u64 v[208:209], s[20:21], 0, v[130:131]
	global_load_lds_dwordx4 v[208:209], off
	s_waitcnt lgkmcnt(8)
	s_barrier
	s_waitcnt lgkmcnt(0)
	s_setprio 1
	v_mfma_f32_16x16x32_bf16 v[124:127], v[148:151], v[170:173], v[124:127]
	v_mfma_f32_16x16x32_bf16 v[120:123], v[162:165], v[170:173], v[120:123]
	v_mfma_f32_16x16x32_bf16 v[108:111], v[148:151], v[178:181], v[108:111]
	v_mfma_f32_16x16x32_bf16 v[104:107], v[162:165], v[178:181], v[104:107]
	v_mfma_f32_16x16x32_bf16 v[92:95], v[148:151], v[186:189], v[92:95]
	v_mfma_f32_16x16x32_bf16 v[88:91], v[162:165], v[186:189], v[88:91]
	v_mfma_f32_16x16x32_bf16 v[76:79], v[148:151], v[200:203], v[76:79]
	v_mfma_f32_16x16x32_bf16 v[72:75], v[162:165], v[200:203], v[72:75]
	v_mfma_f32_16x16x32_bf16 v[124:127], v[152:155], v[174:177], v[124:127]
	v_mfma_f32_16x16x32_bf16 v[120:123], v[166:169], v[174:177], v[120:123]
	v_mfma_f32_16x16x32_bf16 v[108:111], v[152:155], v[182:185], v[108:111]
	v_mfma_f32_16x16x32_bf16 v[104:107], v[166:169], v[182:185], v[104:107]
	v_mfma_f32_16x16x32_bf16 v[92:95], v[152:155], v[196:199], v[92:95]
	v_mfma_f32_16x16x32_bf16 v[88:91], v[166:169], v[196:199], v[88:91]
	v_mfma_f32_16x16x32_bf16 v[76:79], v[152:155], v[204:207], v[76:79]
	v_mfma_f32_16x16x32_bf16 v[72:75], v[166:169], v[204:207], v[72:75]
	s_setprio 0
	s_barrier
	s_add_i32 s65, 0, 0x1c000
	s_add_i32 s20, s64, s23
	v_add_u32_e32 v195, s65, v156
	v_lshl_add_u64 v[190:191], v[190:191], 0, s[10:11]
	s_mov_b32 m0, s20
	ds_read_b128 v[208:211], v195
	ds_read_b128 v[212:215], v195 offset:1024
	ds_read_b128 v[216:219], v195 offset:2048
	ds_read_b128 v[220:223], v195 offset:3072
	global_load_lds_dwordx4 v[190:191], off
	s_add_i32 m0, s20, 0x2000
	v_lshl_add_u64 v[190:191], v[224:225], 0, s[10:11]
	global_load_lds_dwordx4 v[190:191], off
	s_barrier
	s_waitcnt lgkmcnt(0)
	s_setprio 1
	v_mfma_f32_16x16x32_bf16 v[116:119], v[208:211], v[170:173], v[116:119]
	v_mfma_f32_16x16x32_bf16 v[112:115], v[216:219], v[170:173], v[112:115]
	v_mfma_f32_16x16x32_bf16 v[100:103], v[208:211], v[178:181], v[100:103]
	v_mfma_f32_16x16x32_bf16 v[96:99], v[216:219], v[178:181], v[96:99]
	v_mfma_f32_16x16x32_bf16 v[84:87], v[208:211], v[186:189], v[84:87]
	v_mfma_f32_16x16x32_bf16 v[80:83], v[216:219], v[186:189], v[80:83]
	v_mfma_f32_16x16x32_bf16 v[68:71], v[208:211], v[200:203], v[68:71]
	v_mfma_f32_16x16x32_bf16 v[64:67], v[216:219], v[200:203], v[64:67]
	v_mfma_f32_16x16x32_bf16 v[116:119], v[212:215], v[174:177], v[116:119]
	v_mfma_f32_16x16x32_bf16 v[112:115], v[220:223], v[174:177], v[112:115]
	v_mfma_f32_16x16x32_bf16 v[100:103], v[212:215], v[182:185], v[100:103]
	v_mfma_f32_16x16x32_bf16 v[96:99], v[220:223], v[182:185], v[96:99]
	v_mfma_f32_16x16x32_bf16 v[84:87], v[212:215], v[196:199], v[84:87]
	v_mfma_f32_16x16x32_bf16 v[80:83], v[220:223], v[196:199], v[80:83]
	v_mfma_f32_16x16x32_bf16 v[68:71], v[212:215], v[204:207], v[68:71]
	v_mfma_f32_16x16x32_bf16 v[64:67], v[220:223], v[204:207], v[64:67]
	s_setprio 0
	s_mov_b32 m0, s34
	v_lshl_add_u64 v[190:191], v[226:227], 0, s[10:11]
	s_barrier
	ds_read_b128 v[170:173], v160 offset:49152
	ds_read_b128 v[174:177], v160 offset:50176
	ds_read_b128 v[178:181], v160 offset:51200
	ds_read_b128 v[182:185], v160 offset:52224
	ds_read_b128 v[186:189], v160 offset:53248
	ds_read_b128 v[196:199], v160 offset:54272
	ds_read_b128 v[200:203], v160 offset:55296
	ds_read_b128 v[204:207], v160 offset:56320
	global_load_lds_dwordx4 v[190:191], off
	s_mov_b32 m0, s35
	v_lshl_add_u64 v[190:191], v[228:229], 0, s[10:11]
	global_load_lds_dwordx4 v[190:191], off
	s_barrier
	s_waitcnt lgkmcnt(0)
	s_setprio 1
	v_mfma_f32_16x16x32_bf16 v[60:63], v[148:151], v[170:173], v[60:63]
	v_mfma_f32_16x16x32_bf16 v[56:59], v[162:165], v[170:173], v[56:59]
	v_mfma_f32_16x16x32_bf16 v[44:47], v[148:151], v[178:181], v[44:47]
	v_mfma_f32_16x16x32_bf16 v[40:43], v[162:165], v[178:181], v[40:43]
	v_mfma_f32_16x16x32_bf16 v[28:31], v[148:151], v[186:189], v[28:31]
	v_mfma_f32_16x16x32_bf16 v[24:27], v[162:165], v[186:189], v[24:27]
	v_mfma_f32_16x16x32_bf16 v[12:15], v[148:151], v[200:203], v[12:15]
	v_mfma_f32_16x16x32_bf16 v[8:11], v[162:165], v[200:203], v[8:11]
	v_mfma_f32_16x16x32_bf16 v[60:63], v[152:155], v[174:177], v[60:63]
	v_mfma_f32_16x16x32_bf16 v[56:59], v[166:169], v[174:177], v[56:59]
	v_mfma_f32_16x16x32_bf16 v[44:47], v[152:155], v[182:185], v[44:47]
	v_mfma_f32_16x16x32_bf16 v[40:43], v[166:169], v[182:185], v[40:43]
	v_mfma_f32_16x16x32_bf16 v[28:31], v[152:155], v[196:199], v[28:31]
	v_mfma_f32_16x16x32_bf16 v[24:27], v[166:169], v[196:199], v[24:27]
	v_mfma_f32_16x16x32_bf16 v[12:15], v[152:155], v[204:207], v[12:15]
	v_mfma_f32_16x16x32_bf16 v[8:11], v[166:169], v[204:207], v[8:11]
	s_setprio 0
	s_barrier
	s_add_u32 s20, s50, 0x200080
	s_addc_u32 s21, s51, 0
	s_add_i32 s50, s65, s23
	s_mov_b32 m0, s50
	v_lshl_add_u64 v[148:149], s[20:21], 0, v[132:133]
	global_load_lds_dwordx4 v[148:149], off
	s_add_i32 m0, s50, 0x2000
	v_lshl_add_u64 v[148:149], s[20:21], 0, v[128:129]
	global_load_lds_dwordx4 v[148:149], off
	s_waitcnt vmcnt(6)
	s_barrier
	s_setprio 1
	v_mfma_f32_16x16x32_bf16 v[52:55], v[208:211], v[170:173], v[52:55]
	v_mfma_f32_16x16x32_bf16 v[48:51], v[216:219], v[170:173], v[48:51]
	v_mfma_f32_16x16x32_bf16 v[36:39], v[208:211], v[178:181], v[36:39]
	v_mfma_f32_16x16x32_bf16 v[32:35], v[216:219], v[178:181], v[32:35]
	v_mfma_f32_16x16x32_bf16 v[20:23], v[208:211], v[186:189], v[20:23]
	v_mfma_f32_16x16x32_bf16 v[16:19], v[216:219], v[186:189], v[16:19]
	v_mfma_f32_16x16x32_bf16 v[4:7], v[208:211], v[200:203], v[4:7]
	v_mfma_f32_16x16x32_bf16 v[0:3], v[216:219], v[200:203], v[0:3]
	v_mfma_f32_16x16x32_bf16 v[52:55], v[212:215], v[174:177], v[52:55]
	v_mfma_f32_16x16x32_bf16 v[48:51], v[220:223], v[174:177], v[48:51]
	v_mfma_f32_16x16x32_bf16 v[36:39], v[212:215], v[182:185], v[36:39]
	v_mfma_f32_16x16x32_bf16 v[32:35], v[220:223], v[182:185], v[32:35]
	v_mfma_f32_16x16x32_bf16 v[20:23], v[212:215], v[196:199], v[20:23]
	v_mfma_f32_16x16x32_bf16 v[16:19], v[220:223], v[196:199], v[16:19]
	v_mfma_f32_16x16x32_bf16 v[4:7], v[212:215], v[204:207], v[4:7]
	v_mfma_f32_16x16x32_bf16 v[0:3], v[220:223], v[204:207], v[0:3]
	s_setprio 0
	s_add_i32 s63, s63, 2
	s_add_u32 s48, s48, 0x100
	s_addc_u32 s49, s49, 0
	s_add_u32 s61, s61, 0x100
	s_addc_u32 s62, s62, 0
	s_cmpk_gt_u32 s63, 0x7d
	s_cbranch_scc0 .Lepi_nl_mlpout0
	s_cmp_lg_u32 s53, 64
	s_cbranch_scc1 .Lepi_nl_mlpout0
	s_lshl_b32 s15, s46, 8
	s_add_i32 s15, s15, s53
	v_or_b32_e32 v154, s15, v147
	s_add_i32 s17, s15, 0xffffe000
	v_lshl_or_b32 v150, s33, 8, v158
	s_lshr_b32 s17, s17, 12
	v_lshlrev_b32_e32 v148, 12, v154
	s_add_i32 s17, s17, 1
	s_cmp_gt_i32 s15, s58
	s_cselect_b32 s17, s17, 0
	s_mul_i32 s17, s17, s56
	v_lshl_add_u32 v148, v150, 1, v148
	s_add_u32 s20, s8, s17
	s_addc_u32 s21, s9, 0
	v_lshlrev_b32_e32 v149, 2, v150
	s_nop 0
	global_load_dwordx4 v[196:199], v149, s[20:21]
	global_load_dwordx4 v[200:203], v149, s[20:21] offset:16
	global_load_dwordx4 v[204:207], v149, s[20:21] offset:512
	global_load_dwordx4 v[208:211], v149, s[20:21] offset:528
	global_load_dwordx4 v[212:215], v148, s[74:75]
	global_load_dwordx4 v[216:219], v148, s[74:75] offset:256
	v_add_u32_e32 v151, 0x10000, v148
	global_load_dwordx4 v[220:223], v151, s[74:75]
	global_load_dwordx4 v[224:227], v151, s[74:75] offset:256
	v_add_u32_e32 v151, 0x20000, v148
	global_load_dwordx4 v[164:167], v151, s[74:75]
	global_load_dwordx4 v[168:171], v151, s[74:75] offset:256
	v_add_u32_e32 v151, 0x30000, v148
	global_load_dwordx4 v[172:175], v151, s[74:75]
	global_load_dwordx4 v[176:179], v151, s[74:75] offset:256
	s_waitcnt vmcnt(0)
	v_lshlrev_b32_e32 v180, 16, v212
	v_and_b32_e32 v181, 0xffff0000, v212
	v_lshlrev_b32_e32 v182, 16, v213
	v_and_b32_e32 v183, 0xffff0000, v213
	v_lshlrev_b32_e32 v184, 16, v214
	v_and_b32_e32 v185, 0xffff0000, v214
	v_lshlrev_b32_e32 v186, 16, v215
	v_and_b32_e32 v187, 0xffff0000, v215
	v_pk_fma_f32 v[124:125], v[124:125], v[196:197], v[180:181]
	v_pk_fma_f32 v[126:127], v[126:127], v[198:199], v[182:183]
	v_pk_fma_f32 v[120:121], v[120:121], v[200:201], v[184:185]
	v_pk_fma_f32 v[122:123], v[122:123], v[202:203], v[186:187]
	v_cvt_pk_bf16_f32 v123, v122, v123
	v_cvt_pk_bf16_f32 v122, v120, v121
	v_cvt_pk_bf16_f32 v121, v126, v127
	v_cvt_pk_bf16_f32 v120, v124, v125
	global_store_dwordx4 v148, v[120:123], s[74:75]
	v_lshlrev_b32_e32 v180, 16, v216
	v_and_b32_e32 v181, 0xffff0000, v216
	v_lshlrev_b32_e32 v182, 16, v217
	v_and_b32_e32 v183, 0xffff0000, v217
	v_lshlrev_b32_e32 v184, 16, v218
	v_and_b32_e32 v185, 0xffff0000, v218
	v_lshlrev_b32_e32 v186, 16, v219
	v_and_b32_e32 v187, 0xffff0000, v219
	v_pk_fma_f32 v[116:117], v[116:117], v[204:205], v[180:181]
	v_pk_fma_f32 v[118:119], v[118:119], v[206:207], v[182:183]
	v_pk_fma_f32 v[112:113], v[112:113], v[208:209], v[184:185]
	v_pk_fma_f32 v[114:115], v[114:115], v[210:211], v[186:187]
	v_cvt_pk_bf16_f32 v115, v114, v115
	v_cvt_pk_bf16_f32 v114, v112, v113
	v_cvt_pk_bf16_f32 v113, v118, v119
	v_cvt_pk_bf16_f32 v112, v116, v117
	global_store_dwordx4 v148, v[112:115], s[74:75] offset:256
	v_lshlrev_b32_e32 v180, 16, v220
	v_and_b32_e32 v181, 0xffff0000, v220
	v_lshlrev_b32_e32 v182, 16, v221
	v_and_b32_e32 v183, 0xffff0000, v221
	v_lshlrev_b32_e32 v184, 16, v222
	v_and_b32_e32 v185, 0xffff0000, v222
	v_lshlrev_b32_e32 v186, 16, v223
	v_and_b32_e32 v187, 0xffff0000, v223
	v_pk_fma_f32 v[108:109], v[108:109], v[196:197], v[180:181]
	v_pk_fma_f32 v[110:111], v[110:111], v[198:199], v[182:183]
	v_pk_fma_f32 v[104:105], v[104:105], v[200:201], v[184:185]
	v_pk_fma_f32 v[106:107], v[106:107], v[202:203], v[186:187]
	v_cvt_pk_bf16_f32 v107, v106, v107
	v_cvt_pk_bf16_f32 v106, v104, v105
	v_cvt_pk_bf16_f32 v105, v110, v111
	v_cvt_pk_bf16_f32 v104, v108, v109
	v_add_u32_e32 v151, 0x10000, v148
	global_store_dwordx4 v151, v[104:107], s[74:75]
	v_lshlrev_b32_e32 v180, 16, v224
	v_and_b32_e32 v181, 0xffff0000, v224
	v_lshlrev_b32_e32 v182, 16, v225
	v_and_b32_e32 v183, 0xffff0000, v225
	v_lshlrev_b32_e32 v184, 16, v226
	v_and_b32_e32 v185, 0xffff0000, v226
	v_lshlrev_b32_e32 v186, 16, v227
	v_and_b32_e32 v187, 0xffff0000, v227
	v_pk_fma_f32 v[100:101], v[100:101], v[204:205], v[180:181]
	v_pk_fma_f32 v[102:103], v[102:103], v[206:207], v[182:183]
	v_pk_fma_f32 v[96:97], v[96:97], v[208:209], v[184:185]
	v_pk_fma_f32 v[98:99], v[98:99], v[210:211], v[186:187]
	v_cvt_pk_bf16_f32 v99, v98, v99
	v_cvt_pk_bf16_f32 v98, v96, v97
	v_cvt_pk_bf16_f32 v97, v102, v103
	v_cvt_pk_bf16_f32 v96, v100, v101
	v_add_u32_e32 v151, 0x10000, v148
	global_store_dwordx4 v151, v[96:99], s[74:75] offset:256
	v_add_u32_e32 v151, 0x80000, v148
	global_load_dwordx4 v[212:215], v151, s[74:75]
	global_load_dwordx4 v[216:219], v151, s[74:75] offset:256
	v_add_u32_e32 v151, 0x90000, v148
	global_load_dwordx4 v[220:223], v151, s[74:75]
	global_load_dwordx4 v[224:227], v151, s[74:75] offset:256
	v_lshlrev_b32_e32 v180, 16, v164
	v_and_b32_e32 v181, 0xffff0000, v164
	v_lshlrev_b32_e32 v182, 16, v165
	v_and_b32_e32 v183, 0xffff0000, v165
	v_lshlrev_b32_e32 v184, 16, v166
	v_and_b32_e32 v185, 0xffff0000, v166
	v_lshlrev_b32_e32 v186, 16, v167
	v_and_b32_e32 v187, 0xffff0000, v167
	v_pk_fma_f32 v[92:93], v[92:93], v[196:197], v[180:181]
	v_pk_fma_f32 v[94:95], v[94:95], v[198:199], v[182:183]
	v_pk_fma_f32 v[88:89], v[88:89], v[200:201], v[184:185]
	v_pk_fma_f32 v[90:91], v[90:91], v[202:203], v[186:187]
	v_cvt_pk_bf16_f32 v91, v90, v91
	v_cvt_pk_bf16_f32 v90, v88, v89
	v_cvt_pk_bf16_f32 v89, v94, v95
	v_cvt_pk_bf16_f32 v88, v92, v93
	v_add_u32_e32 v151, 0x20000, v148
	global_store_dwordx4 v151, v[88:91], s[74:75]
	v_lshlrev_b32_e32 v180, 16, v168
	v_and_b32_e32 v181, 0xffff0000, v168
	v_lshlrev_b32_e32 v182, 16, v169
	v_and_b32_e32 v183, 0xffff0000, v169
	v_lshlrev_b32_e32 v184, 16, v170
	v_and_b32_e32 v185, 0xffff0000, v170
	v_lshlrev_b32_e32 v186, 16, v171
	v_and_b32_e32 v187, 0xffff0000, v171
	v_pk_fma_f32 v[84:85], v[84:85], v[204:205], v[180:181]
	v_pk_fma_f32 v[86:87], v[86:87], v[206:207], v[182:183]
	v_pk_fma_f32 v[80:81], v[80:81], v[208:209], v[184:185]
	v_pk_fma_f32 v[82:83], v[82:83], v[210:211], v[186:187]
	v_cvt_pk_bf16_f32 v83, v82, v83
	v_cvt_pk_bf16_f32 v82, v80, v81
	v_cvt_pk_bf16_f32 v81, v86, v87
	v_cvt_pk_bf16_f32 v80, v84, v85
	v_add_u32_e32 v151, 0x20000, v148
	global_store_dwordx4 v151, v[80:83], s[74:75] offset:256
	v_lshlrev_b32_e32 v180, 16, v172
	v_and_b32_e32 v181, 0xffff0000, v172
	v_lshlrev_b32_e32 v182, 16, v173
	v_and_b32_e32 v183, 0xffff0000, v173
	v_lshlrev_b32_e32 v184, 16, v174
	v_and_b32_e32 v185, 0xffff0000, v174
	v_lshlrev_b32_e32 v186, 16, v175
	v_and_b32_e32 v187, 0xffff0000, v175
	v_pk_fma_f32 v[76:77], v[76:77], v[196:197], v[180:181]
	v_pk_fma_f32 v[78:79], v[78:79], v[198:199], v[182:183]
	v_pk_fma_f32 v[72:73], v[72:73], v[200:201], v[184:185]
	v_pk_fma_f32 v[74:75], v[74:75], v[202:203], v[186:187]
	v_cvt_pk_bf16_f32 v75, v74, v75
	v_cvt_pk_bf16_f32 v74, v72, v73
	v_cvt_pk_bf16_f32 v73, v78, v79
	v_cvt_pk_bf16_f32 v72, v76, v77
	v_add_u32_e32 v151, 0x30000, v148
	global_store_dwordx4 v151, v[72:75], s[74:75]
	v_lshlrev_b32_e32 v180, 16, v176
	v_and_b32_e32 v181, 0xffff0000, v176
	v_lshlrev_b32_e32 v182, 16, v177
	v_and_b32_e32 v183, 0xffff0000, v177
	v_lshlrev_b32_e32 v184, 16, v178
	v_and_b32_e32 v185, 0xffff0000, v178
	v_lshlrev_b32_e32 v186, 16, v179
	v_and_b32_e32 v187, 0xffff0000, v179
	v_pk_fma_f32 v[68:69], v[68:69], v[204:205], v[180:181]
	v_pk_fma_f32 v[70:71], v[70:71], v[206:207], v[182:183]
	v_pk_fma_f32 v[64:65], v[64:65], v[208:209], v[184:185]
	v_pk_fma_f32 v[66:67], v[66:67], v[210:211], v[186:187]
	v_cvt_pk_bf16_f32 v67, v66, v67
	v_cvt_pk_bf16_f32 v66, v64, v65
	v_cvt_pk_bf16_f32 v65, v70, v71
	v_cvt_pk_bf16_f32 v64, v68, v69
	v_add_u32_e32 v151, 0x30000, v148
	global_store_dwordx4 v151, v[64:67], s[74:75] offset:256
	v_add_u32_e32 v151, 0xa0000, v148
	global_load_dwordx4 v[164:167], v151, s[74:75]
	global_load_dwordx4 v[168:171], v151, s[74:75] offset:256
	v_add_u32_e32 v151, 0xb0000, v148
	global_load_dwordx4 v[172:175], v151, s[74:75]
	global_load_dwordx4 v[176:179], v151, s[74:75] offset:256
	s_waitcnt vmcnt(0)
	v_lshlrev_b32_e32 v180, 16, v212
	v_and_b32_e32 v181, 0xffff0000, v212
	v_lshlrev_b32_e32 v182, 16, v213
	v_and_b32_e32 v183, 0xffff0000, v213
	v_lshlrev_b32_e32 v184, 16, v214
	v_and_b32_e32 v185, 0xffff0000, v214
	v_lshlrev_b32_e32 v186, 16, v215
	v_and_b32_e32 v187, 0xffff0000, v215
	v_pk_fma_f32 v[60:61], v[60:61], v[196:197], v[180:181]
	v_pk_fma_f32 v[62:63], v[62:63], v[198:199], v[182:183]
	v_pk_fma_f32 v[56:57], v[56:57], v[200:201], v[184:185]
	v_pk_fma_f32 v[58:59], v[58:59], v[202:203], v[186:187]
	v_cvt_pk_bf16_f32 v59, v58, v59
	v_cvt_pk_bf16_f32 v58, v56, v57
	v_cvt_pk_bf16_f32 v57, v62, v63
	v_cvt_pk_bf16_f32 v56, v60, v61
	v_add_u32_e32 v151, 0x80000, v148
	global_store_dwordx4 v151, v[56:59], s[74:75]
	v_lshlrev_b32_e32 v180, 16, v216
	v_and_b32_e32 v181, 0xffff0000, v216
	v_lshlrev_b32_e32 v182, 16, v217
	v_and_b32_e32 v183, 0xffff0000, v217
	v_lshlrev_b32_e32 v184, 16, v218
	v_and_b32_e32 v185, 0xffff0000, v218
	v_lshlrev_b32_e32 v186, 16, v219
	v_and_b32_e32 v187, 0xffff0000, v219
	v_pk_fma_f32 v[52:53], v[52:53], v[204:205], v[180:181]
	v_pk_fma_f32 v[54:55], v[54:55], v[206:207], v[182:183]
	v_pk_fma_f32 v[48:49], v[48:49], v[208:209], v[184:185]
	v_pk_fma_f32 v[50:51], v[50:51], v[210:211], v[186:187]
	v_cvt_pk_bf16_f32 v51, v50, v51
	v_cvt_pk_bf16_f32 v50, v48, v49
	v_cvt_pk_bf16_f32 v49, v54, v55
	v_cvt_pk_bf16_f32 v48, v52, v53
	v_add_u32_e32 v151, 0x80000, v148
	global_store_dwordx4 v151, v[48:51], s[74:75] offset:256
	v_lshlrev_b32_e32 v180, 16, v220
	v_and_b32_e32 v181, 0xffff0000, v220
	v_lshlrev_b32_e32 v182, 16, v221
	v_and_b32_e32 v183, 0xffff0000, v221
	v_lshlrev_b32_e32 v184, 16, v222
	v_and_b32_e32 v185, 0xffff0000, v222
	v_lshlrev_b32_e32 v186, 16, v223
	v_and_b32_e32 v187, 0xffff0000, v223
	v_pk_fma_f32 v[44:45], v[44:45], v[196:197], v[180:181]
	v_pk_fma_f32 v[46:47], v[46:47], v[198:199], v[182:183]
	v_pk_fma_f32 v[40:41], v[40:41], v[200:201], v[184:185]
	v_pk_fma_f32 v[42:43], v[42:43], v[202:203], v[186:187]
	v_cvt_pk_bf16_f32 v43, v42, v43
	v_cvt_pk_bf16_f32 v42, v40, v41
	v_cvt_pk_bf16_f32 v41, v46, v47
	v_cvt_pk_bf16_f32 v40, v44, v45
	v_add_u32_e32 v151, 0x90000, v148
	global_store_dwordx4 v151, v[40:43], s[74:75]
	v_lshlrev_b32_e32 v180, 16, v224
	v_and_b32_e32 v181, 0xffff0000, v224
	v_lshlrev_b32_e32 v182, 16, v225
	v_and_b32_e32 v183, 0xffff0000, v225
	v_lshlrev_b32_e32 v184, 16, v226
	v_and_b32_e32 v185, 0xffff0000, v226
	v_lshlrev_b32_e32 v186, 16, v227
	v_and_b32_e32 v187, 0xffff0000, v227
	v_pk_fma_f32 v[36:37], v[36:37], v[204:205], v[180:181]
	v_pk_fma_f32 v[38:39], v[38:39], v[206:207], v[182:183]
	v_pk_fma_f32 v[32:33], v[32:33], v[208:209], v[184:185]
	v_pk_fma_f32 v[34:35], v[34:35], v[210:211], v[186:187]
	v_cvt_pk_bf16_f32 v35, v34, v35
	v_cvt_pk_bf16_f32 v34, v32, v33
	v_cvt_pk_bf16_f32 v33, v38, v39
	v_cvt_pk_bf16_f32 v32, v36, v37
	v_add_u32_e32 v151, 0x90000, v148
	global_store_dwordx4 v151, v[32:35], s[74:75] offset:256
	v_lshlrev_b32_e32 v180, 16, v164
	v_and_b32_e32 v181, 0xffff0000, v164
	v_lshlrev_b32_e32 v182, 16, v165
	v_and_b32_e32 v183, 0xffff0000, v165
	v_lshlrev_b32_e32 v184, 16, v166
	v_and_b32_e32 v185, 0xffff0000, v166
	v_lshlrev_b32_e32 v186, 16, v167
	v_and_b32_e32 v187, 0xffff0000, v167
	v_pk_fma_f32 v[28:29], v[28:29], v[196:197], v[180:181]
	v_pk_fma_f32 v[30:31], v[30:31], v[198:199], v[182:183]
	v_pk_fma_f32 v[24:25], v[24:25], v[200:201], v[184:185]
	v_pk_fma_f32 v[26:27], v[26:27], v[202:203], v[186:187]
	v_cvt_pk_bf16_f32 v27, v26, v27
	v_cvt_pk_bf16_f32 v26, v24, v25
	v_cvt_pk_bf16_f32 v25, v30, v31
	v_cvt_pk_bf16_f32 v24, v28, v29
	v_add_u32_e32 v151, 0xa0000, v148
	global_store_dwordx4 v151, v[24:27], s[74:75]
	v_lshlrev_b32_e32 v180, 16, v168
	v_and_b32_e32 v181, 0xffff0000, v168
	v_lshlrev_b32_e32 v182, 16, v169
	v_and_b32_e32 v183, 0xffff0000, v169
	v_lshlrev_b32_e32 v184, 16, v170
	v_and_b32_e32 v185, 0xffff0000, v170
	v_lshlrev_b32_e32 v186, 16, v171
	v_and_b32_e32 v187, 0xffff0000, v171
	v_pk_fma_f32 v[20:21], v[20:21], v[204:205], v[180:181]
	v_pk_fma_f32 v[22:23], v[22:23], v[206:207], v[182:183]
	v_pk_fma_f32 v[16:17], v[16:17], v[208:209], v[184:185]
	v_pk_fma_f32 v[18:19], v[18:19], v[210:211], v[186:187]
	v_cvt_pk_bf16_f32 v19, v18, v19
	v_cvt_pk_bf16_f32 v18, v16, v17
	v_cvt_pk_bf16_f32 v17, v22, v23
	v_cvt_pk_bf16_f32 v16, v20, v21
	v_add_u32_e32 v151, 0xa0000, v148
	global_store_dwordx4 v151, v[16:19], s[74:75] offset:256
	v_lshlrev_b32_e32 v180, 16, v172
	v_and_b32_e32 v181, 0xffff0000, v172
	v_lshlrev_b32_e32 v182, 16, v173
	v_and_b32_e32 v183, 0xffff0000, v173
	v_lshlrev_b32_e32 v184, 16, v174
	v_and_b32_e32 v185, 0xffff0000, v174
	v_lshlrev_b32_e32 v186, 16, v175
	v_and_b32_e32 v187, 0xffff0000, v175
	v_pk_fma_f32 v[12:13], v[12:13], v[196:197], v[180:181]
	v_pk_fma_f32 v[14:15], v[14:15], v[198:199], v[182:183]
	v_pk_fma_f32 v[8:9], v[8:9], v[200:201], v[184:185]
	v_pk_fma_f32 v[10:11], v[10:11], v[202:203], v[186:187]
	v_cvt_pk_bf16_f32 v11, v10, v11
	v_cvt_pk_bf16_f32 v10, v8, v9
	v_cvt_pk_bf16_f32 v9, v14, v15
	v_cvt_pk_bf16_f32 v8, v12, v13
	v_add_u32_e32 v151, 0xb0000, v148
	global_store_dwordx4 v151, v[8:11], s[74:75]
	v_lshlrev_b32_e32 v180, 16, v176
	v_and_b32_e32 v181, 0xffff0000, v176
	v_lshlrev_b32_e32 v182, 16, v177
	v_and_b32_e32 v183, 0xffff0000, v177
	v_lshlrev_b32_e32 v184, 16, v178
	v_and_b32_e32 v185, 0xffff0000, v178
	v_lshlrev_b32_e32 v186, 16, v179
	v_and_b32_e32 v187, 0xffff0000, v179
	v_pk_fma_f32 v[4:5], v[4:5], v[204:205], v[180:181]
	v_pk_fma_f32 v[6:7], v[6:7], v[206:207], v[182:183]
	v_pk_fma_f32 v[0:1], v[0:1], v[208:209], v[184:185]
	v_pk_fma_f32 v[2:3], v[2:3], v[210:211], v[186:187]
	v_cvt_pk_bf16_f32 v3, v2, v3
	v_cvt_pk_bf16_f32 v2, v0, v1
	v_cvt_pk_bf16_f32 v1, v6, v7
	v_cvt_pk_bf16_f32 v0, v4, v5
	v_add_u32_e32 v151, 0xb0000, v148
	global_store_dwordx4 v151, v[0:3], s[74:75] offset:256

.LBB0_1090:
	ds_read_b128 v[148:151], v163
	ds_read_b128 v[166:169], v163 offset:1024
	ds_read_b128 v[170:173], v163 offset:2048
	ds_read_b128 v[174:177], v163 offset:3072
	s_add_u32 s18, s16, 0xfff80080
	s_addc_u32 s19, s17, -1
	s_cmp_eq_u32 s35, 28
	s_cselect_b32 s21, s1, s19
	s_cselect_b32 s20, s15, s18
	s_cselect_b32 s19, s22, s34
	s_cselect_b32 s18, s23, s33
	v_lshl_add_u64 v[142:143], s[16:17], 0, v[134:135]
	s_add_i32 m0, s38, 0xc000
	ds_read_b128 v[178:181], v164
	ds_read_b128 v[182:185], v164 offset:1024
	ds_read_b128 v[186:189], v164 offset:2048
	ds_read_b128 v[196:199], v164 offset:3072
	ds_read_b128 v[200:203], v164 offset:4096
	ds_read_b128 v[204:207], v164 offset:5120
	ds_read_b128 v[208:211], v164 offset:6144
	ds_read_b128 v[212:215], v164 offset:7168
	global_load_lds_dwordx4 v[142:143], off
	s_add_i32 m0, s38, 0xe000
	v_lshl_add_u64 v[142:143], s[16:17], 0, v[136:137]
	global_load_lds_dwordx4 v[142:143], off
	s_waitcnt lgkmcnt(8)
	s_barrier
	s_waitcnt lgkmcnt(0)
	s_setprio 1
	v_mfma_f32_16x16x32_bf16 v[124:127], v[148:151], v[178:181], v[124:127]
	v_mfma_f32_16x16x32_bf16 v[120:123], v[170:173], v[178:181], v[120:123]
	v_mfma_f32_16x16x32_bf16 v[108:111], v[148:151], v[186:189], v[108:111]
	v_mfma_f32_16x16x32_bf16 v[104:107], v[170:173], v[186:189], v[104:107]
	v_mfma_f32_16x16x32_bf16 v[92:95], v[148:151], v[200:203], v[92:95]
	v_mfma_f32_16x16x32_bf16 v[88:91], v[170:173], v[200:203], v[88:91]
	v_mfma_f32_16x16x32_bf16 v[76:79], v[148:151], v[208:211], v[76:79]
	v_mfma_f32_16x16x32_bf16 v[72:75], v[170:173], v[208:211], v[72:75]
	v_mfma_f32_16x16x32_bf16 v[124:127], v[166:169], v[182:185], v[124:127]
	v_mfma_f32_16x16x32_bf16 v[120:123], v[174:177], v[182:185], v[120:123]
	v_mfma_f32_16x16x32_bf16 v[108:111], v[166:169], v[196:199], v[108:111]
	v_mfma_f32_16x16x32_bf16 v[104:107], v[174:177], v[196:199], v[104:107]
	v_mfma_f32_16x16x32_bf16 v[92:95], v[166:169], v[204:207], v[92:95]
	v_mfma_f32_16x16x32_bf16 v[88:91], v[174:177], v[204:207], v[88:91]
	v_mfma_f32_16x16x32_bf16 v[76:79], v[166:169], v[212:215], v[76:79]
	v_mfma_f32_16x16x32_bf16 v[72:75], v[174:177], v[212:215], v[72:75]
	s_setprio 0
	s_barrier
	s_add_i32 s49, s65, s37
	v_lshl_add_u64 v[142:143], s[18:19], 0, v[128:129]
	s_mov_b32 m0, s49
	ds_read_b128 v[216:219], v165
	ds_read_b128 v[220:223], v165 offset:1024
	ds_read_b128 v[224:227], v165 offset:2048
	ds_read_b128 v[228:231], v165 offset:3072
	global_load_lds_dwordx4 v[142:143], off
	s_add_i32 m0, s49, 0x2000
	v_lshl_add_u64 v[152:153], s[18:19], 0, v[130:131]
	global_load_lds_dwordx4 v[152:153], off
	s_barrier
	s_waitcnt lgkmcnt(0)
	s_setprio 1
	v_mfma_f32_16x16x32_bf16 v[116:119], v[216:219], v[178:181], v[116:119]
	v_mfma_f32_16x16x32_bf16 v[112:115], v[224:227], v[178:181], v[112:115]
	v_mfma_f32_16x16x32_bf16 v[100:103], v[216:219], v[186:189], v[100:103]
	v_mfma_f32_16x16x32_bf16 v[96:99], v[224:227], v[186:189], v[96:99]
	v_mfma_f32_16x16x32_bf16 v[84:87], v[216:219], v[200:203], v[84:87]
	v_mfma_f32_16x16x32_bf16 v[80:83], v[224:227], v[200:203], v[80:83]
	v_mfma_f32_16x16x32_bf16 v[68:71], v[216:219], v[208:211], v[68:71]
	v_mfma_f32_16x16x32_bf16 v[64:67], v[224:227], v[208:211], v[64:67]
	v_mfma_f32_16x16x32_bf16 v[116:119], v[220:223], v[182:185], v[116:119]
	v_mfma_f32_16x16x32_bf16 v[112:115], v[228:231], v[182:185], v[112:115]
	v_mfma_f32_16x16x32_bf16 v[100:103], v[220:223], v[196:199], v[100:103]
	v_mfma_f32_16x16x32_bf16 v[96:99], v[228:231], v[196:199], v[96:99]
	v_mfma_f32_16x16x32_bf16 v[84:87], v[220:223], v[204:207], v[84:87]
	v_mfma_f32_16x16x32_bf16 v[80:83], v[228:231], v[204:207], v[80:83]
	v_mfma_f32_16x16x32_bf16 v[68:71], v[220:223], v[212:215], v[68:71]
	v_mfma_f32_16x16x32_bf16 v[64:67], v[228:231], v[212:215], v[64:67]
	s_setprio 0
	s_mov_b32 m0, s38
	v_lshl_add_u64 v[190:191], s[20:21], 0, v[128:129]
	s_barrier
	ds_read_b128 v[178:181], v164 offset:16384
	ds_read_b128 v[182:185], v164 offset:17408
	ds_read_b128 v[186:189], v164 offset:18432
	ds_read_b128 v[196:199], v164 offset:19456
	ds_read_b128 v[200:203], v164 offset:20480
	ds_read_b128 v[204:207], v164 offset:21504
	ds_read_b128 v[208:211], v164 offset:22528
	ds_read_b128 v[212:215], v164 offset:23552
	global_load_lds_dwordx4 v[190:191], off
	s_mov_b32 m0, s39
	v_lshl_add_u64 v[232:233], s[20:21], 0, v[130:131]
	global_load_lds_dwordx4 v[232:233], off
	s_barrier
	s_waitcnt lgkmcnt(0)
	s_setprio 1
	v_mfma_f32_16x16x32_bf16 v[60:63], v[148:151], v[178:181], v[60:63]
	v_mfma_f32_16x16x32_bf16 v[56:59], v[170:173], v[178:181], v[56:59]
	v_mfma_f32_16x16x32_bf16 v[44:47], v[148:151], v[186:189], v[44:47]
	v_mfma_f32_16x16x32_bf16 v[40:43], v[170:173], v[186:189], v[40:43]
	v_mfma_f32_16x16x32_bf16 v[28:31], v[148:151], v[200:203], v[28:31]
	v_mfma_f32_16x16x32_bf16 v[24:27], v[170:173], v[200:203], v[24:27]
	v_mfma_f32_16x16x32_bf16 v[12:15], v[148:151], v[208:211], v[12:15]
	v_mfma_f32_16x16x32_bf16 v[8:11], v[170:173], v[208:211], v[8:11]
	v_mfma_f32_16x16x32_bf16 v[60:63], v[166:169], v[182:185], v[60:63]
	v_mfma_f32_16x16x32_bf16 v[56:59], v[174:177], v[182:185], v[56:59]
	v_mfma_f32_16x16x32_bf16 v[44:47], v[166:169], v[196:199], v[44:47]
	v_mfma_f32_16x16x32_bf16 v[40:43], v[174:177], v[196:199], v[40:43]
	v_mfma_f32_16x16x32_bf16 v[28:31], v[166:169], v[204:207], v[28:31]
	v_mfma_f32_16x16x32_bf16 v[24:27], v[174:177], v[204:207], v[24:27]
	v_mfma_f32_16x16x32_bf16 v[12:15], v[166:169], v[212:215], v[12:15]
	v_mfma_f32_16x16x32_bf16 v[8:11], v[174:177], v[212:215], v[8:11]
	s_setprio 0
	s_barrier
	s_add_u32 s80, s18, 0x80000
	s_addc_u32 s81, s19, 0
	s_add_i32 s49, s67, s37
	s_mov_b32 m0, s49
	v_lshl_add_u64 v[148:149], s[80:81], 0, v[128:129]
	global_load_lds_dwordx4 v[148:149], off
	s_add_i32 m0, s49, 0x2000
	v_lshl_add_u64 v[148:149], s[80:81], 0, v[130:131]
	global_load_lds_dwordx4 v[148:149], off
	s_waitcnt vmcnt(6)
	s_barrier
	s_setprio 1
	v_mfma_f32_16x16x32_bf16 v[52:55], v[216:219], v[178:181], v[52:55]
	v_mfma_f32_16x16x32_bf16 v[48:51], v[224:227], v[178:181], v[48:51]
	v_mfma_f32_16x16x32_bf16 v[36:39], v[216:219], v[186:189], v[36:39]
	v_mfma_f32_16x16x32_bf16 v[32:35], v[224:227], v[186:189], v[32:35]
	v_mfma_f32_16x16x32_bf16 v[20:23], v[216:219], v[200:203], v[20:23]
	v_mfma_f32_16x16x32_bf16 v[16:19], v[224:227], v[200:203], v[16:19]
	v_mfma_f32_16x16x32_bf16 v[4:7], v[216:219], v[208:211], v[4:7]
	v_mfma_f32_16x16x32_bf16 v[0:3], v[224:227], v[208:211], v[0:3]
	v_mfma_f32_16x16x32_bf16 v[52:55], v[220:223], v[182:185], v[52:55]
	v_mfma_f32_16x16x32_bf16 v[48:51], v[228:231], v[182:185], v[48:51]
	v_mfma_f32_16x16x32_bf16 v[36:39], v[220:223], v[196:199], v[36:39]
	v_mfma_f32_16x16x32_bf16 v[32:35], v[228:231], v[196:199], v[32:35]
	v_mfma_f32_16x16x32_bf16 v[20:23], v[220:223], v[204:207], v[20:23]
	v_mfma_f32_16x16x32_bf16 v[16:19], v[228:231], v[204:207], v[16:19]
	v_mfma_f32_16x16x32_bf16 v[4:7], v[220:223], v[212:215], v[4:7]
	v_mfma_f32_16x16x32_bf16 v[0:3], v[228:231], v[212:215], v[0:3]
	s_setprio 0
	s_add_i32 s49, 0, 0x18000
	v_add_u32_e32 v132, s49, v154
	s_barrier
	ds_read_b128 v[148:151], v132
	ds_read_b128 v[166:169], v132 offset:1024
	ds_read_b128 v[170:173], v132 offset:2048
	ds_read_b128 v[174:177], v132 offset:3072
	s_add_u32 s20, s20, 0x80000
	s_addc_u32 s21, s21, 0
	s_mov_b32 m0, s56
	v_lshl_add_u64 v[216:217], s[20:21], 0, v[128:129]
	ds_read_b128 v[178:181], v164 offset:32768
	ds_read_b128 v[182:185], v164 offset:33792
	ds_read_b128 v[186:189], v164 offset:34816
	ds_read_b128 v[196:199], v164 offset:35840
	ds_read_b128 v[200:203], v164 offset:36864
	ds_read_b128 v[204:207], v164 offset:37888
	ds_read_b128 v[208:211], v164 offset:38912
	ds_read_b128 v[212:215], v164 offset:39936
	global_load_lds_dwordx4 v[216:217], off
	s_mov_b32 m0, s57
	v_lshl_add_u64 v[216:217], s[20:21], 0, v[130:131]
	global_load_lds_dwordx4 v[216:217], off
	s_waitcnt lgkmcnt(8)
	s_barrier
	s_waitcnt lgkmcnt(0)
	s_setprio 1
	v_mfma_f32_16x16x32_bf16 v[124:127], v[148:151], v[178:181], v[124:127]
	v_mfma_f32_16x16x32_bf16 v[120:123], v[170:173], v[178:181], v[120:123]
	v_mfma_f32_16x16x32_bf16 v[108:111], v[148:151], v[186:189], v[108:111]
	v_mfma_f32_16x16x32_bf16 v[104:107], v[170:173], v[186:189], v[104:107]
	v_mfma_f32_16x16x32_bf16 v[92:95], v[148:151], v[200:203], v[92:95]
	v_mfma_f32_16x16x32_bf16 v[88:91], v[170:173], v[200:203], v[88:91]
	v_mfma_f32_16x16x32_bf16 v[76:79], v[148:151], v[208:211], v[76:79]
	v_mfma_f32_16x16x32_bf16 v[72:75], v[170:173], v[208:211], v[72:75]
	v_mfma_f32_16x16x32_bf16 v[124:127], v[166:169], v[182:185], v[124:127]
	v_mfma_f32_16x16x32_bf16 v[120:123], v[174:177], v[182:185], v[120:123]
	v_mfma_f32_16x16x32_bf16 v[108:111], v[166:169], v[196:199], v[108:111]
	v_mfma_f32_16x16x32_bf16 v[104:107], v[174:177], v[196:199], v[104:107]
	v_mfma_f32_16x16x32_bf16 v[92:95], v[166:169], v[204:207], v[92:95]
	v_mfma_f32_16x16x32_bf16 v[88:91], v[174:177], v[204:207], v[88:91]
	v_mfma_f32_16x16x32_bf16 v[76:79], v[166:169], v[212:215], v[76:79]
	v_mfma_f32_16x16x32_bf16 v[72:75], v[174:177], v[212:215], v[72:75]
	s_setprio 0
	s_barrier
	s_add_i32 s20, 0, 0x1c000
	s_add_i32 s21, s49, s37
	v_add_u32_e32 v132, s20, v154
	v_lshl_add_u64 v[142:143], v[142:143], 0, s[46:47]
	s_mov_b32 m0, s21
	ds_read_b128 v[216:219], v132
	ds_read_b128 v[220:223], v132 offset:1024
	ds_read_b128 v[224:227], v132 offset:2048
	ds_read_b128 v[228:231], v132 offset:3072
	global_load_lds_dwordx4 v[142:143], off
	s_add_i32 m0, s21, 0x2000
	v_lshl_add_u64 v[142:143], v[152:153], 0, s[46:47]
	global_load_lds_dwordx4 v[142:143], off
	s_barrier
	s_waitcnt lgkmcnt(0)
	s_setprio 1
	v_mfma_f32_16x16x32_bf16 v[116:119], v[216:219], v[178:181], v[116:119]
	v_mfma_f32_16x16x32_bf16 v[112:115], v[224:227], v[178:181], v[112:115]
	v_mfma_f32_16x16x32_bf16 v[100:103], v[216:219], v[186:189], v[100:103]
	v_mfma_f32_16x16x32_bf16 v[96:99], v[224:227], v[186:189], v[96:99]
	v_mfma_f32_16x16x32_bf16 v[84:87], v[216:219], v[200:203], v[84:87]
	v_mfma_f32_16x16x32_bf16 v[80:83], v[224:227], v[200:203], v[80:83]
	v_mfma_f32_16x16x32_bf16 v[68:71], v[216:219], v[208:211], v[68:71]
	v_mfma_f32_16x16x32_bf16 v[64:67], v[224:227], v[208:211], v[64:67]
	v_mfma_f32_16x16x32_bf16 v[116:119], v[220:223], v[182:185], v[116:119]
	v_mfma_f32_16x16x32_bf16 v[112:115], v[228:231], v[182:185], v[112:115]
	v_mfma_f32_16x16x32_bf16 v[100:103], v[220:223], v[196:199], v[100:103]
	v_mfma_f32_16x16x32_bf16 v[96:99], v[228:231], v[196:199], v[96:99]
	v_mfma_f32_16x16x32_bf16 v[84:87], v[220:223], v[204:207], v[84:87]
	v_mfma_f32_16x16x32_bf16 v[80:83], v[228:231], v[204:207], v[80:83]
	v_mfma_f32_16x16x32_bf16 v[68:71], v[220:223], v[212:215], v[68:71]
	v_mfma_f32_16x16x32_bf16 v[64:67], v[228:231], v[212:215], v[64:67]
	s_setprio 0
	s_mov_b32 m0, s60
	v_lshl_add_u64 v[142:143], v[190:191], 0, s[46:47]
	s_barrier
	ds_read_b128 v[178:181], v164 offset:49152
	ds_read_b128 v[182:185], v164 offset:50176
	ds_read_b128 v[186:189], v164 offset:51200
	ds_read_b128 v[196:199], v164 offset:52224
	ds_read_b128 v[200:203], v164 offset:53248
	ds_read_b128 v[204:207], v164 offset:54272
	ds_read_b128 v[208:211], v164 offset:55296
	ds_read_b128 v[212:215], v164 offset:56320
	global_load_lds_dwordx4 v[142:143], off
	s_mov_b32 m0, s61
	v_lshl_add_u64 v[142:143], v[232:233], 0, s[46:47]
	global_load_lds_dwordx4 v[142:143], off
	s_barrier
	s_waitcnt lgkmcnt(0)
	s_setprio 1
	v_mfma_f32_16x16x32_bf16 v[60:63], v[148:151], v[178:181], v[60:63]
	v_mfma_f32_16x16x32_bf16 v[56:59], v[170:173], v[178:181], v[56:59]
	v_mfma_f32_16x16x32_bf16 v[44:47], v[148:151], v[186:189], v[44:47]
	v_mfma_f32_16x16x32_bf16 v[40:43], v[170:173], v[186:189], v[40:43]
	v_mfma_f32_16x16x32_bf16 v[28:31], v[148:151], v[200:203], v[28:31]
	v_mfma_f32_16x16x32_bf16 v[24:27], v[170:173], v[200:203], v[24:27]
	v_mfma_f32_16x16x32_bf16 v[12:15], v[148:151], v[208:211], v[12:15]
	v_mfma_f32_16x16x32_bf16 v[8:11], v[170:173], v[208:211], v[8:11]
	v_mfma_f32_16x16x32_bf16 v[60:63], v[166:169], v[182:185], v[60:63]
	v_mfma_f32_16x16x32_bf16 v[56:59], v[174:177], v[182:185], v[56:59]
	v_mfma_f32_16x16x32_bf16 v[44:47], v[166:169], v[196:199], v[44:47]
	v_mfma_f32_16x16x32_bf16 v[40:43], v[174:177], v[196:199], v[40:43]
	v_mfma_f32_16x16x32_bf16 v[28:31], v[166:169], v[204:207], v[28:31]
	v_mfma_f32_16x16x32_bf16 v[24:27], v[174:177], v[204:207], v[24:27]
	v_mfma_f32_16x16x32_bf16 v[12:15], v[166:169], v[212:215], v[12:15]
	v_mfma_f32_16x16x32_bf16 v[8:11], v[174:177], v[212:215], v[8:11]
	s_setprio 0
	s_barrier
	s_add_u32 s18, s18, 0x80080
	s_addc_u32 s19, s19, 0
	s_add_i32 s20, s20, s37
	s_mov_b32 m0, s20
	v_lshl_add_u64 v[142:143], s[18:19], 0, v[128:129]
	global_load_lds_dwordx4 v[142:143], off
	s_add_i32 m0, s20, 0x2000
	v_lshl_add_u64 v[142:143], s[18:19], 0, v[130:131]
	global_load_lds_dwordx4 v[142:143], off
	s_waitcnt vmcnt(6)
	s_barrier
	s_setprio 1
	v_mfma_f32_16x16x32_bf16 v[52:55], v[216:219], v[178:181], v[52:55]
	v_mfma_f32_16x16x32_bf16 v[48:51], v[224:227], v[178:181], v[48:51]
	v_mfma_f32_16x16x32_bf16 v[36:39], v[216:219], v[186:189], v[36:39]
	v_mfma_f32_16x16x32_bf16 v[32:35], v[224:227], v[186:189], v[32:35]
	v_mfma_f32_16x16x32_bf16 v[20:23], v[216:219], v[200:203], v[20:23]
	v_mfma_f32_16x16x32_bf16 v[16:19], v[224:227], v[200:203], v[16:19]
	v_mfma_f32_16x16x32_bf16 v[4:7], v[216:219], v[208:211], v[4:7]
	v_mfma_f32_16x16x32_bf16 v[0:3], v[224:227], v[208:211], v[0:3]
	v_mfma_f32_16x16x32_bf16 v[52:55], v[220:223], v[182:185], v[52:55]
	v_mfma_f32_16x16x32_bf16 v[48:51], v[228:231], v[182:185], v[48:51]
	v_mfma_f32_16x16x32_bf16 v[36:39], v[220:223], v[196:199], v[36:39]
	v_mfma_f32_16x16x32_bf16 v[32:35], v[228:231], v[196:199], v[32:35]
	v_mfma_f32_16x16x32_bf16 v[20:23], v[220:223], v[204:207], v[20:23]
	v_mfma_f32_16x16x32_bf16 v[16:19], v[228:231], v[204:207], v[16:19]
	v_mfma_f32_16x16x32_bf16 v[4:7], v[220:223], v[212:215], v[4:7]
	v_mfma_f32_16x16x32_bf16 v[0:3], v[228:231], v[212:215], v[0:3]
	s_setprio 0
	s_add_i32 s35, s35, 2
	s_add_u32 s16, s16, 0x100
	s_addc_u32 s17, s17, 0
	s_add_u32 s33, s33, 0x100
	s_addc_u32 s34, s34, 0
	s_cmp_gt_u32 s35, 29
	s_barrier
	s_cbranch_scc0 .LBB0_1090
	s_lshl_b32 s34, s14, 8
	s_add_i32 s34, s34, s59
	v_or_b32_e32 v150, s34, v147
	v_lshl_or_b32 v142, s0, 8, v162
	v_ashrrev_i32_e32 v151, 31, v150
	v_cmp_gt_i32_e64 s[18:19], s58, v150
	v_cmp_lt_i32_e64 s[16:17], s68, v150
	v_lshlrev_b64 v[148:149], 8, v[150:151]
	v_cmp_lt_i32_e64 s[14:15], s76, v142
	v_add_u32_e32 v132, 0xfffff700, v142
	v_add_u32_e32 v174, 0xfffff710, v142
	v_add_u32_e32 v172, 0xfffff701, v142
	v_add_u32_e32 v170, 0xfffff711, v142
	v_add_u32_e32 v169, 0xfffff702, v142
	v_add_u32_e32 v168, 0xfffff712, v142
	v_add_u32_e32 v167, 0xfffff703, v142
	v_add_u32_e32 v166, 0xfffff713, v142
	v_lshl_add_u64 v[152:153], v[150:151], 1, s[24:25]
	s_and_saveexec_b64 s[0:1], s[14:15]
	s_xor_b64 s[0:1], exec, s[0:1]
	s_cbranch_execz .LBB0_1095
	v_bfe_u32 v143, v124, 16, 1
	v_add3_u32 v143, v124, v143, s77
	v_mad_u64_u32 v[176:177], s[20:21], v132, s66, v[152:153]
	global_store_short_d16_hi v[176:177], v143, off
	v_bfe_u32 v143, v120, 16, 1
	v_add3_u32 v143, v120, v143, s77
	v_mad_u64_u32 v[176:177], s[20:21], v174, s66, v[152:153]
	global_store_short_d16_hi v[176:177], v143, off
	v_bfe_u32 v143, v125, 16, 1
	v_add3_u32 v143, v125, v143, s77
	v_mad_u64_u32 v[176:177], s[20:21], v172, s66, v[152:153]
	global_store_short_d16_hi v[176:177], v143, off
	v_bfe_u32 v143, v121, 16, 1
	v_add3_u32 v143, v121, v143, s77
	v_mad_u64_u32 v[176:177], s[20:21], v170, s66, v[152:153]
	global_store_short_d16_hi v[176:177], v143, off
	v_bfe_u32 v143, v126, 16, 1
	v_add3_u32 v143, v126, v143, s77
	v_mad_u64_u32 v[176:177], s[20:21], v169, s66, v[152:153]
	global_store_short_d16_hi v[176:177], v143, off
	v_bfe_u32 v143, v122, 16, 1
	v_add3_u32 v143, v122, v143, s77
	v_mad_u64_u32 v[176:177], s[20:21], v168, s66, v[152:153]
	global_store_short_d16_hi v[176:177], v143, off
	v_bfe_u32 v143, v127, 16, 1
	v_add3_u32 v143, v127, v143, s77
	v_mad_u64_u32 v[176:177], s[20:21], v167, s66, v[152:153]
	global_store_short_d16_hi v[176:177], v143, off
	v_bfe_u32 v143, v123, 16, 1
	v_add3_u32 v143, v123, v143, s77
	v_mad_u64_u32 v[176:177], s[20:21], v166, s66, v[152:153]
	global_store_short_d16_hi v[176:177], v143, off
	s_and_saveexec_b64 s[20:21], s[18:19]
	s_cbranch_execz .LBB0_1094
	v_lshl_add_u64 v[176:177], v[148:149], 2, s[44:45]
	v_lshl_add_u64 v[176:177], v[132:133], 2, v[176:177]
	global_store_dwordx4 v[176:177], v[124:127], off
	global_store_dwordx4 v[176:177], v[120:123], off offset:64

.LBB0_1346:
	ds_read_b128 v[148:151], v158
	ds_read_b128 v[152:155], v158 offset:1024
	ds_read_b128 v[162:165], v158 offset:2048
	ds_read_b128 v[166:169], v158 offset:3072
	s_add_u32 s20, s38, 0xfff80080
	s_addc_u32 s21, s39, -1
	s_cmp_eq_u32 s61, 28
	s_cselect_b32 s21, s17, s21
	s_cselect_b32 s20, s57, s20
	s_cselect_b32 s45, s15, s60
	s_cselect_b32 s44, s58, s59
	v_lshl_add_u64 v[190:191], s[38:39], 0, v[136:137]
	s_add_i32 m0, s37, 0xc000
	ds_read_b128 v[170:173], v159
	ds_read_b128 v[174:177], v159 offset:1024
	ds_read_b128 v[178:181], v159 offset:2048
	ds_read_b128 v[182:185], v159 offset:3072
	ds_read_b128 v[186:189], v159 offset:4096
	ds_read_b128 v[196:199], v159 offset:5120
	ds_read_b128 v[200:203], v159 offset:6144
	ds_read_b128 v[204:207], v159 offset:7168
	global_load_lds_dwordx4 v[190:191], off
	s_add_i32 m0, s37, 0xe000
	v_lshl_add_u64 v[190:191], s[38:39], 0, v[138:139]
	global_load_lds_dwordx4 v[190:191], off
	s_waitcnt lgkmcnt(8)
	s_barrier
	s_waitcnt lgkmcnt(0)
	s_setprio 1
	v_mfma_f32_16x16x32_bf16 v[124:127], v[148:151], v[170:173], v[124:127]
	v_mfma_f32_16x16x32_bf16 v[120:123], v[162:165], v[170:173], v[120:123]
	v_mfma_f32_16x16x32_bf16 v[108:111], v[148:151], v[178:181], v[108:111]
	v_mfma_f32_16x16x32_bf16 v[104:107], v[162:165], v[178:181], v[104:107]
	v_mfma_f32_16x16x32_bf16 v[92:95], v[148:151], v[186:189], v[92:95]
	v_mfma_f32_16x16x32_bf16 v[88:91], v[162:165], v[186:189], v[88:91]
	v_mfma_f32_16x16x32_bf16 v[76:79], v[148:151], v[200:203], v[76:79]
	v_mfma_f32_16x16x32_bf16 v[72:75], v[162:165], v[200:203], v[72:75]
	v_mfma_f32_16x16x32_bf16 v[124:127], v[152:155], v[174:177], v[124:127]
	v_mfma_f32_16x16x32_bf16 v[120:123], v[166:169], v[174:177], v[120:123]
	v_mfma_f32_16x16x32_bf16 v[108:111], v[152:155], v[182:185], v[108:111]
	v_mfma_f32_16x16x32_bf16 v[104:107], v[166:169], v[182:185], v[104:107]
	v_mfma_f32_16x16x32_bf16 v[92:95], v[152:155], v[196:199], v[92:95]
	v_mfma_f32_16x16x32_bf16 v[88:91], v[166:169], v[196:199], v[88:91]
	v_mfma_f32_16x16x32_bf16 v[76:79], v[152:155], v[204:207], v[76:79]
	v_mfma_f32_16x16x32_bf16 v[72:75], v[166:169], v[204:207], v[72:75]
	s_setprio 0
	s_barrier
	s_add_i32 s62, s53, s23
	v_lshl_add_u64 v[190:191], s[44:45], 0, v[132:133]
	s_mov_b32 m0, s62
	ds_read_b128 v[208:211], v160
	ds_read_b128 v[212:215], v160 offset:1024
	ds_read_b128 v[216:219], v160 offset:2048
	ds_read_b128 v[220:223], v160 offset:3072
	global_load_lds_dwordx4 v[190:191], off
	s_add_i32 m0, s62, 0x2000
	v_lshl_add_u64 v[224:225], s[44:45], 0, v[128:129]
	global_load_lds_dwordx4 v[224:225], off
	s_barrier
	s_waitcnt lgkmcnt(0)
	s_setprio 1
	v_mfma_f32_16x16x32_bf16 v[116:119], v[208:211], v[170:173], v[116:119]
	v_mfma_f32_16x16x32_bf16 v[112:115], v[216:219], v[170:173], v[112:115]
	v_mfma_f32_16x16x32_bf16 v[100:103], v[208:211], v[178:181], v[100:103]
	v_mfma_f32_16x16x32_bf16 v[96:99], v[216:219], v[178:181], v[96:99]
	v_mfma_f32_16x16x32_bf16 v[84:87], v[208:211], v[186:189], v[84:87]
	v_mfma_f32_16x16x32_bf16 v[80:83], v[216:219], v[186:189], v[80:83]
	v_mfma_f32_16x16x32_bf16 v[68:71], v[208:211], v[200:203], v[68:71]
	v_mfma_f32_16x16x32_bf16 v[64:67], v[216:219], v[200:203], v[64:67]
	v_mfma_f32_16x16x32_bf16 v[116:119], v[212:215], v[174:177], v[116:119]
	v_mfma_f32_16x16x32_bf16 v[112:115], v[220:223], v[174:177], v[112:115]
	v_mfma_f32_16x16x32_bf16 v[100:103], v[212:215], v[182:185], v[100:103]
	v_mfma_f32_16x16x32_bf16 v[96:99], v[220:223], v[182:185], v[96:99]
	v_mfma_f32_16x16x32_bf16 v[84:87], v[212:215], v[196:199], v[84:87]
	v_mfma_f32_16x16x32_bf16 v[80:83], v[220:223], v[196:199], v[80:83]
	v_mfma_f32_16x16x32_bf16 v[68:71], v[212:215], v[204:207], v[68:71]
	v_mfma_f32_16x16x32_bf16 v[64:67], v[220:223], v[204:207], v[64:67]
	s_setprio 0
	s_mov_b32 m0, s37
	v_lshl_add_u64 v[226:227], s[20:21], 0, v[134:135]
	s_barrier
	ds_read_b128 v[170:173], v159 offset:16384
	ds_read_b128 v[174:177], v159 offset:17408
	ds_read_b128 v[178:181], v159 offset:18432
	ds_read_b128 v[182:185], v159 offset:19456
	ds_read_b128 v[186:189], v159 offset:20480
	ds_read_b128 v[196:199], v159 offset:21504
	ds_read_b128 v[200:203], v159 offset:22528
	ds_read_b128 v[204:207], v159 offset:23552
	global_load_lds_dwordx4 v[226:227], off
	s_mov_b32 m0, s47
	v_lshl_add_u64 v[228:229], s[20:21], 0, v[130:131]
	global_load_lds_dwordx4 v[228:229], off
	s_barrier
	s_waitcnt lgkmcnt(0)
	s_setprio 1
	v_mfma_f32_16x16x32_bf16 v[60:63], v[148:151], v[170:173], v[60:63]
	v_mfma_f32_16x16x32_bf16 v[56:59], v[162:165], v[170:173], v[56:59]
	v_mfma_f32_16x16x32_bf16 v[44:47], v[148:151], v[178:181], v[44:47]
	v_mfma_f32_16x16x32_bf16 v[40:43], v[162:165], v[178:181], v[40:43]
	v_mfma_f32_16x16x32_bf16 v[28:31], v[148:151], v[186:189], v[28:31]
	v_mfma_f32_16x16x32_bf16 v[24:27], v[162:165], v[186:189], v[24:27]
	v_mfma_f32_16x16x32_bf16 v[12:15], v[148:151], v[200:203], v[12:15]
	v_mfma_f32_16x16x32_bf16 v[8:11], v[162:165], v[200:203], v[8:11]
	v_mfma_f32_16x16x32_bf16 v[60:63], v[152:155], v[174:177], v[60:63]
	v_mfma_f32_16x16x32_bf16 v[56:59], v[166:169], v[174:177], v[56:59]
	v_mfma_f32_16x16x32_bf16 v[44:47], v[152:155], v[182:185], v[44:47]
	v_mfma_f32_16x16x32_bf16 v[40:43], v[166:169], v[182:185], v[40:43]
	v_mfma_f32_16x16x32_bf16 v[28:31], v[152:155], v[196:199], v[28:31]
	v_mfma_f32_16x16x32_bf16 v[24:27], v[166:169], v[196:199], v[24:27]
	v_mfma_f32_16x16x32_bf16 v[12:15], v[152:155], v[204:207], v[12:15]
	v_mfma_f32_16x16x32_bf16 v[8:11], v[166:169], v[204:207], v[8:11]
	s_setprio 0
	s_barrier
	s_add_u32 s62, s44, 0x80000
	s_addc_u32 s63, s45, 0
	s_add_i32 s64, s55, s23
	s_mov_b32 m0, s64
	v_lshl_add_u64 v[148:149], s[62:63], 0, v[132:133]
	global_load_lds_dwordx4 v[148:149], off
	s_add_i32 m0, s64, 0x2000
	v_lshl_add_u64 v[148:149], s[62:63], 0, v[128:129]
	global_load_lds_dwordx4 v[148:149], off
	s_waitcnt vmcnt(6)
	s_barrier
	s_setprio 1
	v_mfma_f32_16x16x32_bf16 v[52:55], v[208:211], v[170:173], v[52:55]
	v_mfma_f32_16x16x32_bf16 v[48:51], v[216:219], v[170:173], v[48:51]
	v_mfma_f32_16x16x32_bf16 v[36:39], v[208:211], v[178:181], v[36:39]
	v_mfma_f32_16x16x32_bf16 v[32:35], v[216:219], v[178:181], v[32:35]
	v_mfma_f32_16x16x32_bf16 v[20:23], v[208:211], v[186:189], v[20:23]
	v_mfma_f32_16x16x32_bf16 v[16:19], v[216:219], v[186:189], v[16:19]
	v_mfma_f32_16x16x32_bf16 v[4:7], v[208:211], v[200:203], v[4:7]
	v_mfma_f32_16x16x32_bf16 v[0:3], v[216:219], v[200:203], v[0:3]
	v_mfma_f32_16x16x32_bf16 v[52:55], v[212:215], v[174:177], v[52:55]
	v_mfma_f32_16x16x32_bf16 v[48:51], v[220:223], v[174:177], v[48:51]
	v_mfma_f32_16x16x32_bf16 v[36:39], v[212:215], v[182:185], v[36:39]
	v_mfma_f32_16x16x32_bf16 v[32:35], v[220:223], v[182:185], v[32:35]
	v_mfma_f32_16x16x32_bf16 v[20:23], v[212:215], v[196:199], v[20:23]
	v_mfma_f32_16x16x32_bf16 v[16:19], v[220:223], v[196:199], v[16:19]
	v_mfma_f32_16x16x32_bf16 v[4:7], v[212:215], v[204:207], v[4:7]
	v_mfma_f32_16x16x32_bf16 v[0:3], v[220:223], v[204:207], v[0:3]
	s_setprio 0
	s_add_i32 s62, 0, 0x18000
	v_add_u32_e32 v161, s62, v147
	s_barrier
	ds_read_b128 v[148:151], v161
	ds_read_b128 v[152:155], v161 offset:1024
	ds_read_b128 v[162:165], v161 offset:2048
	ds_read_b128 v[166:169], v161 offset:3072
	s_add_u32 s20, s20, 0x80000
	s_addc_u32 s21, s21, 0
	s_mov_b32 m0, s48
	v_lshl_add_u64 v[208:209], s[20:21], 0, v[134:135]
	ds_read_b128 v[170:173], v159 offset:32768
	ds_read_b128 v[174:177], v159 offset:33792
	ds_read_b128 v[178:181], v159 offset:34816
	ds_read_b128 v[182:185], v159 offset:35840
	ds_read_b128 v[186:189], v159 offset:36864
	ds_read_b128 v[196:199], v159 offset:37888
	ds_read_b128 v[200:203], v159 offset:38912
	ds_read_b128 v[204:207], v159 offset:39936
	global_load_lds_dwordx4 v[208:209], off
	s_mov_b32 m0, s49
	v_lshl_add_u64 v[208:209], s[20:21], 0, v[130:131]
	global_load_lds_dwordx4 v[208:209], off
	s_waitcnt lgkmcnt(8)
	s_barrier
	s_waitcnt lgkmcnt(0)
	s_setprio 1
	v_mfma_f32_16x16x32_bf16 v[124:127], v[148:151], v[170:173], v[124:127]
	v_mfma_f32_16x16x32_bf16 v[120:123], v[162:165], v[170:173], v[120:123]
	v_mfma_f32_16x16x32_bf16 v[108:111], v[148:151], v[178:181], v[108:111]
	v_mfma_f32_16x16x32_bf16 v[104:107], v[162:165], v[178:181], v[104:107]
	v_mfma_f32_16x16x32_bf16 v[92:95], v[148:151], v[186:189], v[92:95]
	v_mfma_f32_16x16x32_bf16 v[88:91], v[162:165], v[186:189], v[88:91]
	v_mfma_f32_16x16x32_bf16 v[76:79], v[148:151], v[200:203], v[76:79]
	v_mfma_f32_16x16x32_bf16 v[72:75], v[162:165], v[200:203], v[72:75]
	v_mfma_f32_16x16x32_bf16 v[124:127], v[152:155], v[174:177], v[124:127]
	v_mfma_f32_16x16x32_bf16 v[120:123], v[166:169], v[174:177], v[120:123]
	v_mfma_f32_16x16x32_bf16 v[108:111], v[152:155], v[182:185], v[108:111]
	v_mfma_f32_16x16x32_bf16 v[104:107], v[166:169], v[182:185], v[104:107]
	v_mfma_f32_16x16x32_bf16 v[92:95], v[152:155], v[196:199], v[92:95]
	v_mfma_f32_16x16x32_bf16 v[88:91], v[166:169], v[196:199], v[88:91]
	v_mfma_f32_16x16x32_bf16 v[76:79], v[152:155], v[204:207], v[76:79]
	v_mfma_f32_16x16x32_bf16 v[72:75], v[166:169], v[204:207], v[72:75]
	s_setprio 0
	s_barrier
	s_add_i32 s63, 0, 0x1c000
	s_add_i32 s20, s62, s23
	v_add_u32_e32 v161, s63, v147
	v_lshl_add_u64 v[190:191], v[190:191], 0, s[10:11]
	s_mov_b32 m0, s20
	ds_read_b128 v[208:211], v161
	ds_read_b128 v[212:215], v161 offset:1024
	ds_read_b128 v[216:219], v161 offset:2048
	ds_read_b128 v[220:223], v161 offset:3072
	global_load_lds_dwordx4 v[190:191], off
	s_add_i32 m0, s20, 0x2000
	v_lshl_add_u64 v[190:191], v[224:225], 0, s[10:11]
	global_load_lds_dwordx4 v[190:191], off
	s_barrier
	s_waitcnt lgkmcnt(0)
	s_setprio 1
	v_mfma_f32_16x16x32_bf16 v[116:119], v[208:211], v[170:173], v[116:119]
	v_mfma_f32_16x16x32_bf16 v[112:115], v[216:219], v[170:173], v[112:115]
	v_mfma_f32_16x16x32_bf16 v[100:103], v[208:211], v[178:181], v[100:103]
	v_mfma_f32_16x16x32_bf16 v[96:99], v[216:219], v[178:181], v[96:99]
	v_mfma_f32_16x16x32_bf16 v[84:87], v[208:211], v[186:189], v[84:87]
	v_mfma_f32_16x16x32_bf16 v[80:83], v[216:219], v[186:189], v[80:83]
	v_mfma_f32_16x16x32_bf16 v[68:71], v[208:211], v[200:203], v[68:71]
	v_mfma_f32_16x16x32_bf16 v[64:67], v[216:219], v[200:203], v[64:67]
	v_mfma_f32_16x16x32_bf16 v[116:119], v[212:215], v[174:177], v[116:119]
	v_mfma_f32_16x16x32_bf16 v[112:115], v[220:223], v[174:177], v[112:115]
	v_mfma_f32_16x16x32_bf16 v[100:103], v[212:215], v[182:185], v[100:103]
	v_mfma_f32_16x16x32_bf16 v[96:99], v[220:223], v[182:185], v[96:99]
	v_mfma_f32_16x16x32_bf16 v[84:87], v[212:215], v[196:199], v[84:87]
	v_mfma_f32_16x16x32_bf16 v[80:83], v[220:223], v[196:199], v[80:83]
	v_mfma_f32_16x16x32_bf16 v[68:71], v[212:215], v[204:207], v[68:71]
	v_mfma_f32_16x16x32_bf16 v[64:67], v[220:223], v[204:207], v[64:67]
	s_setprio 0
	s_mov_b32 m0, s34
	v_lshl_add_u64 v[190:191], v[226:227], 0, s[10:11]
	s_barrier
	ds_read_b128 v[170:173], v159 offset:49152
	ds_read_b128 v[174:177], v159 offset:50176
	ds_read_b128 v[178:181], v159 offset:51200
	ds_read_b128 v[182:185], v159 offset:52224
	ds_read_b128 v[186:189], v159 offset:53248
	ds_read_b128 v[196:199], v159 offset:54272
	ds_read_b128 v[200:203], v159 offset:55296
	ds_read_b128 v[204:207], v159 offset:56320
	global_load_lds_dwordx4 v[190:191], off
	s_mov_b32 m0, s35
	v_lshl_add_u64 v[190:191], v[228:229], 0, s[10:11]
	global_load_lds_dwordx4 v[190:191], off
	s_barrier
	s_waitcnt lgkmcnt(0)
	s_setprio 1
	v_mfma_f32_16x16x32_bf16 v[60:63], v[148:151], v[170:173], v[60:63]
	v_mfma_f32_16x16x32_bf16 v[56:59], v[162:165], v[170:173], v[56:59]
	v_mfma_f32_16x16x32_bf16 v[44:47], v[148:151], v[178:181], v[44:47]
	v_mfma_f32_16x16x32_bf16 v[40:43], v[162:165], v[178:181], v[40:43]
	v_mfma_f32_16x16x32_bf16 v[28:31], v[148:151], v[186:189], v[28:31]
	v_mfma_f32_16x16x32_bf16 v[24:27], v[162:165], v[186:189], v[24:27]
	v_mfma_f32_16x16x32_bf16 v[12:15], v[148:151], v[200:203], v[12:15]
	v_mfma_f32_16x16x32_bf16 v[8:11], v[162:165], v[200:203], v[8:11]
	v_mfma_f32_16x16x32_bf16 v[60:63], v[152:155], v[174:177], v[60:63]
	v_mfma_f32_16x16x32_bf16 v[56:59], v[166:169], v[174:177], v[56:59]
	v_mfma_f32_16x16x32_bf16 v[44:47], v[152:155], v[182:185], v[44:47]
	v_mfma_f32_16x16x32_bf16 v[40:43], v[166:169], v[182:185], v[40:43]
	v_mfma_f32_16x16x32_bf16 v[28:31], v[152:155], v[196:199], v[28:31]
	v_mfma_f32_16x16x32_bf16 v[24:27], v[166:169], v[196:199], v[24:27]
	v_mfma_f32_16x16x32_bf16 v[12:15], v[152:155], v[204:207], v[12:15]
	v_mfma_f32_16x16x32_bf16 v[8:11], v[166:169], v[204:207], v[8:11]
	s_setprio 0
	s_barrier
	s_add_u32 s20, s44, 0x80080
	s_addc_u32 s21, s45, 0
	s_add_i32 s44, s63, s23
	s_mov_b32 m0, s44
	v_lshl_add_u64 v[148:149], s[20:21], 0, v[132:133]
	global_load_lds_dwordx4 v[148:149], off
	s_add_i32 m0, s44, 0x2000
	v_lshl_add_u64 v[148:149], s[20:21], 0, v[128:129]
	global_load_lds_dwordx4 v[148:149], off
	s_waitcnt vmcnt(6)
	s_barrier
	s_setprio 1
	v_mfma_f32_16x16x32_bf16 v[52:55], v[208:211], v[170:173], v[52:55]
	v_mfma_f32_16x16x32_bf16 v[48:51], v[216:219], v[170:173], v[48:51]
	v_mfma_f32_16x16x32_bf16 v[36:39], v[208:211], v[178:181], v[36:39]
	v_mfma_f32_16x16x32_bf16 v[32:35], v[216:219], v[178:181], v[32:35]
	v_mfma_f32_16x16x32_bf16 v[20:23], v[208:211], v[186:189], v[20:23]
	v_mfma_f32_16x16x32_bf16 v[16:19], v[216:219], v[186:189], v[16:19]
	v_mfma_f32_16x16x32_bf16 v[4:7], v[208:211], v[200:203], v[4:7]
	v_mfma_f32_16x16x32_bf16 v[0:3], v[216:219], v[200:203], v[0:3]
	v_mfma_f32_16x16x32_bf16 v[52:55], v[212:215], v[174:177], v[52:55]
	v_mfma_f32_16x16x32_bf16 v[48:51], v[220:223], v[174:177], v[48:51]
	v_mfma_f32_16x16x32_bf16 v[36:39], v[212:215], v[182:185], v[36:39]
	v_mfma_f32_16x16x32_bf16 v[32:35], v[220:223], v[182:185], v[32:35]
	v_mfma_f32_16x16x32_bf16 v[20:23], v[212:215], v[196:199], v[20:23]
	v_mfma_f32_16x16x32_bf16 v[16:19], v[220:223], v[196:199], v[16:19]
	v_mfma_f32_16x16x32_bf16 v[4:7], v[212:215], v[204:207], v[4:7]
	v_mfma_f32_16x16x32_bf16 v[0:3], v[220:223], v[204:207], v[0:3]
	s_setprio 0
	s_add_i32 s61, s61, 2
	s_add_u32 s38, s38, 0x100
	s_addc_u32 s39, s39, 0
	s_add_u32 s59, s59, 0x100
	s_addc_u32 s60, s60, 0
	s_cmp_gt_u32 s61, 29
	s_cbranch_scc0 .Lepi_nl_c_out
	s_cmp_lg_u32 s51, 64
	s_cbranch_scc1 .Lepi_nl_c_out
	s_lshl_b32 s15, s36, 8
	s_add_i32 s15, s15, s51
	v_or_b32_e32 v154, s15, v145
	s_add_i32 s17, s15, 0xffffe000
	v_lshl_or_b32 v150, s33, 8, v157
	s_lshr_b32 s17, s17, 12
	v_lshlrev_b32_e32 v148, 12, v154
	s_add_i32 s17, s17, 1
	s_cmp_gt_i32 s15, s56
	s_cselect_b32 s17, s17, 0
	s_mul_i32 s17, s17, s54
	v_lshl_add_u32 v148, v150, 1, v148
	s_add_u32 s20, s8, s17
	s_addc_u32 s21, s9, 0
	v_lshlrev_b32_e32 v149, 2, v150
	s_nop 0
	global_load_dwordx4 v[196:199], v149, s[20:21]
	global_load_dwordx4 v[200:203], v149, s[20:21] offset:16
	global_load_dwordx4 v[204:207], v149, s[20:21] offset:512
	global_load_dwordx4 v[208:211], v149, s[20:21] offset:528
	global_load_dwordx4 v[212:215], v148, s[74:75]
	global_load_dwordx4 v[216:219], v148, s[74:75] offset:256
	v_add_u32_e32 v151, 0x10000, v148
	global_load_dwordx4 v[220:223], v151, s[74:75]
	global_load_dwordx4 v[224:227], v151, s[74:75] offset:256
	v_add_u32_e32 v151, 0x20000, v148
	global_load_dwordx4 v[164:167], v151, s[74:75]
	global_load_dwordx4 v[168:171], v151, s[74:75] offset:256
	v_add_u32_e32 v151, 0x30000, v148
	global_load_dwordx4 v[172:175], v151, s[74:75]
	global_load_dwordx4 v[176:179], v151, s[74:75] offset:256
	s_waitcnt vmcnt(0)
	v_lshlrev_b32_e32 v180, 16, v212
	v_and_b32_e32 v181, 0xffff0000, v212
	v_lshlrev_b32_e32 v182, 16, v213
	v_and_b32_e32 v183, 0xffff0000, v213
	v_lshlrev_b32_e32 v184, 16, v214
	v_and_b32_e32 v185, 0xffff0000, v214
	v_lshlrev_b32_e32 v186, 16, v215
	v_and_b32_e32 v187, 0xffff0000, v215
	v_pk_fma_f32 v[124:125], v[124:125], v[196:197], v[180:181]
	v_pk_fma_f32 v[126:127], v[126:127], v[198:199], v[182:183]
	v_pk_fma_f32 v[120:121], v[120:121], v[200:201], v[184:185]
	v_pk_fma_f32 v[122:123], v[122:123], v[202:203], v[186:187]
	v_cvt_pk_bf16_f32 v123, v122, v123
	v_cvt_pk_bf16_f32 v122, v120, v121
	v_cvt_pk_bf16_f32 v121, v126, v127
	v_cvt_pk_bf16_f32 v120, v124, v125
	global_store_dwordx4 v148, v[120:123], s[74:75]
	v_lshlrev_b32_e32 v180, 16, v216
	v_and_b32_e32 v181, 0xffff0000, v216
	v_lshlrev_b32_e32 v182, 16, v217
	v_and_b32_e32 v183, 0xffff0000, v217
	v_lshlrev_b32_e32 v184, 16, v218
	v_and_b32_e32 v185, 0xffff0000, v218
	v_lshlrev_b32_e32 v186, 16, v219
	v_and_b32_e32 v187, 0xffff0000, v219
	v_pk_fma_f32 v[116:117], v[116:117], v[204:205], v[180:181]
	v_pk_fma_f32 v[118:119], v[118:119], v[206:207], v[182:183]
	v_pk_fma_f32 v[112:113], v[112:113], v[208:209], v[184:185]
	v_pk_fma_f32 v[114:115], v[114:115], v[210:211], v[186:187]
	v_cvt_pk_bf16_f32 v115, v114, v115
	v_cvt_pk_bf16_f32 v114, v112, v113
	v_cvt_pk_bf16_f32 v113, v118, v119
	v_cvt_pk_bf16_f32 v112, v116, v117
	global_store_dwordx4 v148, v[112:115], s[74:75] offset:256
	v_lshlrev_b32_e32 v180, 16, v220
	v_and_b32_e32 v181, 0xffff0000, v220
	v_lshlrev_b32_e32 v182, 16, v221
	v_and_b32_e32 v183, 0xffff0000, v221
	v_lshlrev_b32_e32 v184, 16, v222
	v_and_b32_e32 v185, 0xffff0000, v222
	v_lshlrev_b32_e32 v186, 16, v223
	v_and_b32_e32 v187, 0xffff0000, v223
	v_pk_fma_f32 v[108:109], v[108:109], v[196:197], v[180:181]
	v_pk_fma_f32 v[110:111], v[110:111], v[198:199], v[182:183]
	v_pk_fma_f32 v[104:105], v[104:105], v[200:201], v[184:185]
	v_pk_fma_f32 v[106:107], v[106:107], v[202:203], v[186:187]
	v_cvt_pk_bf16_f32 v107, v106, v107
	v_cvt_pk_bf16_f32 v106, v104, v105
	v_cvt_pk_bf16_f32 v105, v110, v111
	v_cvt_pk_bf16_f32 v104, v108, v109
	v_add_u32_e32 v151, 0x10000, v148
	global_store_dwordx4 v151, v[104:107], s[74:75]
	v_lshlrev_b32_e32 v180, 16, v224
	v_and_b32_e32 v181, 0xffff0000, v224
	v_lshlrev_b32_e32 v182, 16, v225
	v_and_b32_e32 v183, 0xffff0000, v225
	v_lshlrev_b32_e32 v184, 16, v226
	v_and_b32_e32 v185, 0xffff0000, v226
	v_lshlrev_b32_e32 v186, 16, v227
	v_and_b32_e32 v187, 0xffff0000, v227
	v_pk_fma_f32 v[100:101], v[100:101], v[204:205], v[180:181]
	v_pk_fma_f32 v[102:103], v[102:103], v[206:207], v[182:183]
	v_pk_fma_f32 v[96:97], v[96:97], v[208:209], v[184:185]
	v_pk_fma_f32 v[98:99], v[98:99], v[210:211], v[186:187]
	v_cvt_pk_bf16_f32 v99, v98, v99
	v_cvt_pk_bf16_f32 v98, v96, v97
	v_cvt_pk_bf16_f32 v97, v102, v103
	v_cvt_pk_bf16_f32 v96, v100, v101
	v_add_u32_e32 v151, 0x10000, v148
	global_store_dwordx4 v151, v[96:99], s[74:75] offset:256
	v_add_u32_e32 v151, 0x80000, v148
	global_load_dwordx4 v[212:215], v151, s[74:75]
	global_load_dwordx4 v[216:219], v151, s[74:75] offset:256
	v_add_u32_e32 v151, 0x90000, v148
	global_load_dwordx4 v[220:223], v151, s[74:75]
	global_load_dwordx4 v[224:227], v151, s[74:75] offset:256
	v_lshlrev_b32_e32 v180, 16, v164
	v_and_b32_e32 v181, 0xffff0000, v164
	v_lshlrev_b32_e32 v182, 16, v165
	v_and_b32_e32 v183, 0xffff0000, v165
	v_lshlrev_b32_e32 v184, 16, v166
	v_and_b32_e32 v185, 0xffff0000, v166
	v_lshlrev_b32_e32 v186, 16, v167
	v_and_b32_e32 v187, 0xffff0000, v167
	v_pk_fma_f32 v[92:93], v[92:93], v[196:197], v[180:181]
	v_pk_fma_f32 v[94:95], v[94:95], v[198:199], v[182:183]
	v_pk_fma_f32 v[88:89], v[88:89], v[200:201], v[184:185]
	v_pk_fma_f32 v[90:91], v[90:91], v[202:203], v[186:187]
	v_cvt_pk_bf16_f32 v91, v90, v91
	v_cvt_pk_bf16_f32 v90, v88, v89
	v_cvt_pk_bf16_f32 v89, v94, v95
	v_cvt_pk_bf16_f32 v88, v92, v93
	v_add_u32_e32 v151, 0x20000, v148
	global_store_dwordx4 v151, v[88:91], s[74:75]
	v_lshlrev_b32_e32 v180, 16, v168
	v_and_b32_e32 v181, 0xffff0000, v168
	v_lshlrev_b32_e32 v182, 16, v169
	v_and_b32_e32 v183, 0xffff0000, v169
	v_lshlrev_b32_e32 v184, 16, v170
	v_and_b32_e32 v185, 0xffff0000, v170
	v_lshlrev_b32_e32 v186, 16, v171
	v_and_b32_e32 v187, 0xffff0000, v171
	v_pk_fma_f32 v[84:85], v[84:85], v[204:205], v[180:181]
	v_pk_fma_f32 v[86:87], v[86:87], v[206:207], v[182:183]
	v_pk_fma_f32 v[80:81], v[80:81], v[208:209], v[184:185]
	v_pk_fma_f32 v[82:83], v[82:83], v[210:211], v[186:187]
	v_cvt_pk_bf16_f32 v83, v82, v83
	v_cvt_pk_bf16_f32 v82, v80, v81
	v_cvt_pk_bf16_f32 v81, v86, v87
	v_cvt_pk_bf16_f32 v80, v84, v85
	v_add_u32_e32 v151, 0x20000, v148
	global_store_dwordx4 v151, v[80:83], s[74:75] offset:256
	v_lshlrev_b32_e32 v180, 16, v172
	v_and_b32_e32 v181, 0xffff0000, v172
	v_lshlrev_b32_e32 v182, 16, v173
	v_and_b32_e32 v183, 0xffff0000, v173
	v_lshlrev_b32_e32 v184, 16, v174
	v_and_b32_e32 v185, 0xffff0000, v174
	v_lshlrev_b32_e32 v186, 16, v175
	v_and_b32_e32 v187, 0xffff0000, v175
	v_pk_fma_f32 v[76:77], v[76:77], v[196:197], v[180:181]
	v_pk_fma_f32 v[78:79], v[78:79], v[198:199], v[182:183]
	v_pk_fma_f32 v[72:73], v[72:73], v[200:201], v[184:185]
	v_pk_fma_f32 v[74:75], v[74:75], v[202:203], v[186:187]
	v_cvt_pk_bf16_f32 v75, v74, v75
	v_cvt_pk_bf16_f32 v74, v72, v73
	v_cvt_pk_bf16_f32 v73, v78, v79
	v_cvt_pk_bf16_f32 v72, v76, v77
	v_add_u32_e32 v151, 0x30000, v148
	global_store_dwordx4 v151, v[72:75], s[74:75]
	v_lshlrev_b32_e32 v180, 16, v176
	v_and_b32_e32 v181, 0xffff0000, v176
	v_lshlrev_b32_e32 v182, 16, v177
	v_and_b32_e32 v183, 0xffff0000, v177
	v_lshlrev_b32_e32 v184, 16, v178
	v_and_b32_e32 v185, 0xffff0000, v178
	v_lshlrev_b32_e32 v186, 16, v179
	v_and_b32_e32 v187, 0xffff0000, v179
	v_pk_fma_f32 v[68:69], v[68:69], v[204:205], v[180:181]
	v_pk_fma_f32 v[70:71], v[70:71], v[206:207], v[182:183]
	v_pk_fma_f32 v[64:65], v[64:65], v[208:209], v[184:185]
	v_pk_fma_f32 v[66:67], v[66:67], v[210:211], v[186:187]
	v_cvt_pk_bf16_f32 v67, v66, v67
	v_cvt_pk_bf16_f32 v66, v64, v65
	v_cvt_pk_bf16_f32 v65, v70, v71
	v_cvt_pk_bf16_f32 v64, v68, v69
	v_add_u32_e32 v151, 0x30000, v148
	global_store_dwordx4 v151, v[64:67], s[74:75] offset:256
	v_add_u32_e32 v151, 0xa0000, v148
	global_load_dwordx4 v[164:167], v151, s[74:75]
	global_load_dwordx4 v[168:171], v151, s[74:75] offset:256
	v_add_u32_e32 v151, 0xb0000, v148
	global_load_dwordx4 v[172:175], v151, s[74:75]
	global_load_dwordx4 v[176:179], v151, s[74:75] offset:256
	s_waitcnt vmcnt(0)
	v_lshlrev_b32_e32 v180, 16, v212
	v_and_b32_e32 v181, 0xffff0000, v212
	v_lshlrev_b32_e32 v182, 16, v213
	v_and_b32_e32 v183, 0xffff0000, v213
	v_lshlrev_b32_e32 v184, 16, v214
	v_and_b32_e32 v185, 0xffff0000, v214
	v_lshlrev_b32_e32 v186, 16, v215
	v_and_b32_e32 v187, 0xffff0000, v215
	v_pk_fma_f32 v[60:61], v[60:61], v[196:197], v[180:181]
	v_pk_fma_f32 v[62:63], v[62:63], v[198:199], v[182:183]
	v_pk_fma_f32 v[56:57], v[56:57], v[200:201], v[184:185]
	v_pk_fma_f32 v[58:59], v[58:59], v[202:203], v[186:187]
	v_cvt_pk_bf16_f32 v59, v58, v59
	v_cvt_pk_bf16_f32 v58, v56, v57
	v_cvt_pk_bf16_f32 v57, v62, v63
	v_cvt_pk_bf16_f32 v56, v60, v61
	v_add_u32_e32 v151, 0x80000, v148
	global_store_dwordx4 v151, v[56:59], s[74:75]
	v_lshlrev_b32_e32 v180, 16, v216
	v_and_b32_e32 v181, 0xffff0000, v216
	v_lshlrev_b32_e32 v182, 16, v217
	v_and_b32_e32 v183, 0xffff0000, v217
	v_lshlrev_b32_e32 v184, 16, v218
	v_and_b32_e32 v185, 0xffff0000, v218
	v_lshlrev_b32_e32 v186, 16, v219
	v_and_b32_e32 v187, 0xffff0000, v219
	v_pk_fma_f32 v[52:53], v[52:53], v[204:205], v[180:181]
	v_pk_fma_f32 v[54:55], v[54:55], v[206:207], v[182:183]
	v_pk_fma_f32 v[48:49], v[48:49], v[208:209], v[184:185]
	v_pk_fma_f32 v[50:51], v[50:51], v[210:211], v[186:187]
	v_cvt_pk_bf16_f32 v51, v50, v51
	v_cvt_pk_bf16_f32 v50, v48, v49
	v_cvt_pk_bf16_f32 v49, v54, v55
	v_cvt_pk_bf16_f32 v48, v52, v53
	v_add_u32_e32 v151, 0x80000, v148
	global_store_dwordx4 v151, v[48:51], s[74:75] offset:256
	v_lshlrev_b32_e32 v180, 16, v220
	v_and_b32_e32 v181, 0xffff0000, v220
	v_lshlrev_b32_e32 v182, 16, v221
	v_and_b32_e32 v183, 0xffff0000, v221
	v_lshlrev_b32_e32 v184, 16, v222
	v_and_b32_e32 v185, 0xffff0000, v222
	v_lshlrev_b32_e32 v186, 16, v223
	v_and_b32_e32 v187, 0xffff0000, v223
	v_pk_fma_f32 v[44:45], v[44:45], v[196:197], v[180:181]
	v_pk_fma_f32 v[46:47], v[46:47], v[198:199], v[182:183]
	v_pk_fma_f32 v[40:41], v[40:41], v[200:201], v[184:185]
	v_pk_fma_f32 v[42:43], v[42:43], v[202:203], v[186:187]
	v_cvt_pk_bf16_f32 v43, v42, v43
	v_cvt_pk_bf16_f32 v42, v40, v41
	v_cvt_pk_bf16_f32 v41, v46, v47
	v_cvt_pk_bf16_f32 v40, v44, v45
	v_add_u32_e32 v151, 0x90000, v148
	global_store_dwordx4 v151, v[40:43], s[74:75]
	v_lshlrev_b32_e32 v180, 16, v224
	v_and_b32_e32 v181, 0xffff0000, v224
	v_lshlrev_b32_e32 v182, 16, v225
	v_and_b32_e32 v183, 0xffff0000, v225
	v_lshlrev_b32_e32 v184, 16, v226
	v_and_b32_e32 v185, 0xffff0000, v226
	v_lshlrev_b32_e32 v186, 16, v227
	v_and_b32_e32 v187, 0xffff0000, v227
	v_pk_fma_f32 v[36:37], v[36:37], v[204:205], v[180:181]
	v_pk_fma_f32 v[38:39], v[38:39], v[206:207], v[182:183]
	v_pk_fma_f32 v[32:33], v[32:33], v[208:209], v[184:185]
	v_pk_fma_f32 v[34:35], v[34:35], v[210:211], v[186:187]
	v_cvt_pk_bf16_f32 v35, v34, v35
	v_cvt_pk_bf16_f32 v34, v32, v33
	v_cvt_pk_bf16_f32 v33, v38, v39
	v_cvt_pk_bf16_f32 v32, v36, v37
	v_add_u32_e32 v151, 0x90000, v148
	global_store_dwordx4 v151, v[32:35], s[74:75] offset:256
	v_lshlrev_b32_e32 v180, 16, v164
	v_and_b32_e32 v181, 0xffff0000, v164
	v_lshlrev_b32_e32 v182, 16, v165
	v_and_b32_e32 v183, 0xffff0000, v165
	v_lshlrev_b32_e32 v184, 16, v166
	v_and_b32_e32 v185, 0xffff0000, v166
	v_lshlrev_b32_e32 v186, 16, v167
	v_and_b32_e32 v187, 0xffff0000, v167
	v_pk_fma_f32 v[28:29], v[28:29], v[196:197], v[180:181]
	v_pk_fma_f32 v[30:31], v[30:31], v[198:199], v[182:183]
	v_pk_fma_f32 v[24:25], v[24:25], v[200:201], v[184:185]
	v_pk_fma_f32 v[26:27], v[26:27], v[202:203], v[186:187]
	v_cvt_pk_bf16_f32 v27, v26, v27
	v_cvt_pk_bf16_f32 v26, v24, v25
	v_cvt_pk_bf16_f32 v25, v30, v31
	v_cvt_pk_bf16_f32 v24, v28, v29
	v_add_u32_e32 v151, 0xa0000, v148
	global_store_dwordx4 v151, v[24:27], s[74:75]
	v_lshlrev_b32_e32 v180, 16, v168
	v_and_b32_e32 v181, 0xffff0000, v168
	v_lshlrev_b32_e32 v182, 16, v169
	v_and_b32_e32 v183, 0xffff0000, v169
	v_lshlrev_b32_e32 v184, 16, v170
	v_and_b32_e32 v185, 0xffff0000, v170
	v_lshlrev_b32_e32 v186, 16, v171
	v_and_b32_e32 v187, 0xffff0000, v171
	v_pk_fma_f32 v[20:21], v[20:21], v[204:205], v[180:181]
	v_pk_fma_f32 v[22:23], v[22:23], v[206:207], v[182:183]
	v_pk_fma_f32 v[16:17], v[16:17], v[208:209], v[184:185]
	v_pk_fma_f32 v[18:19], v[18:19], v[210:211], v[186:187]
	v_cvt_pk_bf16_f32 v19, v18, v19
	v_cvt_pk_bf16_f32 v18, v16, v17
	v_cvt_pk_bf16_f32 v17, v22, v23
	v_cvt_pk_bf16_f32 v16, v20, v21
	v_add_u32_e32 v151, 0xa0000, v148
	global_store_dwordx4 v151, v[16:19], s[74:75] offset:256
	v_lshlrev_b32_e32 v180, 16, v172
	v_and_b32_e32 v181, 0xffff0000, v172
	v_lshlrev_b32_e32 v182, 16, v173
	v_and_b32_e32 v183, 0xffff0000, v173
	v_lshlrev_b32_e32 v184, 16, v174
	v_and_b32_e32 v185, 0xffff0000, v174
	v_lshlrev_b32_e32 v186, 16, v175
	v_and_b32_e32 v187, 0xffff0000, v175
	v_pk_fma_f32 v[12:13], v[12:13], v[196:197], v[180:181]
	v_pk_fma_f32 v[14:15], v[14:15], v[198:199], v[182:183]
	v_pk_fma_f32 v[8:9], v[8:9], v[200:201], v[184:185]
	v_pk_fma_f32 v[10:11], v[10:11], v[202:203], v[186:187]
	v_cvt_pk_bf16_f32 v11, v10, v11
	v_cvt_pk_bf16_f32 v10, v8, v9
	v_cvt_pk_bf16_f32 v9, v14, v15
	v_cvt_pk_bf16_f32 v8, v12, v13
	v_add_u32_e32 v151, 0xb0000, v148
	global_store_dwordx4 v151, v[8:11], s[74:75]
	v_lshlrev_b32_e32 v180, 16, v176
	v_and_b32_e32 v181, 0xffff0000, v176
	v_lshlrev_b32_e32 v182, 16, v177
	v_and_b32_e32 v183, 0xffff0000, v177
	v_lshlrev_b32_e32 v184, 16, v178
	v_and_b32_e32 v185, 0xffff0000, v178
	v_lshlrev_b32_e32 v186, 16, v179
	v_and_b32_e32 v187, 0xffff0000, v179
	v_pk_fma_f32 v[4:5], v[4:5], v[204:205], v[180:181]
	v_pk_fma_f32 v[6:7], v[6:7], v[206:207], v[182:183]
	v_pk_fma_f32 v[0:1], v[0:1], v[208:209], v[184:185]
	v_pk_fma_f32 v[2:3], v[2:3], v[210:211], v[186:187]
	v_cvt_pk_bf16_f32 v3, v2, v3
	v_cvt_pk_bf16_f32 v2, v0, v1
	v_cvt_pk_bf16_f32 v1, v6, v7
	v_cvt_pk_bf16_f32 v0, v4, v5
	v_add_u32_e32 v151, 0xb0000, v148
	global_store_dwordx4 v151, v[0:3], s[74:75] offset:256

.LBB0_1402:
	ds_read_b128 v[154:157], v151
	ds_read_b128 v[158:161], v151 offset:1024
	ds_read_b128 v[162:165], v151 offset:2048
	ds_read_b128 v[166:169], v151 offset:3072
	s_add_u32 s20, s26, 0xfff80080
	s_addc_u32 s21, s27, -1
	s_cmp_eq_u32 s52, 28
	s_cselect_b32 s21, s15, s21
	s_cselect_b32 s20, s48, s20
	s_cselect_b32 s37, s11, s51
	s_cselect_b32 s36, s49, s50
	v_lshl_add_u64 v[148:149], s[26:27], 0, v[136:137]
	s_add_i32 m0, s25, 0xc000
	ds_read_b128 v[170:173], v152
	ds_read_b128 v[174:177], v152 offset:1024
	ds_read_b128 v[178:181], v152 offset:2048
	ds_read_b128 v[182:185], v152 offset:3072
	ds_read_b128 v[186:189], v152 offset:4096
	ds_read_b128 v[196:199], v152 offset:5120
	ds_read_b128 v[200:203], v152 offset:6144
	ds_read_b128 v[204:207], v152 offset:7168
	global_load_lds_dwordx4 v[148:149], off
	s_add_i32 m0, s25, 0xe000
	v_lshl_add_u64 v[148:149], s[26:27], 0, v[138:139]
	global_load_lds_dwordx4 v[148:149], off
	s_waitcnt lgkmcnt(8)
	s_barrier
	s_waitcnt lgkmcnt(0)
	s_setprio 1
	v_mfma_f32_16x16x32_bf16 v[124:127], v[154:157], v[170:173], v[124:127]
	v_mfma_f32_16x16x32_bf16 v[120:123], v[162:165], v[170:173], v[120:123]
	v_mfma_f32_16x16x32_bf16 v[108:111], v[154:157], v[178:181], v[108:111]
	v_mfma_f32_16x16x32_bf16 v[104:107], v[162:165], v[178:181], v[104:107]
	v_mfma_f32_16x16x32_bf16 v[92:95], v[154:157], v[186:189], v[92:95]
	v_mfma_f32_16x16x32_bf16 v[88:91], v[162:165], v[186:189], v[88:91]
	v_mfma_f32_16x16x32_bf16 v[76:79], v[154:157], v[200:203], v[76:79]
	v_mfma_f32_16x16x32_bf16 v[72:75], v[162:165], v[200:203], v[72:75]
	v_mfma_f32_16x16x32_bf16 v[124:127], v[158:161], v[174:177], v[124:127]
	v_mfma_f32_16x16x32_bf16 v[120:123], v[166:169], v[174:177], v[120:123]
	v_mfma_f32_16x16x32_bf16 v[108:111], v[158:161], v[182:185], v[108:111]
	v_mfma_f32_16x16x32_bf16 v[104:107], v[166:169], v[182:185], v[104:107]
	v_mfma_f32_16x16x32_bf16 v[92:95], v[158:161], v[196:199], v[92:95]
	v_mfma_f32_16x16x32_bf16 v[88:91], v[166:169], v[196:199], v[88:91]
	v_mfma_f32_16x16x32_bf16 v[76:79], v[158:161], v[204:207], v[76:79]
	v_mfma_f32_16x16x32_bf16 v[72:75], v[166:169], v[204:207], v[72:75]
	s_setprio 0
	s_barrier
	s_add_i32 s53, s46, s23
	v_lshl_add_u64 v[148:149], s[36:37], 0, v[132:133]
	s_mov_b32 m0, s53
	ds_read_b128 v[208:211], v153
	ds_read_b128 v[212:215], v153 offset:1024
	ds_read_b128 v[216:219], v153 offset:2048
	ds_read_b128 v[220:223], v153 offset:3072
	global_load_lds_dwordx4 v[148:149], off
	s_add_i32 m0, s53, 0x2000
	v_lshl_add_u64 v[190:191], s[36:37], 0, v[128:129]
	global_load_lds_dwordx4 v[190:191], off
	s_barrier
	s_waitcnt lgkmcnt(0)
	s_setprio 1
	v_mfma_f32_16x16x32_bf16 v[116:119], v[208:211], v[170:173], v[116:119]
	v_mfma_f32_16x16x32_bf16 v[112:115], v[216:219], v[170:173], v[112:115]
	v_mfma_f32_16x16x32_bf16 v[100:103], v[208:211], v[178:181], v[100:103]
	v_mfma_f32_16x16x32_bf16 v[96:99], v[216:219], v[178:181], v[96:99]
	v_mfma_f32_16x16x32_bf16 v[84:87], v[208:211], v[186:189], v[84:87]
	v_mfma_f32_16x16x32_bf16 v[80:83], v[216:219], v[186:189], v[80:83]
	v_mfma_f32_16x16x32_bf16 v[68:71], v[208:211], v[200:203], v[68:71]
	v_mfma_f32_16x16x32_bf16 v[64:67], v[216:219], v[200:203], v[64:67]
	v_mfma_f32_16x16x32_bf16 v[116:119], v[212:215], v[174:177], v[116:119]
	v_mfma_f32_16x16x32_bf16 v[112:115], v[220:223], v[174:177], v[112:115]
	v_mfma_f32_16x16x32_bf16 v[100:103], v[212:215], v[182:185], v[100:103]
	v_mfma_f32_16x16x32_bf16 v[96:99], v[220:223], v[182:185], v[96:99]
	v_mfma_f32_16x16x32_bf16 v[84:87], v[212:215], v[196:199], v[84:87]
	v_mfma_f32_16x16x32_bf16 v[80:83], v[220:223], v[196:199], v[80:83]
	v_mfma_f32_16x16x32_bf16 v[68:71], v[212:215], v[204:207], v[68:71]
	v_mfma_f32_16x16x32_bf16 v[64:67], v[220:223], v[204:207], v[64:67]
	s_setprio 0
	s_mov_b32 m0, s25
	v_lshl_add_u64 v[224:225], s[20:21], 0, v[134:135]
	s_barrier
	ds_read_b128 v[170:173], v152 offset:16384
	ds_read_b128 v[174:177], v152 offset:17408
	ds_read_b128 v[178:181], v152 offset:18432
	ds_read_b128 v[182:185], v152 offset:19456
	ds_read_b128 v[186:189], v152 offset:20480
	ds_read_b128 v[196:199], v152 offset:21504
	ds_read_b128 v[200:203], v152 offset:22528
	ds_read_b128 v[204:207], v152 offset:23552
	global_load_lds_dwordx4 v[224:225], off
	s_mov_b32 m0, s35
	v_lshl_add_u64 v[226:227], s[20:21], 0, v[130:131]
	global_load_lds_dwordx4 v[226:227], off
	s_barrier
	s_waitcnt lgkmcnt(0)
	s_setprio 1
	v_mfma_f32_16x16x32_bf16 v[60:63], v[154:157], v[170:173], v[60:63]
	v_mfma_f32_16x16x32_bf16 v[56:59], v[162:165], v[170:173], v[56:59]
	v_mfma_f32_16x16x32_bf16 v[44:47], v[154:157], v[178:181], v[44:47]
	v_mfma_f32_16x16x32_bf16 v[40:43], v[162:165], v[178:181], v[40:43]
	v_mfma_f32_16x16x32_bf16 v[28:31], v[154:157], v[186:189], v[28:31]
	v_mfma_f32_16x16x32_bf16 v[24:27], v[162:165], v[186:189], v[24:27]
	v_mfma_f32_16x16x32_bf16 v[12:15], v[154:157], v[200:203], v[12:15]
	v_mfma_f32_16x16x32_bf16 v[8:11], v[162:165], v[200:203], v[8:11]
	v_mfma_f32_16x16x32_bf16 v[60:63], v[158:161], v[174:177], v[60:63]
	v_mfma_f32_16x16x32_bf16 v[56:59], v[166:169], v[174:177], v[56:59]
	v_mfma_f32_16x16x32_bf16 v[44:47], v[158:161], v[182:185], v[44:47]
	v_mfma_f32_16x16x32_bf16 v[40:43], v[166:169], v[182:185], v[40:43]
	v_mfma_f32_16x16x32_bf16 v[28:31], v[158:161], v[196:199], v[28:31]
	v_mfma_f32_16x16x32_bf16 v[24:27], v[166:169], v[196:199], v[24:27]
	v_mfma_f32_16x16x32_bf16 v[12:15], v[158:161], v[204:207], v[12:15]
	v_mfma_f32_16x16x32_bf16 v[8:11], v[166:169], v[204:207], v[8:11]
	s_setprio 0
	s_barrier
	s_add_u32 s54, s36, 0x80000
	s_addc_u32 s55, s37, 0
	s_add_i32 s53, s47, s23
	s_mov_b32 m0, s53
	v_lshl_add_u64 v[154:155], s[54:55], 0, v[132:133]
	global_load_lds_dwordx4 v[154:155], off
	s_add_i32 m0, s53, 0x2000
	v_lshl_add_u64 v[154:155], s[54:55], 0, v[128:129]
	global_load_lds_dwordx4 v[154:155], off
	s_waitcnt vmcnt(6)
	s_barrier
	s_setprio 1
	v_mfma_f32_16x16x32_bf16 v[52:55], v[208:211], v[170:173], v[52:55]
	v_mfma_f32_16x16x32_bf16 v[48:51], v[216:219], v[170:173], v[48:51]
	v_mfma_f32_16x16x32_bf16 v[36:39], v[208:211], v[178:181], v[36:39]
	v_mfma_f32_16x16x32_bf16 v[32:35], v[216:219], v[178:181], v[32:35]
	v_mfma_f32_16x16x32_bf16 v[20:23], v[208:211], v[186:189], v[20:23]
	v_mfma_f32_16x16x32_bf16 v[16:19], v[216:219], v[186:189], v[16:19]
	v_mfma_f32_16x16x32_bf16 v[4:7], v[208:211], v[200:203], v[4:7]
	v_mfma_f32_16x16x32_bf16 v[0:3], v[216:219], v[200:203], v[0:3]
	v_mfma_f32_16x16x32_bf16 v[52:55], v[212:215], v[174:177], v[52:55]
	v_mfma_f32_16x16x32_bf16 v[48:51], v[220:223], v[174:177], v[48:51]
	v_mfma_f32_16x16x32_bf16 v[36:39], v[212:215], v[182:185], v[36:39]
	v_mfma_f32_16x16x32_bf16 v[32:35], v[220:223], v[182:185], v[32:35]
	v_mfma_f32_16x16x32_bf16 v[20:23], v[212:215], v[196:199], v[20:23]
	v_mfma_f32_16x16x32_bf16 v[16:19], v[220:223], v[196:199], v[16:19]
	v_mfma_f32_16x16x32_bf16 v[4:7], v[212:215], v[204:207], v[4:7]
	v_mfma_f32_16x16x32_bf16 v[0:3], v[220:223], v[204:207], v[0:3]
	s_setprio 0
	s_add_i32 s53, 0, 0x18000
	v_add_u32_e32 v166, s53, v147
	s_barrier
	ds_read_b128 v[154:157], v166
	ds_read_b128 v[158:161], v166 offset:1024
	ds_read_b128 v[162:165], v166 offset:2048
	ds_read_b128 v[166:169], v166 offset:3072
	s_add_u32 s20, s20, 0x80000
	s_addc_u32 s21, s21, 0
	s_mov_b32 m0, s38
	v_lshl_add_u64 v[208:209], s[20:21], 0, v[134:135]
	ds_read_b128 v[170:173], v152 offset:32768
	ds_read_b128 v[174:177], v152 offset:33792
	ds_read_b128 v[178:181], v152 offset:34816
	ds_read_b128 v[182:185], v152 offset:35840
	ds_read_b128 v[186:189], v152 offset:36864
	ds_read_b128 v[196:199], v152 offset:37888
	ds_read_b128 v[200:203], v152 offset:38912
	ds_read_b128 v[204:207], v152 offset:39936
	global_load_lds_dwordx4 v[208:209], off
	s_mov_b32 m0, s39
	v_lshl_add_u64 v[208:209], s[20:21], 0, v[130:131]
	global_load_lds_dwordx4 v[208:209], off
	s_waitcnt lgkmcnt(8)
	s_barrier
	s_waitcnt lgkmcnt(0)
	s_setprio 1
	v_mfma_f32_16x16x32_bf16 v[124:127], v[154:157], v[170:173], v[124:127]
	v_mfma_f32_16x16x32_bf16 v[120:123], v[162:165], v[170:173], v[120:123]
	v_mfma_f32_16x16x32_bf16 v[108:111], v[154:157], v[178:181], v[108:111]
	v_mfma_f32_16x16x32_bf16 v[104:107], v[162:165], v[178:181], v[104:107]
	v_mfma_f32_16x16x32_bf16 v[92:95], v[154:157], v[186:189], v[92:95]
	v_mfma_f32_16x16x32_bf16 v[88:91], v[162:165], v[186:189], v[88:91]
	v_mfma_f32_16x16x32_bf16 v[76:79], v[154:157], v[200:203], v[76:79]
	v_mfma_f32_16x16x32_bf16 v[72:75], v[162:165], v[200:203], v[72:75]
	v_mfma_f32_16x16x32_bf16 v[124:127], v[158:161], v[174:177], v[124:127]
	v_mfma_f32_16x16x32_bf16 v[120:123], v[166:169], v[174:177], v[120:123]
	v_mfma_f32_16x16x32_bf16 v[108:111], v[158:161], v[182:185], v[108:111]
	v_mfma_f32_16x16x32_bf16 v[104:107], v[166:169], v[182:185], v[104:107]
	v_mfma_f32_16x16x32_bf16 v[92:95], v[158:161], v[196:199], v[92:95]
	v_mfma_f32_16x16x32_bf16 v[88:91], v[166:169], v[196:199], v[88:91]
	v_mfma_f32_16x16x32_bf16 v[76:79], v[158:161], v[204:207], v[76:79]
	v_mfma_f32_16x16x32_bf16 v[72:75], v[166:169], v[204:207], v[72:75]
	s_setprio 0
	s_barrier
	s_add_i32 s54, 0, 0x1c000
	s_add_i32 s20, s53, s23
	v_add_u32_e32 v193, s54, v147
	v_lshl_add_u64 v[148:149], v[148:149], 0, s[8:9]
	s_mov_b32 m0, s20
	ds_read_b128 v[208:211], v193
	ds_read_b128 v[212:215], v193 offset:1024
	ds_read_b128 v[216:219], v193 offset:2048
	ds_read_b128 v[220:223], v193 offset:3072
	global_load_lds_dwordx4 v[148:149], off
	s_add_i32 m0, s20, 0x2000
	v_lshl_add_u64 v[148:149], v[190:191], 0, s[8:9]
	global_load_lds_dwordx4 v[148:149], off
	s_barrier
	s_waitcnt lgkmcnt(0)
	s_setprio 1
	v_mfma_f32_16x16x32_bf16 v[116:119], v[208:211], v[170:173], v[116:119]
	v_mfma_f32_16x16x32_bf16 v[112:115], v[216:219], v[170:173], v[112:115]
	v_mfma_f32_16x16x32_bf16 v[100:103], v[208:211], v[178:181], v[100:103]
	v_mfma_f32_16x16x32_bf16 v[96:99], v[216:219], v[178:181], v[96:99]
	v_mfma_f32_16x16x32_bf16 v[84:87], v[208:211], v[186:189], v[84:87]
	v_mfma_f32_16x16x32_bf16 v[80:83], v[216:219], v[186:189], v[80:83]
	v_mfma_f32_16x16x32_bf16 v[68:71], v[208:211], v[200:203], v[68:71]
	v_mfma_f32_16x16x32_bf16 v[64:67], v[216:219], v[200:203], v[64:67]
	v_mfma_f32_16x16x32_bf16 v[116:119], v[212:215], v[174:177], v[116:119]
	v_mfma_f32_16x16x32_bf16 v[112:115], v[220:223], v[174:177], v[112:115]
	v_mfma_f32_16x16x32_bf16 v[100:103], v[212:215], v[182:185], v[100:103]
	v_mfma_f32_16x16x32_bf16 v[96:99], v[220:223], v[182:185], v[96:99]
	v_mfma_f32_16x16x32_bf16 v[84:87], v[212:215], v[196:199], v[84:87]
	v_mfma_f32_16x16x32_bf16 v[80:83], v[220:223], v[196:199], v[80:83]
	v_mfma_f32_16x16x32_bf16 v[68:71], v[212:215], v[204:207], v[68:71]
	v_mfma_f32_16x16x32_bf16 v[64:67], v[220:223], v[204:207], v[64:67]
	s_setprio 0
	s_mov_b32 m0, s41
	v_lshl_add_u64 v[148:149], v[224:225], 0, s[8:9]
	s_barrier
	ds_read_b128 v[170:173], v152 offset:49152
	ds_read_b128 v[174:177], v152 offset:50176
	ds_read_b128 v[178:181], v152 offset:51200
	ds_read_b128 v[182:185], v152 offset:52224
	ds_read_b128 v[186:189], v152 offset:53248
	ds_read_b128 v[196:199], v152 offset:54272
	ds_read_b128 v[200:203], v152 offset:55296
	ds_read_b128 v[204:207], v152 offset:56320
	global_load_lds_dwordx4 v[148:149], off
	s_mov_b32 m0, s44
	v_lshl_add_u64 v[148:149], v[226:227], 0, s[8:9]
	global_load_lds_dwordx4 v[148:149], off
	s_barrier
	s_waitcnt lgkmcnt(0)
	s_setprio 1
	v_mfma_f32_16x16x32_bf16 v[60:63], v[154:157], v[170:173], v[60:63]
	v_mfma_f32_16x16x32_bf16 v[56:59], v[162:165], v[170:173], v[56:59]
	v_mfma_f32_16x16x32_bf16 v[44:47], v[154:157], v[178:181], v[44:47]
	v_mfma_f32_16x16x32_bf16 v[40:43], v[162:165], v[178:181], v[40:43]
	v_mfma_f32_16x16x32_bf16 v[28:31], v[154:157], v[186:189], v[28:31]
	v_mfma_f32_16x16x32_bf16 v[24:27], v[162:165], v[186:189], v[24:27]
	v_mfma_f32_16x16x32_bf16 v[12:15], v[154:157], v[200:203], v[12:15]
	v_mfma_f32_16x16x32_bf16 v[8:11], v[162:165], v[200:203], v[8:11]
	v_mfma_f32_16x16x32_bf16 v[60:63], v[158:161], v[174:177], v[60:63]
	v_mfma_f32_16x16x32_bf16 v[56:59], v[166:169], v[174:177], v[56:59]
	v_mfma_f32_16x16x32_bf16 v[44:47], v[158:161], v[182:185], v[44:47]
	v_mfma_f32_16x16x32_bf16 v[40:43], v[166:169], v[182:185], v[40:43]
	v_mfma_f32_16x16x32_bf16 v[28:31], v[158:161], v[196:199], v[28:31]
	v_mfma_f32_16x16x32_bf16 v[24:27], v[166:169], v[196:199], v[24:27]
	v_mfma_f32_16x16x32_bf16 v[12:15], v[158:161], v[204:207], v[12:15]
	v_mfma_f32_16x16x32_bf16 v[8:11], v[166:169], v[204:207], v[8:11]
	s_setprio 0
	s_barrier
	s_add_u32 s20, s36, 0x80080
	s_addc_u32 s21, s37, 0
	s_add_i32 s36, s54, s23
	s_mov_b32 m0, s36
	v_lshl_add_u64 v[148:149], s[20:21], 0, v[132:133]
	global_load_lds_dwordx4 v[148:149], off
	s_add_i32 m0, s36, 0x2000
	v_lshl_add_u64 v[148:149], s[20:21], 0, v[128:129]
	global_load_lds_dwordx4 v[148:149], off
	s_waitcnt vmcnt(6)
	s_barrier
	s_setprio 1
	v_mfma_f32_16x16x32_bf16 v[52:55], v[208:211], v[170:173], v[52:55]
	v_mfma_f32_16x16x32_bf16 v[48:51], v[216:219], v[170:173], v[48:51]
	v_mfma_f32_16x16x32_bf16 v[36:39], v[208:211], v[178:181], v[36:39]
	v_mfma_f32_16x16x32_bf16 v[32:35], v[216:219], v[178:181], v[32:35]
	v_mfma_f32_16x16x32_bf16 v[20:23], v[208:211], v[186:189], v[20:23]
	v_mfma_f32_16x16x32_bf16 v[16:19], v[216:219], v[186:189], v[16:19]
	v_mfma_f32_16x16x32_bf16 v[4:7], v[208:211], v[200:203], v[4:7]
	v_mfma_f32_16x16x32_bf16 v[0:3], v[216:219], v[200:203], v[0:3]
	v_mfma_f32_16x16x32_bf16 v[52:55], v[212:215], v[174:177], v[52:55]
	v_mfma_f32_16x16x32_bf16 v[48:51], v[220:223], v[174:177], v[48:51]
	v_mfma_f32_16x16x32_bf16 v[36:39], v[212:215], v[182:185], v[36:39]
	v_mfma_f32_16x16x32_bf16 v[32:35], v[220:223], v[182:185], v[32:35]
	v_mfma_f32_16x16x32_bf16 v[20:23], v[212:215], v[196:199], v[20:23]
	v_mfma_f32_16x16x32_bf16 v[16:19], v[220:223], v[196:199], v[16:19]
	v_mfma_f32_16x16x32_bf16 v[4:7], v[212:215], v[204:207], v[4:7]
	v_mfma_f32_16x16x32_bf16 v[0:3], v[220:223], v[204:207], v[0:3]
	s_setprio 0
	s_add_i32 s52, s52, 2
	s_add_u32 s26, s26, 0x100
	s_addc_u32 s27, s27, 0
	s_add_u32 s50, s50, 0x100
	s_addc_u32 s51, s51, 0
	s_cmp_gt_u32 s52, 29
	s_cbranch_scc0 .Ldup_nl_mlpin1
	s_cmpk_gt_u32 s12, 0xff
	s_cbranch_scc0 .Ldup_nl_mlpin1
	v_lshl_add_u32 v148, s24, 8, v145
	v_max_f32_e32 v124, v124, v124
	v_max_f32_e32 v120, v120, v120
	v_ashrrev_i32_e32 v149, 31, v148
	v_max_f32_e32 v124, 0, v124
	v_max_f32_e32 v120, 0, v120
	v_lshlrev_b64 v[156:157], 14, v[148:149]
	v_mul_f32_e32 v149, v124, v124
	v_mul_f32_e32 v124, v120, v120
	v_max_f32_e32 v120, v125, v125
	v_max_f32_e32 v121, v121, v121
	v_max_f32_e32 v120, 0, v120
	v_max_f32_e32 v121, 0, v121
	v_mul_f32_e32 v158, v120, v120
	v_mul_f32_e32 v159, v121, v121
	v_max_f32_e32 v120, v126, v126
	v_max_f32_e32 v121, v122, v122
	v_max_f32_e32 v120, 0, v120
	v_max_f32_e32 v121, 0, v121
	v_lshl_or_b32 v154, s33, 8, v150
	v_mul_f32_e32 v160, v120, v120
	v_mul_f32_e32 v125, v121, v121
	v_max_f32_e32 v120, v127, v127
	v_max_f32_e32 v121, v123, v123
	v_max_f32_e32 v116, v116, v116
	v_max_f32_e32 v112, v112, v112
	v_max_f32_e32 v117, v117, v117
	v_max_f32_e32 v113, v113, v113
	v_max_f32_e32 v118, v118, v118
	v_max_f32_e32 v114, v114, v114
	v_max_f32_e32 v119, v119, v119
	v_max_f32_e32 v115, v115, v115
	v_ashrrev_i32_e32 v155, 31, v154
	v_max_f32_e32 v120, 0, v120
	v_max_f32_e32 v121, 0, v121
	v_max_f32_e32 v116, 0, v116
	v_max_f32_e32 v112, 0, v112
	v_max_f32_e32 v117, 0, v117
	v_max_f32_e32 v113, 0, v113
	v_max_f32_e32 v118, 0, v118
	v_max_f32_e32 v114, 0, v114
	v_max_f32_e32 v119, 0, v119
	v_max_f32_e32 v115, 0, v115
	v_mul_f32_e32 v161, v120, v120
	v_mul_f32_e32 v162, v121, v121
	v_lshl_add_u64 v[122:123], s[28:29], 0, v[156:157]
	v_lshlrev_b64 v[120:121], 1, v[154:155]
	v_mul_f32_e32 v116, v116, v116
	v_mul_f32_e32 v112, v112, v112
	v_mul_f32_e32 v117, v117, v117
	v_mul_f32_e32 v113, v113, v113
	v_mul_f32_e32 v118, v118, v118
	v_mul_f32_e32 v114, v114, v114
	v_mul_f32_e32 v119, v119, v119
	v_mul_f32_e32 v115, v115, v115
	v_max_f32_e32 v104, v104, v104
	v_lshl_add_u64 v[126:127], v[122:123], 0, v[120:121]
	v_cvt_pk_bf16_f32 v115, v114, v115
	v_cvt_pk_bf16_f32 v114, v112, v113
	v_cvt_pk_bf16_f32 v113, v118, v119
	v_cvt_pk_bf16_f32 v112, v116, v117
	v_max_f32_e32 v104, 0, v104
	global_store_dwordx4 v[126:127], v[112:115], off offset:256
	v_max_f32_e32 v105, v105, v105
	v_max_f32_e32 v105, 0, v105
	v_mul_f32_e32 v115, v104, v104
	v_max_f32_e32 v104, v109, v109
	v_max_f32_e32 v104, 0, v104
	v_mul_f32_e32 v116, v104, v104
	v_mul_f32_e32 v117, v105, v105
	v_max_f32_e32 v104, v110, v110
	v_max_f32_e32 v105, v106, v106
	v_or_b32_e32 v112, 16, v148
	v_max_f32_e32 v104, 0, v104
	v_max_f32_e32 v105, 0, v105
	v_ashrrev_i32_e32 v113, 31, v112
	v_mul_f32_e32 v110, v104, v104
	v_mul_f32_e32 v106, v105, v105
	v_max_f32_e32 v104, v111, v111
	v_max_f32_e32 v105, v107, v107
	v_max_f32_e32 v100, v100, v100
	v_max_f32_e32 v96, v96, v96
	v_max_f32_e32 v101, v101, v101
	v_max_f32_e32 v97, v97, v97
	v_max_f32_e32 v102, v102, v102
	v_max_f32_e32 v98, v98, v98
	v_max_f32_e32 v103, v103, v103
	v_max_f32_e32 v99, v99, v99
	v_lshlrev_b64 v[112:113], 14, v[112:113]
	v_max_f32_e32 v108, v108, v108
	v_max_f32_e32 v104, 0, v104
	v_max_f32_e32 v105, 0, v105
	v_max_f32_e32 v100, 0, v100
	v_max_f32_e32 v96, 0, v96
	v_max_f32_e32 v101, 0, v101
	v_max_f32_e32 v97, 0, v97
	v_max_f32_e32 v102, 0, v102
	v_max_f32_e32 v98, 0, v98
	v_max_f32_e32 v103, 0, v103
	v_max_f32_e32 v99, 0, v99
	v_max_f32_e32 v108, 0, v108
	v_mul_f32_e32 v111, v104, v104
	v_mul_f32_e32 v107, v105, v105
	v_lshl_add_u64 v[104:105], s[28:29], 0, v[112:113]
	v_mul_f32_e32 v100, v100, v100
	v_mul_f32_e32 v96, v96, v96
	v_mul_f32_e32 v101, v101, v101
	v_mul_f32_e32 v97, v97, v97
	v_mul_f32_e32 v102, v102, v102
	v_mul_f32_e32 v98, v98, v98
	v_mul_f32_e32 v103, v103, v103
	v_mul_f32_e32 v99, v99, v99
	v_max_f32_e32 v88, v88, v88
	v_mul_f32_e32 v114, v108, v108
	v_lshl_add_u64 v[108:109], v[104:105], 0, v[120:121]
	v_cvt_pk_bf16_f32 v99, v98, v99
	v_cvt_pk_bf16_f32 v98, v96, v97
	v_cvt_pk_bf16_f32 v97, v102, v103
	v_cvt_pk_bf16_f32 v96, v100, v101
	v_max_f32_e32 v88, 0, v88
	global_store_dwordx4 v[108:109], v[96:99], off offset:256
	v_max_f32_e32 v89, v89, v89
	v_max_f32_e32 v89, 0, v89
	v_mul_f32_e32 v99, v88, v88
	v_max_f32_e32 v88, v93, v93
	v_max_f32_e32 v88, 0, v88
	v_mul_f32_e32 v100, v88, v88
	v_mul_f32_e32 v101, v89, v89
	v_max_f32_e32 v88, v94, v94
	v_max_f32_e32 v89, v90, v90
	v_or_b32_e32 v96, 32, v148
	v_max_f32_e32 v88, 0, v88
	v_max_f32_e32 v89, 0, v89
	v_ashrrev_i32_e32 v97, 31, v96
	v_mul_f32_e32 v94, v88, v88
	v_mul_f32_e32 v90, v89, v89
	v_max_f32_e32 v88, v95, v95
	v_max_f32_e32 v89, v91, v91
	v_max_f32_e32 v84, v84, v84
	v_max_f32_e32 v80, v80, v80
	v_max_f32_e32 v85, v85, v85
	v_max_f32_e32 v81, v81, v81
	v_max_f32_e32 v86, v86, v86
	v_max_f32_e32 v82, v82, v82
	v_max_f32_e32 v87, v87, v87
	v_max_f32_e32 v83, v83, v83
	v_lshlrev_b64 v[96:97], 14, v[96:97]
	v_max_f32_e32 v92, v92, v92
	v_max_f32_e32 v88, 0, v88
	v_max_f32_e32 v89, 0, v89
	v_max_f32_e32 v84, 0, v84
	v_max_f32_e32 v80, 0, v80
	v_max_f32_e32 v85, 0, v85
	v_max_f32_e32 v81, 0, v81
	v_max_f32_e32 v86, 0, v86
	v_max_f32_e32 v82, 0, v82
	v_max_f32_e32 v87, 0, v87
	v_max_f32_e32 v83, 0, v83
	v_max_f32_e32 v92, 0, v92
	v_mul_f32_e32 v95, v88, v88
	v_mul_f32_e32 v91, v89, v89
	v_lshl_add_u64 v[88:89], s[28:29], 0, v[96:97]
	v_mul_f32_e32 v84, v84, v84
	v_mul_f32_e32 v80, v80, v80
	v_mul_f32_e32 v85, v85, v85
	v_mul_f32_e32 v81, v81, v81
	v_mul_f32_e32 v86, v86, v86
	v_mul_f32_e32 v82, v82, v82
	v_mul_f32_e32 v87, v87, v87
	v_mul_f32_e32 v83, v83, v83
	v_max_f32_e32 v72, v72, v72
	v_mul_f32_e32 v98, v92, v92
	v_lshl_add_u64 v[92:93], v[88:89], 0, v[120:121]
	v_cvt_pk_bf16_f32 v83, v82, v83
	v_cvt_pk_bf16_f32 v82, v80, v81
	v_cvt_pk_bf16_f32 v81, v86, v87
	v_cvt_pk_bf16_f32 v80, v84, v85
	v_max_f32_e32 v72, 0, v72
	global_store_dwordx4 v[92:93], v[80:83], off offset:256
	v_max_f32_e32 v73, v73, v73
	v_max_f32_e32 v73, 0, v73
	v_mul_f32_e32 v83, v72, v72
	v_max_f32_e32 v72, v77, v77
	v_max_f32_e32 v72, 0, v72
	v_mul_f32_e32 v84, v72, v72
	v_mul_f32_e32 v85, v73, v73
	v_max_f32_e32 v72, v78, v78
	v_max_f32_e32 v73, v74, v74
	v_or_b32_e32 v80, 48, v148
	v_max_f32_e32 v72, 0, v72
	v_max_f32_e32 v73, 0, v73
	v_ashrrev_i32_e32 v81, 31, v80
	v_mul_f32_e32 v78, v72, v72
	v_mul_f32_e32 v74, v73, v73
	v_max_f32_e32 v72, v79, v79
	v_max_f32_e32 v73, v75, v75
	v_max_f32_e32 v68, v68, v68
	v_max_f32_e32 v64, v64, v64
	v_max_f32_e32 v69, v69, v69
	v_max_f32_e32 v65, v65, v65
	v_max_f32_e32 v70, v70, v70
	v_max_f32_e32 v66, v66, v66
	v_max_f32_e32 v71, v71, v71
	v_max_f32_e32 v67, v67, v67
	v_lshlrev_b64 v[80:81], 14, v[80:81]
	v_max_f32_e32 v76, v76, v76
	v_max_f32_e32 v72, 0, v72
	v_max_f32_e32 v73, 0, v73
	v_max_f32_e32 v68, 0, v68
	v_max_f32_e32 v64, 0, v64
	v_max_f32_e32 v69, 0, v69
	v_max_f32_e32 v65, 0, v65
	v_max_f32_e32 v70, 0, v70
	v_max_f32_e32 v66, 0, v66
	v_max_f32_e32 v71, 0, v71
	v_max_f32_e32 v67, 0, v67
	v_max_f32_e32 v76, 0, v76
	v_mul_f32_e32 v79, v72, v72
	v_mul_f32_e32 v75, v73, v73
	v_lshl_add_u64 v[72:73], s[28:29], 0, v[80:81]
	v_mul_f32_e32 v68, v68, v68
	v_mul_f32_e32 v64, v64, v64
	v_mul_f32_e32 v69, v69, v69
	v_mul_f32_e32 v65, v65, v65
	v_mul_f32_e32 v70, v70, v70
	v_mul_f32_e32 v66, v66, v66
	v_mul_f32_e32 v71, v71, v71
	v_mul_f32_e32 v67, v67, v67
	v_max_f32_e32 v56, v56, v56
	v_mul_f32_e32 v82, v76, v76
	v_lshl_add_u64 v[76:77], v[72:73], 0, v[120:121]
	v_cvt_pk_bf16_f32 v67, v66, v67
	v_cvt_pk_bf16_f32 v66, v64, v65
	v_cvt_pk_bf16_f32 v65, v70, v71
	v_cvt_pk_bf16_f32 v64, v68, v69
	v_max_f32_e32 v56, 0, v56
	global_store_dwordx4 v[76:77], v[64:67], off offset:256
	v_max_f32_e32 v57, v57, v57
	v_max_f32_e32 v57, 0, v57
	v_mul_f32_e32 v67, v56, v56
	v_max_f32_e32 v56, v61, v61
	v_max_f32_e32 v56, 0, v56
	v_mul_f32_e32 v68, v56, v56
	v_mul_f32_e32 v69, v57, v57
	v_max_f32_e32 v56, v62, v62
	v_max_f32_e32 v57, v58, v58
	v_add_u32_e32 v64, 0x80, v148
	v_max_f32_e32 v56, 0, v56
	v_max_f32_e32 v57, 0, v57
	v_ashrrev_i32_e32 v65, 31, v64
	v_mul_f32_e32 v62, v56, v56
	v_mul_f32_e32 v58, v57, v57
	v_max_f32_e32 v56, v63, v63
	v_max_f32_e32 v57, v59, v59
	v_max_f32_e32 v52, v52, v52
	v_max_f32_e32 v48, v48, v48
	v_max_f32_e32 v53, v53, v53
	v_max_f32_e32 v49, v49, v49
	v_max_f32_e32 v54, v54, v54
	v_max_f32_e32 v50, v50, v50
	v_max_f32_e32 v55, v55, v55
	v_max_f32_e32 v51, v51, v51
	v_lshlrev_b64 v[64:65], 14, v[64:65]
	v_max_f32_e32 v60, v60, v60
	v_max_f32_e32 v56, 0, v56
	v_max_f32_e32 v57, 0, v57
	v_max_f32_e32 v52, 0, v52
	v_max_f32_e32 v48, 0, v48
	v_max_f32_e32 v53, 0, v53
	v_max_f32_e32 v49, 0, v49
	v_max_f32_e32 v54, 0, v54
	v_max_f32_e32 v50, 0, v50
	v_max_f32_e32 v55, 0, v55
	v_max_f32_e32 v51, 0, v51
	v_max_f32_e32 v60, 0, v60
	v_mul_f32_e32 v63, v56, v56
	v_mul_f32_e32 v59, v57, v57
	v_lshl_add_u64 v[56:57], s[28:29], 0, v[64:65]
	v_mul_f32_e32 v52, v52, v52
	v_mul_f32_e32 v48, v48, v48
	v_mul_f32_e32 v53, v53, v53
	v_mul_f32_e32 v49, v49, v49
	v_mul_f32_e32 v54, v54, v54
	v_mul_f32_e32 v50, v50, v50
	v_mul_f32_e32 v55, v55, v55
	v_mul_f32_e32 v51, v51, v51
	v_max_f32_e32 v40, v40, v40
	v_mul_f32_e32 v66, v60, v60
	v_lshl_add_u64 v[60:61], v[56:57], 0, v[120:121]
	v_cvt_pk_bf16_f32 v51, v50, v51
	v_cvt_pk_bf16_f32 v50, v48, v49
	v_cvt_pk_bf16_f32 v49, v54, v55
	v_cvt_pk_bf16_f32 v48, v52, v53
	v_max_f32_e32 v40, 0, v40
	global_store_dwordx4 v[60:61], v[48:51], off offset:256
	v_max_f32_e32 v41, v41, v41
	v_max_f32_e32 v41, 0, v41
	v_mul_f32_e32 v51, v40, v40
	v_max_f32_e32 v40, v45, v45
	v_max_f32_e32 v40, 0, v40
	v_mul_f32_e32 v52, v40, v40
	v_mul_f32_e32 v53, v41, v41
	v_max_f32_e32 v40, v46, v46
	v_max_f32_e32 v41, v42, v42
	v_add_u32_e32 v48, 0x90, v148
	v_max_f32_e32 v40, 0, v40
	v_max_f32_e32 v41, 0, v41
	v_ashrrev_i32_e32 v49, 31, v48
	v_mul_f32_e32 v46, v40, v40
	v_mul_f32_e32 v42, v41, v41
	v_max_f32_e32 v40, v47, v47
	v_max_f32_e32 v41, v43, v43
	v_max_f32_e32 v36, v36, v36
	v_max_f32_e32 v32, v32, v32
	v_max_f32_e32 v37, v37, v37
	v_max_f32_e32 v33, v33, v33
	v_max_f32_e32 v38, v38, v38
	v_max_f32_e32 v34, v34, v34
	v_max_f32_e32 v39, v39, v39
	v_max_f32_e32 v35, v35, v35
	v_lshlrev_b64 v[48:49], 14, v[48:49]
	v_max_f32_e32 v44, v44, v44
	v_max_f32_e32 v40, 0, v40
	v_max_f32_e32 v41, 0, v41
	v_max_f32_e32 v36, 0, v36
	v_max_f32_e32 v32, 0, v32
	v_max_f32_e32 v37, 0, v37
	v_max_f32_e32 v33, 0, v33
	v_max_f32_e32 v38, 0, v38
	v_max_f32_e32 v34, 0, v34
	v_max_f32_e32 v39, 0, v39
	v_max_f32_e32 v35, 0, v35
	v_max_f32_e32 v44, 0, v44
	v_mul_f32_e32 v47, v40, v40
	v_mul_f32_e32 v43, v41, v41
	v_lshl_add_u64 v[40:41], s[28:29], 0, v[48:49]
	v_mul_f32_e32 v36, v36, v36
	v_mul_f32_e32 v32, v32, v32
	v_mul_f32_e32 v37, v37, v37
	v_mul_f32_e32 v33, v33, v33
	v_mul_f32_e32 v38, v38, v38
	v_mul_f32_e32 v34, v34, v34
	v_mul_f32_e32 v39, v39, v39
	v_mul_f32_e32 v35, v35, v35
	v_max_f32_e32 v24, v24, v24
	v_mul_f32_e32 v50, v44, v44
	v_lshl_add_u64 v[44:45], v[40:41], 0, v[120:121]
	v_cvt_pk_bf16_f32 v35, v34, v35
	v_cvt_pk_bf16_f32 v34, v32, v33
	v_cvt_pk_bf16_f32 v33, v38, v39
	v_cvt_pk_bf16_f32 v32, v36, v37
	v_max_f32_e32 v24, 0, v24
	global_store_dwordx4 v[44:45], v[32:35], off offset:256
	v_max_f32_e32 v25, v25, v25
	v_max_f32_e32 v25, 0, v25
	v_mul_f32_e32 v35, v24, v24
	v_max_f32_e32 v24, v29, v29
	v_max_f32_e32 v24, 0, v24
	v_mul_f32_e32 v36, v24, v24
	v_mul_f32_e32 v37, v25, v25
	v_max_f32_e32 v24, v30, v30
	v_max_f32_e32 v25, v26, v26
	v_add_u32_e32 v32, 0xa0, v148
	v_max_f32_e32 v24, 0, v24
	v_max_f32_e32 v25, 0, v25
	v_ashrrev_i32_e32 v33, 31, v32
	v_mul_f32_e32 v30, v24, v24
	v_mul_f32_e32 v26, v25, v25
	v_max_f32_e32 v24, v31, v31
	v_max_f32_e32 v25, v27, v27
	v_max_f32_e32 v20, v20, v20
	v_max_f32_e32 v16, v16, v16
	v_max_f32_e32 v21, v21, v21
	v_max_f32_e32 v17, v17, v17
	v_max_f32_e32 v22, v22, v22
	v_max_f32_e32 v18, v18, v18
	v_max_f32_e32 v23, v23, v23
	v_max_f32_e32 v19, v19, v19
	v_lshlrev_b64 v[32:33], 14, v[32:33]
	v_max_f32_e32 v28, v28, v28
	v_max_f32_e32 v24, 0, v24
	v_max_f32_e32 v25, 0, v25
	v_max_f32_e32 v20, 0, v20
	v_max_f32_e32 v16, 0, v16
	v_max_f32_e32 v21, 0, v21
	v_max_f32_e32 v17, 0, v17
	v_max_f32_e32 v22, 0, v22
	v_max_f32_e32 v18, 0, v18
	v_max_f32_e32 v23, 0, v23
	v_max_f32_e32 v19, 0, v19
	v_max_f32_e32 v28, 0, v28
	v_mul_f32_e32 v31, v24, v24
	v_mul_f32_e32 v27, v25, v25
	v_lshl_add_u64 v[24:25], s[28:29], 0, v[32:33]
	v_mul_f32_e32 v20, v20, v20
	v_mul_f32_e32 v16, v16, v16
	v_mul_f32_e32 v21, v21, v21
	v_mul_f32_e32 v17, v17, v17
	v_mul_f32_e32 v22, v22, v22
	v_mul_f32_e32 v18, v18, v18
	v_mul_f32_e32 v23, v23, v23
	v_mul_f32_e32 v19, v19, v19
	v_max_f32_e32 v8, v8, v8
	v_mul_f32_e32 v34, v28, v28
	v_lshl_add_u64 v[28:29], v[24:25], 0, v[120:121]
	v_cvt_pk_bf16_f32 v19, v18, v19
	v_cvt_pk_bf16_f32 v18, v16, v17
	v_cvt_pk_bf16_f32 v17, v22, v23
	v_cvt_pk_bf16_f32 v16, v20, v21
	v_max_f32_e32 v8, 0, v8
	global_store_dwordx4 v[28:29], v[16:19], off offset:256
	v_max_f32_e32 v9, v9, v9
	v_max_f32_e32 v9, 0, v9
	v_mul_f32_e32 v19, v8, v8
	v_max_f32_e32 v8, v13, v13
	v_max_f32_e32 v8, 0, v8
	v_mul_f32_e32 v20, v8, v8
	v_mul_f32_e32 v21, v9, v9
	v_max_f32_e32 v8, v14, v14
	v_max_f32_e32 v9, v10, v10
	v_add_u32_e32 v16, 0xb0, v148
	v_max_f32_e32 v8, 0, v8
	v_max_f32_e32 v9, 0, v9
	v_ashrrev_i32_e32 v17, 31, v16
	v_max_f32_e32 v12, v12, v12
	v_mul_f32_e32 v14, v8, v8
	v_mul_f32_e32 v10, v9, v9
	v_max_f32_e32 v8, v15, v15
	v_max_f32_e32 v9, v11, v11
	v_max_f32_e32 v4, v4, v4
	v_max_f32_e32 v0, v0, v0
	v_max_f32_e32 v5, v5, v5
	v_max_f32_e32 v1, v1, v1
	v_max_f32_e32 v6, v6, v6
	v_max_f32_e32 v2, v2, v2
	v_max_f32_e32 v7, v7, v7
	v_max_f32_e32 v3, v3, v3
	v_lshlrev_b64 v[16:17], 14, v[16:17]
	v_max_f32_e32 v12, 0, v12
	v_max_f32_e32 v8, 0, v8
	v_max_f32_e32 v9, 0, v9
	v_max_f32_e32 v4, 0, v4
	v_max_f32_e32 v0, 0, v0
	v_max_f32_e32 v5, 0, v5
	v_max_f32_e32 v1, 0, v1
	v_max_f32_e32 v6, 0, v6
	v_max_f32_e32 v2, 0, v2
	v_max_f32_e32 v7, 0, v7
	v_max_f32_e32 v3, 0, v3
	v_mul_f32_e32 v18, v12, v12
	v_mul_f32_e32 v15, v8, v8
	v_mul_f32_e32 v11, v9, v9
	v_lshl_add_u64 v[8:9], s[28:29], 0, v[16:17]
	v_mul_f32_e32 v4, v4, v4
	v_mul_f32_e32 v0, v0, v0
	v_mul_f32_e32 v5, v5, v5
	v_mul_f32_e32 v1, v1, v1
	v_mul_f32_e32 v6, v6, v6
	v_mul_f32_e32 v2, v2, v2
	v_mul_f32_e32 v7, v7, v7
	v_mul_f32_e32 v3, v3, v3
	v_cvt_pk_bf16_f32 v125, v125, v162
	v_cvt_pk_bf16_f32 v124, v124, v159
	v_cvt_pk_bf16_f32 v123, v160, v161
	v_cvt_pk_bf16_f32 v122, v149, v158
	v_cvt_pk_bf16_f32 v107, v106, v107
	v_cvt_pk_bf16_f32 v106, v115, v117
	v_cvt_pk_bf16_f32 v105, v110, v111
	v_cvt_pk_bf16_f32 v104, v114, v116
	v_cvt_pk_bf16_f32 v91, v90, v91
	v_cvt_pk_bf16_f32 v90, v99, v101
	v_cvt_pk_bf16_f32 v89, v94, v95
	v_cvt_pk_bf16_f32 v88, v98, v100
	v_cvt_pk_bf16_f32 v75, v74, v75
	v_cvt_pk_bf16_f32 v74, v83, v85
	v_cvt_pk_bf16_f32 v73, v78, v79
	v_cvt_pk_bf16_f32 v72, v82, v84
	v_cvt_pk_bf16_f32 v59, v58, v59
	v_cvt_pk_bf16_f32 v58, v67, v69
	v_cvt_pk_bf16_f32 v57, v62, v63
	v_cvt_pk_bf16_f32 v56, v66, v68
	v_cvt_pk_bf16_f32 v43, v42, v43
	v_cvt_pk_bf16_f32 v42, v51, v53
	v_cvt_pk_bf16_f32 v41, v46, v47
	v_cvt_pk_bf16_f32 v40, v50, v52
	v_cvt_pk_bf16_f32 v27, v26, v27
	v_cvt_pk_bf16_f32 v26, v35, v37
	v_cvt_pk_bf16_f32 v25, v30, v31
	v_cvt_pk_bf16_f32 v24, v34, v36
	v_lshl_add_u64 v[12:13], v[8:9], 0, v[120:121]
	v_cvt_pk_bf16_f32 v11, v10, v11
	v_cvt_pk_bf16_f32 v10, v19, v21
	v_cvt_pk_bf16_f32 v9, v14, v15
	v_cvt_pk_bf16_f32 v8, v18, v20
	v_cvt_pk_bf16_f32 v3, v2, v3
	v_cvt_pk_bf16_f32 v2, v0, v1
	v_cvt_pk_bf16_f32 v1, v6, v7
	v_cvt_pk_bf16_f32 v0, v4, v5
	global_store_dwordx4 v[126:127], v[122:125], off
	global_store_dwordx4 v[108:109], v[104:107], off
	global_store_dwordx4 v[92:93], v[88:91], off
	global_store_dwordx4 v[76:77], v[72:75], off
	global_store_dwordx4 v[60:61], v[56:59], off
	global_store_dwordx4 v[44:45], v[40:43], off
	global_store_dwordx4 v[28:29], v[24:27], off
	global_store_dwordx4 v[12:13], v[8:11], off
	global_store_dwordx4 v[12:13], v[0:3], off offset:256

.LBB0_1433:
	ds_read_b128 v[148:151], v158
	ds_read_b128 v[152:155], v158 offset:1024
	ds_read_b128 v[162:165], v158 offset:2048
	ds_read_b128 v[166:169], v158 offset:3072
	s_add_u32 s20, s26, 0xffe00080
	s_addc_u32 s21, s27, -1
	s_cmpk_eq_i32 s53, 0x7c
	s_cselect_b32 s21, s15, s21
	s_cselect_b32 s20, s49, s20
	s_cselect_b32 s31, s11, s52
	s_cselect_b32 s30, s50, s51
	v_lshl_add_u64 v[204:205], s[26:27], 0, v[136:137]
	s_add_i32 m0, s25, 0xc000
	ds_read_b128 v[170:173], v159
	ds_read_b128 v[174:177], v159 offset:1024
	ds_read_b128 v[178:181], v159 offset:2048
	ds_read_b128 v[182:185], v159 offset:3072
	ds_read_b128 v[186:189], v159 offset:4096
	ds_read_b128 v[190:193], v159 offset:5120
	ds_read_b128 v[196:199], v159 offset:6144
	ds_read_b128 v[200:203], v159 offset:7168
	global_load_lds_dwordx4 v[204:205], off
	s_add_i32 m0, s25, 0xe000
	v_lshl_add_u64 v[204:205], s[26:27], 0, v[138:139]
	global_load_lds_dwordx4 v[204:205], off
	s_waitcnt lgkmcnt(8)
	s_barrier
	s_waitcnt lgkmcnt(0)
	s_setprio 1
	v_mfma_f32_16x16x32_bf16 v[124:127], v[148:151], v[170:173], v[124:127]
	v_mfma_f32_16x16x32_bf16 v[120:123], v[162:165], v[170:173], v[120:123]
	v_mfma_f32_16x16x32_bf16 v[108:111], v[148:151], v[178:181], v[108:111]
	v_mfma_f32_16x16x32_bf16 v[104:107], v[162:165], v[178:181], v[104:107]
	v_mfma_f32_16x16x32_bf16 v[92:95], v[148:151], v[186:189], v[92:95]
	v_mfma_f32_16x16x32_bf16 v[88:91], v[162:165], v[186:189], v[88:91]
	v_mfma_f32_16x16x32_bf16 v[76:79], v[148:151], v[196:199], v[76:79]
	v_mfma_f32_16x16x32_bf16 v[72:75], v[162:165], v[196:199], v[72:75]
	v_mfma_f32_16x16x32_bf16 v[124:127], v[152:155], v[174:177], v[124:127]
	v_mfma_f32_16x16x32_bf16 v[120:123], v[166:169], v[174:177], v[120:123]
	v_mfma_f32_16x16x32_bf16 v[108:111], v[152:155], v[182:185], v[108:111]
	v_mfma_f32_16x16x32_bf16 v[104:107], v[166:169], v[182:185], v[104:107]
	v_mfma_f32_16x16x32_bf16 v[92:95], v[152:155], v[190:193], v[92:95]
	v_mfma_f32_16x16x32_bf16 v[88:91], v[166:169], v[190:193], v[88:91]
	v_mfma_f32_16x16x32_bf16 v[76:79], v[152:155], v[200:203], v[76:79]
	v_mfma_f32_16x16x32_bf16 v[72:75], v[166:169], v[200:203], v[72:75]
	s_setprio 0
	s_barrier
	s_add_i32 s54, s45, s23
	v_lshl_add_u64 v[220:221], s[30:31], 0, v[132:133]
	s_mov_b32 m0, s54
	ds_read_b128 v[204:207], v160
	ds_read_b128 v[208:211], v160 offset:1024
	ds_read_b128 v[212:215], v160 offset:2048
	ds_read_b128 v[216:219], v160 offset:3072
	global_load_lds_dwordx4 v[220:221], off
	s_add_i32 m0, s54, 0x2000
	v_lshl_add_u64 v[222:223], s[30:31], 0, v[128:129]
	global_load_lds_dwordx4 v[222:223], off
	s_barrier
	s_waitcnt lgkmcnt(0)
	s_setprio 1
	v_mfma_f32_16x16x32_bf16 v[116:119], v[204:207], v[170:173], v[116:119]
	v_mfma_f32_16x16x32_bf16 v[112:115], v[212:215], v[170:173], v[112:115]
	v_mfma_f32_16x16x32_bf16 v[100:103], v[204:207], v[178:181], v[100:103]
	v_mfma_f32_16x16x32_bf16 v[96:99], v[212:215], v[178:181], v[96:99]
	v_mfma_f32_16x16x32_bf16 v[84:87], v[204:207], v[186:189], v[84:87]
	v_mfma_f32_16x16x32_bf16 v[80:83], v[212:215], v[186:189], v[80:83]
	v_mfma_f32_16x16x32_bf16 v[68:71], v[204:207], v[196:199], v[68:71]
	v_mfma_f32_16x16x32_bf16 v[64:67], v[212:215], v[196:199], v[64:67]
	v_mfma_f32_16x16x32_bf16 v[116:119], v[208:211], v[174:177], v[116:119]
	v_mfma_f32_16x16x32_bf16 v[112:115], v[216:219], v[174:177], v[112:115]
	v_mfma_f32_16x16x32_bf16 v[100:103], v[208:211], v[182:185], v[100:103]
	v_mfma_f32_16x16x32_bf16 v[96:99], v[216:219], v[182:185], v[96:99]
	v_mfma_f32_16x16x32_bf16 v[84:87], v[208:211], v[190:193], v[84:87]
	v_mfma_f32_16x16x32_bf16 v[80:83], v[216:219], v[190:193], v[80:83]
	v_mfma_f32_16x16x32_bf16 v[68:71], v[208:211], v[200:203], v[68:71]
	v_mfma_f32_16x16x32_bf16 v[64:67], v[216:219], v[200:203], v[64:67]
	s_setprio 0
	s_mov_b32 m0, s25
	v_lshl_add_u64 v[224:225], s[20:21], 0, v[134:135]
	s_barrier
	ds_read_b128 v[170:173], v159 offset:16384
	ds_read_b128 v[174:177], v159 offset:17408
	ds_read_b128 v[178:181], v159 offset:18432
	ds_read_b128 v[182:185], v159 offset:19456
	ds_read_b128 v[186:189], v159 offset:20480
	ds_read_b128 v[190:193], v159 offset:21504
	ds_read_b128 v[196:199], v159 offset:22528
	ds_read_b128 v[200:203], v159 offset:23552
	global_load_lds_dwordx4 v[224:225], off
	s_mov_b32 m0, s37
	v_lshl_add_u64 v[226:227], s[20:21], 0, v[130:131]
	global_load_lds_dwordx4 v[226:227], off
	s_barrier
	s_waitcnt lgkmcnt(0)
	s_setprio 1
	v_mfma_f32_16x16x32_bf16 v[60:63], v[148:151], v[170:173], v[60:63]
	v_mfma_f32_16x16x32_bf16 v[56:59], v[162:165], v[170:173], v[56:59]
	v_mfma_f32_16x16x32_bf16 v[44:47], v[148:151], v[178:181], v[44:47]
	v_mfma_f32_16x16x32_bf16 v[40:43], v[162:165], v[178:181], v[40:43]
	v_mfma_f32_16x16x32_bf16 v[28:31], v[148:151], v[186:189], v[28:31]
	v_mfma_f32_16x16x32_bf16 v[24:27], v[162:165], v[186:189], v[24:27]
	v_mfma_f32_16x16x32_bf16 v[12:15], v[148:151], v[196:199], v[12:15]
	v_mfma_f32_16x16x32_bf16 v[8:11], v[162:165], v[196:199], v[8:11]
	v_mfma_f32_16x16x32_bf16 v[60:63], v[152:155], v[174:177], v[60:63]
	v_mfma_f32_16x16x32_bf16 v[56:59], v[166:169], v[174:177], v[56:59]
	v_mfma_f32_16x16x32_bf16 v[44:47], v[152:155], v[182:185], v[44:47]
	v_mfma_f32_16x16x32_bf16 v[40:43], v[166:169], v[182:185], v[40:43]
	v_mfma_f32_16x16x32_bf16 v[28:31], v[152:155], v[190:193], v[28:31]
	v_mfma_f32_16x16x32_bf16 v[24:27], v[166:169], v[190:193], v[24:27]
	v_mfma_f32_16x16x32_bf16 v[12:15], v[152:155], v[200:203], v[12:15]
	v_mfma_f32_16x16x32_bf16 v[8:11], v[166:169], v[200:203], v[8:11]
	s_setprio 0
	s_barrier
	s_add_u32 s54, s30, 0x200000
	s_addc_u32 s55, s31, 0
	s_add_i32 s56, s47, s23
	s_mov_b32 m0, s56
	v_lshl_add_u64 v[148:149], s[54:55], 0, v[132:133]
	global_load_lds_dwordx4 v[148:149], off
	s_add_i32 m0, s56, 0x2000
	v_lshl_add_u64 v[148:149], s[54:55], 0, v[128:129]
	global_load_lds_dwordx4 v[148:149], off
	s_waitcnt vmcnt(6)
	s_barrier
	s_setprio 1
	v_mfma_f32_16x16x32_bf16 v[52:55], v[204:207], v[170:173], v[52:55]
	v_mfma_f32_16x16x32_bf16 v[48:51], v[212:215], v[170:173], v[48:51]
	v_mfma_f32_16x16x32_bf16 v[36:39], v[204:207], v[178:181], v[36:39]
	v_mfma_f32_16x16x32_bf16 v[32:35], v[212:215], v[178:181], v[32:35]
	v_mfma_f32_16x16x32_bf16 v[20:23], v[204:207], v[186:189], v[20:23]
	v_mfma_f32_16x16x32_bf16 v[16:19], v[212:215], v[186:189], v[16:19]
	v_mfma_f32_16x16x32_bf16 v[4:7], v[204:207], v[196:199], v[4:7]
	v_mfma_f32_16x16x32_bf16 v[0:3], v[212:215], v[196:199], v[0:3]
	v_mfma_f32_16x16x32_bf16 v[52:55], v[208:211], v[174:177], v[52:55]
	v_mfma_f32_16x16x32_bf16 v[48:51], v[216:219], v[174:177], v[48:51]
	v_mfma_f32_16x16x32_bf16 v[36:39], v[208:211], v[182:185], v[36:39]
	v_mfma_f32_16x16x32_bf16 v[32:35], v[216:219], v[182:185], v[32:35]
	v_mfma_f32_16x16x32_bf16 v[20:23], v[208:211], v[190:193], v[20:23]
	v_mfma_f32_16x16x32_bf16 v[16:19], v[216:219], v[190:193], v[16:19]
	v_mfma_f32_16x16x32_bf16 v[4:7], v[208:211], v[200:203], v[4:7]
	v_mfma_f32_16x16x32_bf16 v[0:3], v[216:219], v[200:203], v[0:3]
	s_setprio 0
	s_add_i32 s54, 0, 0x18000
	v_add_u32_e32 v161, s54, v147
	s_barrier
	ds_read_b128 v[148:151], v161
	ds_read_b128 v[152:155], v161 offset:1024
	ds_read_b128 v[162:165], v161 offset:2048
	ds_read_b128 v[166:169], v161 offset:3072
	s_add_u32 s20, s20, 0x200000
	s_addc_u32 s21, s21, 0
	s_mov_b32 m0, s38
	v_lshl_add_u64 v[204:205], s[20:21], 0, v[134:135]
	ds_read_b128 v[170:173], v159 offset:32768
	ds_read_b128 v[174:177], v159 offset:33792
	ds_read_b128 v[178:181], v159 offset:34816
	ds_read_b128 v[182:185], v159 offset:35840
	ds_read_b128 v[186:189], v159 offset:36864
	ds_read_b128 v[190:193], v159 offset:37888
	ds_read_b128 v[196:199], v159 offset:38912
	ds_read_b128 v[200:203], v159 offset:39936
	global_load_lds_dwordx4 v[204:205], off
	s_mov_b32 m0, s39
	v_lshl_add_u64 v[204:205], s[20:21], 0, v[130:131]
	global_load_lds_dwordx4 v[204:205], off
	s_waitcnt lgkmcnt(8)
	s_barrier
	s_waitcnt lgkmcnt(0)
	s_setprio 1
	v_mfma_f32_16x16x32_bf16 v[124:127], v[148:151], v[170:173], v[124:127]
	v_mfma_f32_16x16x32_bf16 v[120:123], v[162:165], v[170:173], v[120:123]
	v_mfma_f32_16x16x32_bf16 v[108:111], v[148:151], v[178:181], v[108:111]
	v_mfma_f32_16x16x32_bf16 v[104:107], v[162:165], v[178:181], v[104:107]
	v_mfma_f32_16x16x32_bf16 v[92:95], v[148:151], v[186:189], v[92:95]
	v_mfma_f32_16x16x32_bf16 v[88:91], v[162:165], v[186:189], v[88:91]
	v_mfma_f32_16x16x32_bf16 v[76:79], v[148:151], v[196:199], v[76:79]
	v_mfma_f32_16x16x32_bf16 v[72:75], v[162:165], v[196:199], v[72:75]
	v_mfma_f32_16x16x32_bf16 v[124:127], v[152:155], v[174:177], v[124:127]
	v_mfma_f32_16x16x32_bf16 v[120:123], v[166:169], v[174:177], v[120:123]
	v_mfma_f32_16x16x32_bf16 v[108:111], v[152:155], v[182:185], v[108:111]
	v_mfma_f32_16x16x32_bf16 v[104:107], v[166:169], v[182:185], v[104:107]
	v_mfma_f32_16x16x32_bf16 v[92:95], v[152:155], v[190:193], v[92:95]
	v_mfma_f32_16x16x32_bf16 v[88:91], v[166:169], v[190:193], v[88:91]
	v_mfma_f32_16x16x32_bf16 v[76:79], v[152:155], v[200:203], v[76:79]
	v_mfma_f32_16x16x32_bf16 v[72:75], v[166:169], v[200:203], v[72:75]
	s_setprio 0
	s_barrier
	s_add_i32 s55, 0, 0x1c000
	s_add_i32 s20, s54, s23
	v_add_u32_e32 v161, s55, v147
	v_lshl_add_u64 v[220:221], v[220:221], 0, s[8:9]
	s_mov_b32 m0, s20
	ds_read_b128 v[204:207], v161
	ds_read_b128 v[208:211], v161 offset:1024
	ds_read_b128 v[212:215], v161 offset:2048
	ds_read_b128 v[216:219], v161 offset:3072
	global_load_lds_dwordx4 v[220:221], off
	s_add_i32 m0, s20, 0x2000
	v_lshl_add_u64 v[220:221], v[222:223], 0, s[8:9]
	global_load_lds_dwordx4 v[220:221], off
	s_barrier
	s_waitcnt lgkmcnt(0)
	s_setprio 1
	v_mfma_f32_16x16x32_bf16 v[116:119], v[204:207], v[170:173], v[116:119]
	v_mfma_f32_16x16x32_bf16 v[112:115], v[212:215], v[170:173], v[112:115]
	v_mfma_f32_16x16x32_bf16 v[100:103], v[204:207], v[178:181], v[100:103]
	v_mfma_f32_16x16x32_bf16 v[96:99], v[212:215], v[178:181], v[96:99]
	v_mfma_f32_16x16x32_bf16 v[84:87], v[204:207], v[186:189], v[84:87]
	v_mfma_f32_16x16x32_bf16 v[80:83], v[212:215], v[186:189], v[80:83]
	v_mfma_f32_16x16x32_bf16 v[68:71], v[204:207], v[196:199], v[68:71]
	v_mfma_f32_16x16x32_bf16 v[64:67], v[212:215], v[196:199], v[64:67]
	v_mfma_f32_16x16x32_bf16 v[116:119], v[208:211], v[174:177], v[116:119]
	v_mfma_f32_16x16x32_bf16 v[112:115], v[216:219], v[174:177], v[112:115]
	v_mfma_f32_16x16x32_bf16 v[100:103], v[208:211], v[182:185], v[100:103]
	v_mfma_f32_16x16x32_bf16 v[96:99], v[216:219], v[182:185], v[96:99]
	v_mfma_f32_16x16x32_bf16 v[84:87], v[208:211], v[190:193], v[84:87]
	v_mfma_f32_16x16x32_bf16 v[80:83], v[216:219], v[190:193], v[80:83]
	v_mfma_f32_16x16x32_bf16 v[68:71], v[208:211], v[200:203], v[68:71]
	v_mfma_f32_16x16x32_bf16 v[64:67], v[216:219], v[200:203], v[64:67]
	s_setprio 0
	s_mov_b32 m0, s35
	v_lshl_add_u64 v[220:221], v[224:225], 0, s[8:9]
	s_barrier
	ds_read_b128 v[170:173], v159 offset:49152
	ds_read_b128 v[174:177], v159 offset:50176
	ds_read_b128 v[178:181], v159 offset:51200
	ds_read_b128 v[182:185], v159 offset:52224
	ds_read_b128 v[186:189], v159 offset:53248
	ds_read_b128 v[190:193], v159 offset:54272
	ds_read_b128 v[196:199], v159 offset:55296
	ds_read_b128 v[200:203], v159 offset:56320
	global_load_lds_dwordx4 v[220:221], off
	s_mov_b32 m0, s41
	v_lshl_add_u64 v[220:221], v[226:227], 0, s[8:9]
	global_load_lds_dwordx4 v[220:221], off
	s_barrier
	s_waitcnt lgkmcnt(0)
	s_setprio 1
	v_mfma_f32_16x16x32_bf16 v[60:63], v[148:151], v[170:173], v[60:63]
	v_mfma_f32_16x16x32_bf16 v[56:59], v[162:165], v[170:173], v[56:59]
	v_mfma_f32_16x16x32_bf16 v[44:47], v[148:151], v[178:181], v[44:47]
	v_mfma_f32_16x16x32_bf16 v[40:43], v[162:165], v[178:181], v[40:43]
	v_mfma_f32_16x16x32_bf16 v[28:31], v[148:151], v[186:189], v[28:31]
	v_mfma_f32_16x16x32_bf16 v[24:27], v[162:165], v[186:189], v[24:27]
	v_mfma_f32_16x16x32_bf16 v[12:15], v[148:151], v[196:199], v[12:15]
	v_mfma_f32_16x16x32_bf16 v[8:11], v[162:165], v[196:199], v[8:11]
	v_mfma_f32_16x16x32_bf16 v[60:63], v[152:155], v[174:177], v[60:63]
	v_mfma_f32_16x16x32_bf16 v[56:59], v[166:169], v[174:177], v[56:59]
	v_mfma_f32_16x16x32_bf16 v[44:47], v[152:155], v[182:185], v[44:47]
	v_mfma_f32_16x16x32_bf16 v[40:43], v[166:169], v[182:185], v[40:43]
	v_mfma_f32_16x16x32_bf16 v[28:31], v[152:155], v[190:193], v[28:31]
	v_mfma_f32_16x16x32_bf16 v[24:27], v[166:169], v[190:193], v[24:27]
	v_mfma_f32_16x16x32_bf16 v[12:15], v[152:155], v[200:203], v[12:15]
	v_mfma_f32_16x16x32_bf16 v[8:11], v[166:169], v[200:203], v[8:11]
	s_setprio 0
	s_barrier
	s_add_u32 s20, s30, 0x200080
	s_addc_u32 s21, s31, 0
	s_add_i32 s30, s55, s23
	s_mov_b32 m0, s30
	v_lshl_add_u64 v[148:149], s[20:21], 0, v[132:133]
	global_load_lds_dwordx4 v[148:149], off
	s_add_i32 m0, s30, 0x2000
	v_lshl_add_u64 v[148:149], s[20:21], 0, v[128:129]
	global_load_lds_dwordx4 v[148:149], off
	s_waitcnt vmcnt(6)
	s_barrier
	s_setprio 1
	v_mfma_f32_16x16x32_bf16 v[52:55], v[204:207], v[170:173], v[52:55]
	v_mfma_f32_16x16x32_bf16 v[48:51], v[212:215], v[170:173], v[48:51]
	v_mfma_f32_16x16x32_bf16 v[36:39], v[204:207], v[178:181], v[36:39]
	v_mfma_f32_16x16x32_bf16 v[32:35], v[212:215], v[178:181], v[32:35]
	v_mfma_f32_16x16x32_bf16 v[20:23], v[204:207], v[186:189], v[20:23]
	v_mfma_f32_16x16x32_bf16 v[16:19], v[212:215], v[186:189], v[16:19]
	v_mfma_f32_16x16x32_bf16 v[4:7], v[204:207], v[196:199], v[4:7]
	v_mfma_f32_16x16x32_bf16 v[0:3], v[212:215], v[196:199], v[0:3]
	v_mfma_f32_16x16x32_bf16 v[52:55], v[208:211], v[174:177], v[52:55]
	v_mfma_f32_16x16x32_bf16 v[48:51], v[216:219], v[174:177], v[48:51]
	v_mfma_f32_16x16x32_bf16 v[36:39], v[208:211], v[182:185], v[36:39]
	v_mfma_f32_16x16x32_bf16 v[32:35], v[216:219], v[182:185], v[32:35]
	v_mfma_f32_16x16x32_bf16 v[20:23], v[208:211], v[190:193], v[20:23]
	v_mfma_f32_16x16x32_bf16 v[16:19], v[216:219], v[190:193], v[16:19]
	v_mfma_f32_16x16x32_bf16 v[4:7], v[208:211], v[200:203], v[4:7]
	v_mfma_f32_16x16x32_bf16 v[0:3], v[216:219], v[200:203], v[0:3]
	s_setprio 0
	s_add_i32 s53, s53, 2
	s_add_u32 s26, s26, 0x100
	s_addc_u32 s27, s27, 0
	s_add_u32 s51, s51, 0x100
	s_addc_u32 s52, s52, 0
	s_cmpk_gt_u32 s53, 0x7d
	s_cbranch_scc0 .Lepi_nl_mlpout1
	s_cmp_lg_u32 s34, 64
	s_cbranch_scc1 .Lepi_nl_mlpout1
	s_lshl_b32 s11, s24, 8
	s_add_i32 s11, s11, s34
	v_or_b32_e32 v154, s11, v145
	s_add_i32 s15, s11, 0xffffe000
	v_lshl_or_b32 v150, s33, 8, v157
	s_lshr_b32 s15, s15, 12
	v_lshlrev_b32_e32 v148, 12, v154
	s_add_i32 s15, s15, 1
	s_cmp_gt_i32 s11, s48
	s_cselect_b32 s15, s15, 0
	s_mul_i32 s15, s15, s46
	v_lshl_add_u32 v148, v150, 1, v148
	s_add_u32 s20, s6, s15
	s_addc_u32 s21, s7, 0
	v_lshlrev_b32_e32 v149, 2, v150
	s_nop 0
	global_load_dwordx4 v[196:199], v149, s[20:21]
	global_load_dwordx4 v[200:203], v149, s[20:21] offset:16
	global_load_dwordx4 v[204:207], v149, s[20:21] offset:512
	global_load_dwordx4 v[208:211], v149, s[20:21] offset:528
	global_load_dwordx4 v[212:215], v148, s[74:75]
	global_load_dwordx4 v[216:219], v148, s[74:75] offset:256
	v_add_u32_e32 v151, 0x10000, v148
	global_load_dwordx4 v[220:223], v151, s[74:75]
	global_load_dwordx4 v[224:227], v151, s[74:75] offset:256
	v_add_u32_e32 v151, 0x20000, v148
	global_load_dwordx4 v[164:167], v151, s[74:75]
	global_load_dwordx4 v[168:171], v151, s[74:75] offset:256
	v_add_u32_e32 v151, 0x30000, v148
	global_load_dwordx4 v[172:175], v151, s[74:75]
	global_load_dwordx4 v[176:179], v151, s[74:75] offset:256
	s_waitcnt vmcnt(0)
	v_lshlrev_b32_e32 v180, 16, v212
	v_and_b32_e32 v181, 0xffff0000, v212
	v_lshlrev_b32_e32 v182, 16, v213
	v_and_b32_e32 v183, 0xffff0000, v213
	v_lshlrev_b32_e32 v184, 16, v214
	v_and_b32_e32 v185, 0xffff0000, v214
	v_lshlrev_b32_e32 v186, 16, v215
	v_and_b32_e32 v187, 0xffff0000, v215
	v_pk_fma_f32 v[124:125], v[124:125], v[196:197], v[180:181]
	v_pk_fma_f32 v[126:127], v[126:127], v[198:199], v[182:183]
	v_pk_fma_f32 v[120:121], v[120:121], v[200:201], v[184:185]
	v_pk_fma_f32 v[122:123], v[122:123], v[202:203], v[186:187]
	v_cvt_pk_bf16_f32 v123, v122, v123
	v_cvt_pk_bf16_f32 v122, v120, v121
	v_cvt_pk_bf16_f32 v121, v126, v127
	v_cvt_pk_bf16_f32 v120, v124, v125
	global_store_dwordx4 v148, v[120:123], s[42:43]
	v_lshlrev_b32_e32 v180, 16, v216
	v_and_b32_e32 v181, 0xffff0000, v216
	v_lshlrev_b32_e32 v182, 16, v217
	v_and_b32_e32 v183, 0xffff0000, v217
	v_lshlrev_b32_e32 v184, 16, v218
	v_and_b32_e32 v185, 0xffff0000, v218
	v_lshlrev_b32_e32 v186, 16, v219
	v_and_b32_e32 v187, 0xffff0000, v219
	v_pk_fma_f32 v[116:117], v[116:117], v[204:205], v[180:181]
	v_pk_fma_f32 v[118:119], v[118:119], v[206:207], v[182:183]
	v_pk_fma_f32 v[112:113], v[112:113], v[208:209], v[184:185]
	v_pk_fma_f32 v[114:115], v[114:115], v[210:211], v[186:187]
	v_cvt_pk_bf16_f32 v115, v114, v115
	v_cvt_pk_bf16_f32 v114, v112, v113
	v_cvt_pk_bf16_f32 v113, v118, v119
	v_cvt_pk_bf16_f32 v112, v116, v117
	global_store_dwordx4 v148, v[112:115], s[42:43] offset:256
	v_lshlrev_b32_e32 v180, 16, v220
	v_and_b32_e32 v181, 0xffff0000, v220
	v_lshlrev_b32_e32 v182, 16, v221
	v_and_b32_e32 v183, 0xffff0000, v221
	v_lshlrev_b32_e32 v184, 16, v222
	v_and_b32_e32 v185, 0xffff0000, v222
	v_lshlrev_b32_e32 v186, 16, v223
	v_and_b32_e32 v187, 0xffff0000, v223
	v_pk_fma_f32 v[108:109], v[108:109], v[196:197], v[180:181]
	v_pk_fma_f32 v[110:111], v[110:111], v[198:199], v[182:183]
	v_pk_fma_f32 v[104:105], v[104:105], v[200:201], v[184:185]
	v_pk_fma_f32 v[106:107], v[106:107], v[202:203], v[186:187]
	v_cvt_pk_bf16_f32 v107, v106, v107
	v_cvt_pk_bf16_f32 v106, v104, v105
	v_cvt_pk_bf16_f32 v105, v110, v111
	v_cvt_pk_bf16_f32 v104, v108, v109
	v_add_u32_e32 v151, 0x10000, v148
	global_store_dwordx4 v151, v[104:107], s[42:43]
	v_lshlrev_b32_e32 v180, 16, v224
	v_and_b32_e32 v181, 0xffff0000, v224
	v_lshlrev_b32_e32 v182, 16, v225
	v_and_b32_e32 v183, 0xffff0000, v225
	v_lshlrev_b32_e32 v184, 16, v226
	v_and_b32_e32 v185, 0xffff0000, v226
	v_lshlrev_b32_e32 v186, 16, v227
	v_and_b32_e32 v187, 0xffff0000, v227
	v_pk_fma_f32 v[100:101], v[100:101], v[204:205], v[180:181]
	v_pk_fma_f32 v[102:103], v[102:103], v[206:207], v[182:183]
	v_pk_fma_f32 v[96:97], v[96:97], v[208:209], v[184:185]
	v_pk_fma_f32 v[98:99], v[98:99], v[210:211], v[186:187]
	v_cvt_pk_bf16_f32 v99, v98, v99
	v_cvt_pk_bf16_f32 v98, v96, v97
	v_cvt_pk_bf16_f32 v97, v102, v103
	v_cvt_pk_bf16_f32 v96, v100, v101
	v_add_u32_e32 v151, 0x10000, v148
	global_store_dwordx4 v151, v[96:99], s[42:43] offset:256
	v_add_u32_e32 v151, 0x80000, v148
	global_load_dwordx4 v[212:215], v151, s[74:75]
	global_load_dwordx4 v[216:219], v151, s[74:75] offset:256
	v_add_u32_e32 v151, 0x90000, v148
	global_load_dwordx4 v[220:223], v151, s[74:75]
	global_load_dwordx4 v[224:227], v151, s[74:75] offset:256
	v_lshlrev_b32_e32 v180, 16, v164
	v_and_b32_e32 v181, 0xffff0000, v164
	v_lshlrev_b32_e32 v182, 16, v165
	v_and_b32_e32 v183, 0xffff0000, v165
	v_lshlrev_b32_e32 v184, 16, v166
	v_and_b32_e32 v185, 0xffff0000, v166
	v_lshlrev_b32_e32 v186, 16, v167
	v_and_b32_e32 v187, 0xffff0000, v167
	v_pk_fma_f32 v[92:93], v[92:93], v[196:197], v[180:181]
	v_pk_fma_f32 v[94:95], v[94:95], v[198:199], v[182:183]
	v_pk_fma_f32 v[88:89], v[88:89], v[200:201], v[184:185]
	v_pk_fma_f32 v[90:91], v[90:91], v[202:203], v[186:187]
	v_cvt_pk_bf16_f32 v91, v90, v91
	v_cvt_pk_bf16_f32 v90, v88, v89
	v_cvt_pk_bf16_f32 v89, v94, v95
	v_cvt_pk_bf16_f32 v88, v92, v93
	v_add_u32_e32 v151, 0x20000, v148
	global_store_dwordx4 v151, v[88:91], s[42:43]
	v_lshlrev_b32_e32 v180, 16, v168
	v_and_b32_e32 v181, 0xffff0000, v168
	v_lshlrev_b32_e32 v182, 16, v169
	v_and_b32_e32 v183, 0xffff0000, v169
	v_lshlrev_b32_e32 v184, 16, v170
	v_and_b32_e32 v185, 0xffff0000, v170
	v_lshlrev_b32_e32 v186, 16, v171
	v_and_b32_e32 v187, 0xffff0000, v171
	v_pk_fma_f32 v[84:85], v[84:85], v[204:205], v[180:181]
	v_pk_fma_f32 v[86:87], v[86:87], v[206:207], v[182:183]
	v_pk_fma_f32 v[80:81], v[80:81], v[208:209], v[184:185]
	v_pk_fma_f32 v[82:83], v[82:83], v[210:211], v[186:187]
	v_cvt_pk_bf16_f32 v83, v82, v83
	v_cvt_pk_bf16_f32 v82, v80, v81
	v_cvt_pk_bf16_f32 v81, v86, v87
	v_cvt_pk_bf16_f32 v80, v84, v85
	v_add_u32_e32 v151, 0x20000, v148
	global_store_dwordx4 v151, v[80:83], s[42:43] offset:256
	v_lshlrev_b32_e32 v180, 16, v172
	v_and_b32_e32 v181, 0xffff0000, v172
	v_lshlrev_b32_e32 v182, 16, v173
	v_and_b32_e32 v183, 0xffff0000, v173
	v_lshlrev_b32_e32 v184, 16, v174
	v_and_b32_e32 v185, 0xffff0000, v174
	v_lshlrev_b32_e32 v186, 16, v175
	v_and_b32_e32 v187, 0xffff0000, v175
	v_pk_fma_f32 v[76:77], v[76:77], v[196:197], v[180:181]
	v_pk_fma_f32 v[78:79], v[78:79], v[198:199], v[182:183]
	v_pk_fma_f32 v[72:73], v[72:73], v[200:201], v[184:185]
	v_pk_fma_f32 v[74:75], v[74:75], v[202:203], v[186:187]
	v_cvt_pk_bf16_f32 v75, v74, v75
	v_cvt_pk_bf16_f32 v74, v72, v73
	v_cvt_pk_bf16_f32 v73, v78, v79
	v_cvt_pk_bf16_f32 v72, v76, v77
	v_add_u32_e32 v151, 0x30000, v148
	global_store_dwordx4 v151, v[72:75], s[42:43]
	v_lshlrev_b32_e32 v180, 16, v176
	v_and_b32_e32 v181, 0xffff0000, v176
	v_lshlrev_b32_e32 v182, 16, v177
	v_and_b32_e32 v183, 0xffff0000, v177
	v_lshlrev_b32_e32 v184, 16, v178
	v_and_b32_e32 v185, 0xffff0000, v178
	v_lshlrev_b32_e32 v186, 16, v179
	v_and_b32_e32 v187, 0xffff0000, v179
	v_pk_fma_f32 v[68:69], v[68:69], v[204:205], v[180:181]
	v_pk_fma_f32 v[70:71], v[70:71], v[206:207], v[182:183]
	v_pk_fma_f32 v[64:65], v[64:65], v[208:209], v[184:185]
	v_pk_fma_f32 v[66:67], v[66:67], v[210:211], v[186:187]
	v_cvt_pk_bf16_f32 v67, v66, v67
	v_cvt_pk_bf16_f32 v66, v64, v65
	v_cvt_pk_bf16_f32 v65, v70, v71
	v_cvt_pk_bf16_f32 v64, v68, v69
	v_add_u32_e32 v151, 0x30000, v148
	global_store_dwordx4 v151, v[64:67], s[42:43] offset:256
	v_add_u32_e32 v151, 0xa0000, v148
	global_load_dwordx4 v[164:167], v151, s[74:75]
	global_load_dwordx4 v[168:171], v151, s[74:75] offset:256
	v_add_u32_e32 v151, 0xb0000, v148
	global_load_dwordx4 v[172:175], v151, s[74:75]
	global_load_dwordx4 v[176:179], v151, s[74:75] offset:256
	s_waitcnt vmcnt(0)
	v_lshlrev_b32_e32 v180, 16, v212
	v_and_b32_e32 v181, 0xffff0000, v212
	v_lshlrev_b32_e32 v182, 16, v213
	v_and_b32_e32 v183, 0xffff0000, v213
	v_lshlrev_b32_e32 v184, 16, v214
	v_and_b32_e32 v185, 0xffff0000, v214
	v_lshlrev_b32_e32 v186, 16, v215
	v_and_b32_e32 v187, 0xffff0000, v215
	v_pk_fma_f32 v[60:61], v[60:61], v[196:197], v[180:181]
	v_pk_fma_f32 v[62:63], v[62:63], v[198:199], v[182:183]
	v_pk_fma_f32 v[56:57], v[56:57], v[200:201], v[184:185]
	v_pk_fma_f32 v[58:59], v[58:59], v[202:203], v[186:187]
	v_cvt_pk_bf16_f32 v59, v58, v59
	v_cvt_pk_bf16_f32 v58, v56, v57
	v_cvt_pk_bf16_f32 v57, v62, v63
	v_cvt_pk_bf16_f32 v56, v60, v61
	v_add_u32_e32 v151, 0x80000, v148
	global_store_dwordx4 v151, v[56:59], s[42:43]
	v_lshlrev_b32_e32 v180, 16, v216
	v_and_b32_e32 v181, 0xffff0000, v216
	v_lshlrev_b32_e32 v182, 16, v217
	v_and_b32_e32 v183, 0xffff0000, v217
	v_lshlrev_b32_e32 v184, 16, v218
	v_and_b32_e32 v185, 0xffff0000, v218
	v_lshlrev_b32_e32 v186, 16, v219
	v_and_b32_e32 v187, 0xffff0000, v219
	v_pk_fma_f32 v[52:53], v[52:53], v[204:205], v[180:181]
	v_pk_fma_f32 v[54:55], v[54:55], v[206:207], v[182:183]
	v_pk_fma_f32 v[48:49], v[48:49], v[208:209], v[184:185]
	v_pk_fma_f32 v[50:51], v[50:51], v[210:211], v[186:187]
	v_cvt_pk_bf16_f32 v51, v50, v51
	v_cvt_pk_bf16_f32 v50, v48, v49
	v_cvt_pk_bf16_f32 v49, v54, v55
	v_cvt_pk_bf16_f32 v48, v52, v53
	v_add_u32_e32 v151, 0x80000, v148
	global_store_dwordx4 v151, v[48:51], s[42:43] offset:256
	v_lshlrev_b32_e32 v180, 16, v220
	v_and_b32_e32 v181, 0xffff0000, v220
	v_lshlrev_b32_e32 v182, 16, v221
	v_and_b32_e32 v183, 0xffff0000, v221
	v_lshlrev_b32_e32 v184, 16, v222
	v_and_b32_e32 v185, 0xffff0000, v222
	v_lshlrev_b32_e32 v186, 16, v223
	v_and_b32_e32 v187, 0xffff0000, v223
	v_pk_fma_f32 v[44:45], v[44:45], v[196:197], v[180:181]
	v_pk_fma_f32 v[46:47], v[46:47], v[198:199], v[182:183]
	v_pk_fma_f32 v[40:41], v[40:41], v[200:201], v[184:185]
	v_pk_fma_f32 v[42:43], v[42:43], v[202:203], v[186:187]
	v_cvt_pk_bf16_f32 v43, v42, v43
	v_cvt_pk_bf16_f32 v42, v40, v41
	v_cvt_pk_bf16_f32 v41, v46, v47
	v_cvt_pk_bf16_f32 v40, v44, v45
	v_add_u32_e32 v151, 0x90000, v148
	global_store_dwordx4 v151, v[40:43], s[42:43]
	v_lshlrev_b32_e32 v180, 16, v224
	v_and_b32_e32 v181, 0xffff0000, v224
	v_lshlrev_b32_e32 v182, 16, v225
	v_and_b32_e32 v183, 0xffff0000, v225
	v_lshlrev_b32_e32 v184, 16, v226
	v_and_b32_e32 v185, 0xffff0000, v226
	v_lshlrev_b32_e32 v186, 16, v227
	v_and_b32_e32 v187, 0xffff0000, v227
	v_pk_fma_f32 v[36:37], v[36:37], v[204:205], v[180:181]
	v_pk_fma_f32 v[38:39], v[38:39], v[206:207], v[182:183]
	v_pk_fma_f32 v[32:33], v[32:33], v[208:209], v[184:185]
	v_pk_fma_f32 v[34:35], v[34:35], v[210:211], v[186:187]
	v_cvt_pk_bf16_f32 v35, v34, v35
	v_cvt_pk_bf16_f32 v34, v32, v33
	v_cvt_pk_bf16_f32 v33, v38, v39
	v_cvt_pk_bf16_f32 v32, v36, v37
	v_add_u32_e32 v151, 0x90000, v148
	global_store_dwordx4 v151, v[32:35], s[42:43] offset:256
	v_lshlrev_b32_e32 v180, 16, v164
	v_and_b32_e32 v181, 0xffff0000, v164
	v_lshlrev_b32_e32 v182, 16, v165
	v_and_b32_e32 v183, 0xffff0000, v165
	v_lshlrev_b32_e32 v184, 16, v166
	v_and_b32_e32 v185, 0xffff0000, v166
	v_lshlrev_b32_e32 v186, 16, v167
	v_and_b32_e32 v187, 0xffff0000, v167
	v_pk_fma_f32 v[28:29], v[28:29], v[196:197], v[180:181]
	v_pk_fma_f32 v[30:31], v[30:31], v[198:199], v[182:183]
	v_pk_fma_f32 v[24:25], v[24:25], v[200:201], v[184:185]
	v_pk_fma_f32 v[26:27], v[26:27], v[202:203], v[186:187]
	v_cvt_pk_bf16_f32 v27, v26, v27
	v_cvt_pk_bf16_f32 v26, v24, v25
	v_cvt_pk_bf16_f32 v25, v30, v31
	v_cvt_pk_bf16_f32 v24, v28, v29
	v_add_u32_e32 v151, 0xa0000, v148
	global_store_dwordx4 v151, v[24:27], s[42:43]
	v_lshlrev_b32_e32 v180, 16, v168
	v_and_b32_e32 v181, 0xffff0000, v168
	v_lshlrev_b32_e32 v182, 16, v169
	v_and_b32_e32 v183, 0xffff0000, v169
	v_lshlrev_b32_e32 v184, 16, v170
	v_and_b32_e32 v185, 0xffff0000, v170
	v_lshlrev_b32_e32 v186, 16, v171
	v_and_b32_e32 v187, 0xffff0000, v171
	v_pk_fma_f32 v[20:21], v[20:21], v[204:205], v[180:181]
	v_pk_fma_f32 v[22:23], v[22:23], v[206:207], v[182:183]
	v_pk_fma_f32 v[16:17], v[16:17], v[208:209], v[184:185]
	v_pk_fma_f32 v[18:19], v[18:19], v[210:211], v[186:187]
	v_cvt_pk_bf16_f32 v19, v18, v19
	v_cvt_pk_bf16_f32 v18, v16, v17
	v_cvt_pk_bf16_f32 v17, v22, v23
	v_cvt_pk_bf16_f32 v16, v20, v21
	v_add_u32_e32 v151, 0xa0000, v148
	global_store_dwordx4 v151, v[16:19], s[42:43] offset:256
	v_lshlrev_b32_e32 v180, 16, v172
	v_and_b32_e32 v181, 0xffff0000, v172
	v_lshlrev_b32_e32 v182, 16, v173
	v_and_b32_e32 v183, 0xffff0000, v173
	v_lshlrev_b32_e32 v184, 16, v174
	v_and_b32_e32 v185, 0xffff0000, v174
	v_lshlrev_b32_e32 v186, 16, v175
	v_and_b32_e32 v187, 0xffff0000, v175
	v_pk_fma_f32 v[12:13], v[12:13], v[196:197], v[180:181]
	v_pk_fma_f32 v[14:15], v[14:15], v[198:199], v[182:183]
	v_pk_fma_f32 v[8:9], v[8:9], v[200:201], v[184:185]
	v_pk_fma_f32 v[10:11], v[10:11], v[202:203], v[186:187]
	v_cvt_pk_bf16_f32 v11, v10, v11
	v_cvt_pk_bf16_f32 v10, v8, v9
	v_cvt_pk_bf16_f32 v9, v14, v15
	v_cvt_pk_bf16_f32 v8, v12, v13
	v_add_u32_e32 v151, 0xb0000, v148
	global_store_dwordx4 v151, v[8:11], s[42:43]
	v_lshlrev_b32_e32 v180, 16, v176
	v_and_b32_e32 v181, 0xffff0000, v176
	v_lshlrev_b32_e32 v182, 16, v177
	v_and_b32_e32 v183, 0xffff0000, v177
	v_lshlrev_b32_e32 v184, 16, v178
	v_and_b32_e32 v185, 0xffff0000, v178
	v_lshlrev_b32_e32 v186, 16, v179
	v_and_b32_e32 v187, 0xffff0000, v179
	v_pk_fma_f32 v[4:5], v[4:5], v[204:205], v[180:181]
	v_pk_fma_f32 v[6:7], v[6:7], v[206:207], v[182:183]
	v_pk_fma_f32 v[0:1], v[0:1], v[208:209], v[184:185]
	v_pk_fma_f32 v[2:3], v[2:3], v[210:211], v[186:187]
	v_cvt_pk_bf16_f32 v3, v2, v3
	v_cvt_pk_bf16_f32 v2, v0, v1
	v_cvt_pk_bf16_f32 v1, v6, v7
	v_cvt_pk_bf16_f32 v0, v4, v5
	v_add_u32_e32 v151, 0xb0000, v148
	global_store_dwordx4 v151, v[0:3], s[42:43] offset:256
